# w_in conversion also moved to the gate/up-1 tail; pipelined tail converter
# speedup vs baseline: 1.0299x; 1.0035x over previous
; __device__ __forceinline__ void tr_load(const float* W, int N, int item, int lane, float (&wv)[32]) {
;     const int nblk = N / 32, kb = item / nblk, nb = item % nblk, k0 = 64 * kb, n0 = 32 * nb;
; #pragma unroll
;     for (int i = 0; i < 32; ++i) { const int kk = 2 * i + (lane >> 5); wv[i] = __builtin_nontemporal_load(W + (size_t)(k0 + kk) * N + n0 + (lane & 31)); }
; }
; __global__ void __launch_bounds__(512, 2) mega_fwd(Params p) {
;     ...
;             transpose_mat<3, true, true>(p.in[6] + (size_t)l * D * INW, D, INW, P_W(WS_WIN), scr, gw, ngw, lane, p.in[5] + l * D);
.LBB0_43:
	s_cmpk_gt_i32 s6, 0x33ff
	s_mov_b32 s37, s91
	s_branch .LBB0_50
	s_add_u32 s12, s7, 0x4200000
	v_readlane_b32 s56, v254, 60
	s_addc_u32 s13, s25, 0
	s_lshl_b64 s[14:15], s[0:1], 2
	v_readlane_b32 s66, v255, 6
	v_readlane_b32 s67, v255, 7
	s_add_u32 s14, s66, s14
	v_readlane_b32 s68, v255, 8
	s_addc_u32 s15, s67, s15
	s_mul_i32 s16, s36, 0x6800000
	v_readlane_b32 s69, v255, 9
	s_add_u32 s16, s68, s16
	s_mul_hi_i32 s18, s6, 0x4ec4ec4f
	s_addc_u32 s17, s69, 0
	s_lshr_b32 s19, s18, 31
	s_ashr_i32 s18, s18, 7
	s_add_i32 s19, s18, s19
	s_mul_i32 s18, s19, 0x1a0
	s_sub_i32 s18, s6, s18
	s_lshl_b32 s18, s18, 5
	v_lshl_or_b32 v34, s19, 6, v134
	s_ashr_i32 s19, s18, 31
	s_lshl_b64 s[18:19], s[18:19], 2
	s_add_u32 s18, s16, s18
	s_addc_u32 s19, s17, s19
	v_mov_b32_e32 v49, v193
	v_lshl_add_u64 v[32:33], s[18:19], 0, v[48:49]
	s_waitcnt vmcnt(0)
	v_mad_i64_i32 v[0:1], s[18:19], v34, s33, v[32:33]
	global_load_dword v0, v[0:1], off nt
	v_or_b32_e32 v1, 2, v34
	s_waitcnt vmcnt(33)
	v_mad_i64_i32 v[2:3], s[18:19], v1, s33, v[32:33]
	global_load_dword v1, v[2:3], off nt
	v_or_b32_e32 v2, 4, v34
	v_mad_i64_i32 v[2:3], s[18:19], v2, s33, v[32:33]
	global_load_dword v2, v[2:3], off nt
	v_or_b32_e32 v3, 6, v34
	s_waitcnt vmcnt(33)
	v_mad_i64_i32 v[4:5], s[18:19], v3, s33, v[32:33]
	global_load_dword v3, v[4:5], off nt
	v_or_b32_e32 v4, 8, v34
	v_mad_i64_i32 v[4:5], s[18:19], v4, s33, v[32:33]
	global_load_dword v4, v[4:5], off nt
	v_or_b32_e32 v5, 10, v34
	s_waitcnt vmcnt(33)
	v_mad_i64_i32 v[6:7], s[18:19], v5, s33, v[32:33]
	global_load_dword v5, v[6:7], off nt
	v_or_b32_e32 v6, 12, v34
	v_mad_i64_i32 v[6:7], s[18:19], v6, s33, v[32:33]
	global_load_dword v6, v[6:7], off nt
	v_or_b32_e32 v7, 14, v34
	s_waitcnt vmcnt(33)
	v_mad_i64_i32 v[8:9], s[18:19], v7, s33, v[32:33]
	global_load_dword v7, v[8:9], off nt
	v_or_b32_e32 v8, 16, v34
	v_mad_i64_i32 v[8:9], s[18:19], v8, s33, v[32:33]
	global_load_dword v8, v[8:9], off nt
	v_or_b32_e32 v9, 18, v34
	s_waitcnt vmcnt(33)
	v_mad_i64_i32 v[10:11], s[18:19], v9, s33, v[32:33]
	global_load_dword v9, v[10:11], off nt
	v_or_b32_e32 v10, 20, v34
	v_mad_i64_i32 v[10:11], s[18:19], v10, s33, v[32:33]
	global_load_dword v10, v[10:11], off nt
	v_or_b32_e32 v11, 22, v34
	s_waitcnt vmcnt(33)
	v_mad_i64_i32 v[12:13], s[18:19], v11, s33, v[32:33]
	global_load_dword v11, v[12:13], off nt
	v_or_b32_e32 v12, 24, v34
	v_mad_i64_i32 v[12:13], s[18:19], v12, s33, v[32:33]
	global_load_dword v12, v[12:13], off nt
	v_or_b32_e32 v13, 26, v34
	s_waitcnt vmcnt(33)
	v_mad_i64_i32 v[14:15], s[18:19], v13, s33, v[32:33]
	global_load_dword v13, v[14:15], off nt
	v_or_b32_e32 v14, 28, v34
	v_mad_i64_i32 v[14:15], s[18:19], v14, s33, v[32:33]
	global_load_dword v14, v[14:15], off nt
	v_or_b32_e32 v15, 30, v34
	s_waitcnt vmcnt(33)
	v_mad_i64_i32 v[16:17], s[18:19], v15, s33, v[32:33]
	global_load_dword v15, v[16:17], off nt
	v_or_b32_e32 v16, 32, v34
	v_mad_i64_i32 v[16:17], s[18:19], v16, s33, v[32:33]
	global_load_dword v16, v[16:17], off nt
	v_or_b32_e32 v17, 34, v34
	s_waitcnt vmcnt(33)
	v_mad_i64_i32 v[18:19], s[18:19], v17, s33, v[32:33]
	global_load_dword v17, v[18:19], off nt
	v_or_b32_e32 v18, 36, v34
	v_mad_i64_i32 v[18:19], s[18:19], v18, s33, v[32:33]
	global_load_dword v18, v[18:19], off nt
	v_or_b32_e32 v19, 38, v34
	s_waitcnt vmcnt(33)
	v_mad_i64_i32 v[20:21], s[18:19], v19, s33, v[32:33]
	global_load_dword v19, v[20:21], off nt
	v_or_b32_e32 v20, 40, v34
	v_mad_i64_i32 v[20:21], s[18:19], v20, s33, v[32:33]
	global_load_dword v20, v[20:21], off nt
	v_or_b32_e32 v21, 42, v34
	s_waitcnt vmcnt(33)
	v_mad_i64_i32 v[22:23], s[18:19], v21, s33, v[32:33]
	global_load_dword v21, v[22:23], off nt
	v_or_b32_e32 v22, 44, v34
	v_mad_i64_i32 v[22:23], s[18:19], v22, s33, v[32:33]
	global_load_dword v22, v[22:23], off nt
	v_or_b32_e32 v23, 46, v34
	s_waitcnt vmcnt(33)
	v_mad_i64_i32 v[24:25], s[18:19], v23, s33, v[32:33]
	global_load_dword v23, v[24:25], off nt
	v_or_b32_e32 v24, 48, v34
	v_mad_i64_i32 v[24:25], s[18:19], v24, s33, v[32:33]
	global_load_dword v24, v[24:25], off nt
	v_or_b32_e32 v25, 50, v34
	s_waitcnt vmcnt(33)
	v_mad_i64_i32 v[26:27], s[18:19], v25, s33, v[32:33]
	global_load_dword v25, v[26:27], off nt
	v_or_b32_e32 v26, 52, v34
	v_mad_i64_i32 v[26:27], s[18:19], v26, s33, v[32:33]
	global_load_dword v26, v[26:27], off nt
	v_or_b32_e32 v27, 54, v34
	s_waitcnt vmcnt(33)
	v_mad_i64_i32 v[28:29], s[18:19], v27, s33, v[32:33]
	global_load_dword v27, v[28:29], off nt
	v_or_b32_e32 v28, 56, v34
	v_mad_i64_i32 v[28:29], s[18:19], v28, s33, v[32:33]
	global_load_dword v28, v[28:29], off nt
	v_or_b32_e32 v29, 58, v34
	s_waitcnt vmcnt(33)
	v_mad_i64_i32 v[30:31], s[18:19], v29, s33, v[32:33]
	global_load_dword v29, v[30:31], off nt
	v_or_b32_e32 v30, 60, v34
	v_mad_i64_i32 v[30:31], s[18:19], v30, s33, v[32:33]
	global_load_dword v30, v[30:31], off nt
	v_or_b32_e32 v31, 62, v34
	v_mad_i64_i32 v[32:33], s[18:19], v31, s33, v[32:33]
	global_load_dword v31, v[32:33], off nt
	v_lshlrev_b32_e32 v33, 3, v132
	v_and_b32_e32 v33, 56, v33
	v_lshlrev_b32_e32 v192, 2, v33
	v_mul_u32_u24_e32 v33, 0x84, v33
	v_add_u32_e32 v32, s26, v48
	v_lshl_add_u64 v[50:51], s[16:17], 0, v[48:49]
	v_lshl_add_u64 v[52:53], s[14:15], 0, v[192:193]
	v_lshlrev_b32_e32 v34, 4, v132
	v_add3_u32 v49, s26, v33, v139
	s_lshl_b32 s14, s6, 5
	v_lshlrev_b32_e32 v33, 1, v138
	v_and_b32_e32 v47, 48, v34
	s_add_i32 s16, s14, 0xfffff400
	s_lshl_b32 s20, s8, 5
	v_lshl_or_b32 v54, s6, 6, v33
	s_lshl_b32 s21, s8, 6
	v_add_u32_e32 v55, v32, v136
	s_mov_b32 s17, s6
	v_readlane_b32 s57, v254, 61
	v_readlane_b32 s58, v254, 62
	v_readlane_b32 s59, v254, 63
	v_readlane_b32 s60, v255, 0
	v_readlane_b32 s61, v255, 1
	v_readlane_b32 s62, v255, 2
	v_readlane_b32 s63, v255, 3
	v_readlane_b32 s64, v255, 4
	v_readlane_b32 s65, v255, 5
	v_readlane_b32 s70, v255, 10
	v_readlane_b32 s71, v255, 11
	s_branch .LBB0_46

; #define LAS __attribute__((address_space(3)))
; __device__ __forceinline__ unsigned pk2(float lo, float hi) { f32x2 f = {lo, hi}; bf16x2_t b = __builtin_convertvector(f, bf16x2_t); return __builtin_bit_cast(unsigned, b); }
; __device__ __forceinline__ void tr_load(const float* W, int N, int item, int lane, float (&wv)[32]) {
;     const int nblk = N / 32, kb = item / nblk, nb = item % nblk, k0 = 64 * kb, n0 = 32 * nb;
; #pragma unroll
;     for (int i = 0; i < 32; ++i) { const int kk = 2 * i + (lane >> 5); wv[i] = __builtin_nontemporal_load(W + (size_t)(k0 + kk) * N + n0 + (lane & 31)); }
; }
; template <int MAP, bool HASG, bool PERMW>
; __device__ __forceinline__ void tr_store(int K, int N, bf16_t* WT, LAS float* scr, int item, int lane, const float* gk) {
;     const int nblk = N / 32, kb = item / nblk, nb = item % nblk, k0 = 64 * kb, n0 = 32 * nb;
;     asm volatile("s_waitcnt lgkmcnt(0)" ::: "memory");
;     const int c = lane & 7;
;     f32x4 g0 = {1.f, 1.f, 1.f, 1.f}, g1 = {1.f, 1.f, 1.f, 1.f};
;     if (HASG) { g0 = *(const f32x4*)(gk + k0 + 8 * c); g1 = *(const f32x4*)(gk + k0 + 8 * c + 4); }
; #pragma unroll
;     for (int j = 0; j < 4; ++j) { const int n = (lane >> 3) + 8 * j; const LAS float* s = scr + (8 * c) * 33 + n;
;         u32x4 o; o.x = pk2(s[0 * 33] * g0[0], s[1 * 33] * g0[1]); o.y = pk2(s[2 * 33] * g0[2], s[3 * 33] * g0[3]); o.z = pk2(s[4 * 33] * g1[0], s[5 * 33] * g1[1]); o.w = pk2(s[6 * 33] * g1[2], s[7 * 33] * g1[3]);
;         const int wr_ = rowmap<MAP>(n0 + n), slot_ = PERMW ? ((wr_ & ~31) + invperm32(wr_ & 31)) : wr_;
;         *(u32x4*)((char*)WT + tiled_off(slot_, k0 + 8 * c, K / 64)) = o; }
; __global__ void __launch_bounds__(512, 2) mega_fwd(Params p) {
;     ...
;             transpose_mat<0>(p.in[4] + (size_t)l * DFF * D, DFF, D, P_W(WS_WD1), scr, gw, ngw, lane);
.LBB0_158:
	s_cmpk_lt_u32 s2, 0x80
	s_cbranch_scc1 .Ltc1_done
	v_writelane_b32 v255, s4, 24
	v_writelane_b32 v255, s5, 25
	v_writelane_b32 v255, s6, 26
	v_writelane_b32 v255, s7, 27
	v_writelane_b32 v255, s8, 28
	v_writelane_b32 v255, s9, 29
	v_writelane_b32 v255, s10, 30
	v_writelane_b32 v255, s11, 31
	v_writelane_b32 v255, s12, 32
	v_writelane_b32 v255, s13, 33
	v_writelane_b32 v255, s14, 34
	v_writelane_b32 v255, s15, 35
	v_writelane_b32 v255, s16, 36
	v_writelane_b32 v255, s17, 37
	v_writelane_b32 v255, s18, 38
	v_writelane_b32 v255, s19, 39
	v_writelane_b32 v255, s20, 40
	v_writelane_b32 v255, s21, 41
	v_writelane_b32 v255, s22, 42
	v_writelane_b32 v255, s23, 43
	v_writelane_b32 v255, s24, 44
	v_writelane_b32 v255, s25, 45
	v_writelane_b32 v255, s26, 46
	v_writelane_b32 v255, s27, 47
	v_writelane_b32 v255, s28, 48
	v_writelane_b32 v255, s29, 49
	v_readfirstlane_b32 s8, v234
	s_nop 3
	s_lshr_b32 s8, s8, 6
	s_sub_u32 s18, s2, 0x80
	s_lshl_b32 s18, s18, 3
	s_add_u32 s18, s18, s8
	s_mul_i32 s10, s8, 0x2100
	v_and_b32_e32 v0, 63, v234
	v_and_b32_e32 v1, 31, v0
	v_lshrrev_b32_e32 v2, 5, v0
	v_lshlrev_b32_e32 v3, 13, v2
	v_lshl_add_u32 v3, v1, 2, v3
	v_mul_u32_u24_e32 v4, 33, v2
	v_add_u32_e32 v4, v4, v1
	v_lshl_add_u32 v4, v4, 2, s10
	v_and_b32_e32 v5, 7, v0
	v_lshrrev_b32_e32 v6, 3, v0
	v_mul_u32_u24_e32 v7, 0x108, v5
	v_add_u32_e32 v7, v7, v6
	v_lshl_add_u32 v7, v7, 2, s10
	v_lshrrev_b32_e32 v12, 2, v5
	v_lshlrev_b32_e32 v12, 10, v12
	v_and_b32_e32 v13, 3, v5
	v_lshl_add_u32 v12, v13, 4, v12
	v_lshl_add_u32 v8, v6, 6, v12
	v_xor_b32_e32 v9, 32, v8
	v_add_u32_e32 v9, 0x200, v9
	v_and_b32_e32 v13, 3, v6
	v_lshl_add_u32 v10, v13, 6, v12
	v_bfe_u32 v13, v6, 2, 1
	v_lshl_add_u32 v10, v13, 11, v10
	v_xor_b32_e32 v11, 32, v10
	v_lshlrev_b32_e32 v14, 5, v5
	v_mul_u32_u24_e32 v15, 0x5800, v2
	v_lshl_add_u32 v15, v1, 2, v15
	v_mul_u32_u24_e32 v12, 0xd000, v2
	v_lshl_add_u32 v12, v1, 2, v12
	v_readlane_b32 s4, v255, 4
	v_readlane_b32 s5, v255, 5
	s_nop 3
	s_and_b32 s6, s60, 0x2c00000
	s_add_u32 s4, s4, s6
	s_addc_u32 s5, s5, 0
	s_add_u32 s6, s76, 0x2c00000
	s_addc_u32 s7, s77, 0
	s_mov_b32 s9, s18
	s_cmpk_ge_u32 s9, 0x1600
	s_cbranch_scc1 .Ltc1a_exit
	s_lshr_b32 s11, s9, 6
	s_and_b32 s12, s9, 63
	s_lshl_b32 s13, s11, 19
	s_lshl_b32 s14, s12, 7
	s_add_u32 s13, s13, s14
	s_add_u32 s14, s4, s13
	s_addc_u32 s15, s5, 0
	global_load_dword v16, v3, s[14:15] nt
	s_add_u32 s14, s14, 0x4000
	s_addc_u32 s15, s15, 0
	global_load_dword v17, v3, s[14:15] nt
	s_add_u32 s14, s14, 0x4000
	s_addc_u32 s15, s15, 0
	global_load_dword v18, v3, s[14:15] nt
	s_add_u32 s14, s14, 0x4000
	s_addc_u32 s15, s15, 0
	global_load_dword v19, v3, s[14:15] nt
	s_add_u32 s14, s14, 0x4000
	s_addc_u32 s15, s15, 0
	global_load_dword v20, v3, s[14:15] nt
	s_add_u32 s14, s14, 0x4000
	s_addc_u32 s15, s15, 0
	global_load_dword v21, v3, s[14:15] nt
	s_add_u32 s14, s14, 0x4000
	s_addc_u32 s15, s15, 0
	global_load_dword v22, v3, s[14:15] nt
	s_add_u32 s14, s14, 0x4000
	s_addc_u32 s15, s15, 0
	global_load_dword v23, v3, s[14:15] nt
	s_add_u32 s14, s14, 0x4000
	s_addc_u32 s15, s15, 0
	global_load_dword v24, v3, s[14:15] nt
	s_add_u32 s14, s14, 0x4000
	s_addc_u32 s15, s15, 0
	global_load_dword v25, v3, s[14:15] nt
	s_add_u32 s14, s14, 0x4000
	s_addc_u32 s15, s15, 0
	global_load_dword v26, v3, s[14:15] nt
	s_add_u32 s14, s14, 0x4000
	s_addc_u32 s15, s15, 0
	global_load_dword v27, v3, s[14:15] nt
	s_add_u32 s14, s14, 0x4000
	s_addc_u32 s15, s15, 0
	global_load_dword v28, v3, s[14:15] nt
	s_add_u32 s14, s14, 0x4000
	s_addc_u32 s15, s15, 0
	global_load_dword v29, v3, s[14:15] nt
	s_add_u32 s14, s14, 0x4000
	s_addc_u32 s15, s15, 0
	global_load_dword v30, v3, s[14:15] nt
	s_add_u32 s14, s14, 0x4000
	s_addc_u32 s15, s15, 0
	global_load_dword v31, v3, s[14:15] nt
	s_add_u32 s14, s14, 0x4000
	s_addc_u32 s15, s15, 0
	global_load_dword v32, v3, s[14:15] nt
	s_add_u32 s14, s14, 0x4000
	s_addc_u32 s15, s15, 0
	global_load_dword v33, v3, s[14:15] nt
	s_add_u32 s14, s14, 0x4000
	s_addc_u32 s15, s15, 0
	global_load_dword v34, v3, s[14:15] nt
	s_add_u32 s14, s14, 0x4000
	s_addc_u32 s15, s15, 0
	global_load_dword v35, v3, s[14:15] nt
	s_add_u32 s14, s14, 0x4000
	s_addc_u32 s15, s15, 0
	global_load_dword v36, v3, s[14:15] nt
	s_add_u32 s14, s14, 0x4000
	s_addc_u32 s15, s15, 0
	global_load_dword v37, v3, s[14:15] nt
	s_add_u32 s14, s14, 0x4000
	s_addc_u32 s15, s15, 0
	global_load_dword v38, v3, s[14:15] nt
	s_add_u32 s14, s14, 0x4000
	s_addc_u32 s15, s15, 0
	global_load_dword v39, v3, s[14:15] nt
	s_add_u32 s14, s14, 0x4000
	s_addc_u32 s15, s15, 0
	global_load_dword v40, v3, s[14:15] nt
	s_add_u32 s14, s14, 0x4000
	s_addc_u32 s15, s15, 0
	global_load_dword v41, v3, s[14:15] nt
	s_add_u32 s14, s14, 0x4000
	s_addc_u32 s15, s15, 0
	global_load_dword v42, v3, s[14:15] nt
	s_add_u32 s14, s14, 0x4000
	s_addc_u32 s15, s15, 0
	global_load_dword v43, v3, s[14:15] nt
	s_add_u32 s14, s14, 0x4000
	s_addc_u32 s15, s15, 0
	global_load_dword v44, v3, s[14:15] nt
	s_add_u32 s14, s14, 0x4000
	s_addc_u32 s15, s15, 0
	global_load_dword v45, v3, s[14:15] nt
	s_add_u32 s14, s14, 0x4000
	s_addc_u32 s15, s15, 0
	global_load_dword v46, v3, s[14:15] nt
	s_add_u32 s14, s14, 0x4000
	s_addc_u32 s15, s15, 0
	global_load_dword v47, v3, s[14:15] nt
	s_lshr_b32 s16, s12, 2
	s_mul_i32 s16, s16, 0x58
	s_add_u32 s16, s16, s11
	s_lshl_b32 s16, s16, 14
	s_and_b32 s17, s12, 3
	s_lshl_b32 s17, s17, 12
	s_add_u32 s16, s16, s17
	s_add_u32 s16, s6, s16
	s_addc_u32 s17, s7, 0
; __device__ __forceinline__ void tr_load(const float* W, int N, int item, int lane, float (&wv)[32]) {
;     const int nblk = N / 32, kb = item / nblk, nb = item % nblk, k0 = 64 * kb, n0 = 32 * nb;
; #pragma unroll
;     for (int i = 0; i < 32; ++i) { const int kk = 2 * i + (lane >> 5); wv[i] = __builtin_nontemporal_load(W + (size_t)(k0 + kk) * N + n0 + (lane & 31)); }
; }
; template <int MAP, bool HASG, bool PERMW>
; __device__ __forceinline__ void tr_store(int K, int N, bf16_t* WT, LAS float* scr, int item, int lane, const float* gk) {
;     const int nblk = N / 32, kb = item / nblk, nb = item % nblk, k0 = 64 * kb, n0 = 32 * nb;
;     asm volatile("s_waitcnt lgkmcnt(0)" ::: "memory");
;     const int c = lane & 7;
;     f32x4 g0 = {1.f, 1.f, 1.f, 1.f}, g1 = {1.f, 1.f, 1.f, 1.f};
;     if (HASG) { g0 = *(const f32x4*)(gk + k0 + 8 * c); g1 = *(const f32x4*)(gk + k0 + 8 * c + 4); }
; #pragma unroll
;     for (int j = 0; j < 4; ++j) { const int n = (lane >> 3) + 8 * j; const LAS float* s = scr + (8 * c) * 33 + n;
;         u32x4 o; o.x = pk2(s[0 * 33] * g0[0], s[1 * 33] * g0[1]); o.y = pk2(s[2 * 33] * g0[2], s[3 * 33] * g0[3]); o.z = pk2(s[4 * 33] * g1[0], s[5 * 33] * g1[1]); o.w = pk2(s[6 * 33] * g1[2], s[7 * 33] * g1[3]);
;         const int wr_ = rowmap<MAP>(n0 + n), slot_ = PERMW ? ((wr_ & ~31) + invperm32(wr_ & 31)) : wr_;
;         *(u32x4*)((char*)WT + tiled_off(slot_, k0 + 8 * c, K / 64)) = o; }
;     asm volatile("s_waitcnt lgkmcnt(0)" ::: "memory");
; }
; template <int MAP, bool HASG = false, bool PERMW = false>
; __device__ __forceinline__ void transpose_mat(const float* W, int K, int N, bf16_t* WT, LAS float* scr, int gw, int ngw, int lane, const float* gk = nullptr) {
;     const int nitems = (K / 64) * (N / 32);
;     int it = gw;
;     if (it >= nitems) return;
;     float wv[32];
;     tr_load(W, N, it, lane, wv);
;     for (;;) {
;         __builtin_amdgcn_sched_barrier(0);
; #pragma unroll
;         for (int i = 0; i < 32; ++i) { const int kk = 2 * i + (lane >> 5); scr[kk * 33 + (lane & 31)] = wv[i]; }
;         __builtin_amdgcn_sched_barrier(0);
;         const int nx = it + ngw;
;         if (nx < nitems) tr_load(W, N, nx, lane, wv);
;         __builtin_amdgcn_sched_barrier(0);
;         tr_store<MAP, HASG, PERMW>(K, N, WT, scr, it, lane, gk);
;         if (nx >= nitems) break;
;         it = nx;
.Ltc1a_loop:
	s_add_u32 s9, s9, 0x400
	s_cmpk_ge_u32 s9, 0x1600
	s_cbranch_scc1 .Ltc1a_lastA
	s_lshr_b32 s11, s9, 6
	s_and_b32 s12, s9, 63
	s_lshl_b32 s13, s11, 19
	s_lshl_b32 s14, s12, 7
	s_add_u32 s13, s13, s14
	s_add_u32 s14, s4, s13
	s_addc_u32 s15, s5, 0
	global_load_dword v88, v3, s[14:15] nt
	s_add_u32 s14, s14, 0x4000
	s_addc_u32 s15, s15, 0
	global_load_dword v89, v3, s[14:15] nt
	s_add_u32 s14, s14, 0x4000
	s_addc_u32 s15, s15, 0
	global_load_dword v90, v3, s[14:15] nt
	s_add_u32 s14, s14, 0x4000
	s_addc_u32 s15, s15, 0
	global_load_dword v91, v3, s[14:15] nt
	s_add_u32 s14, s14, 0x4000
	s_addc_u32 s15, s15, 0
	global_load_dword v92, v3, s[14:15] nt
	s_add_u32 s14, s14, 0x4000
	s_addc_u32 s15, s15, 0
	global_load_dword v93, v3, s[14:15] nt
	s_add_u32 s14, s14, 0x4000
	s_addc_u32 s15, s15, 0
	global_load_dword v94, v3, s[14:15] nt
	s_add_u32 s14, s14, 0x4000
	s_addc_u32 s15, s15, 0
	global_load_dword v95, v3, s[14:15] nt
	s_add_u32 s14, s14, 0x4000
	s_addc_u32 s15, s15, 0
	global_load_dword v96, v3, s[14:15] nt
	s_add_u32 s14, s14, 0x4000
	s_addc_u32 s15, s15, 0
	global_load_dword v97, v3, s[14:15] nt
	s_add_u32 s14, s14, 0x4000
	s_addc_u32 s15, s15, 0
	global_load_dword v98, v3, s[14:15] nt
	s_add_u32 s14, s14, 0x4000
	s_addc_u32 s15, s15, 0
	global_load_dword v99, v3, s[14:15] nt
	s_add_u32 s14, s14, 0x4000
	s_addc_u32 s15, s15, 0
	global_load_dword v100, v3, s[14:15] nt
	s_add_u32 s14, s14, 0x4000
	s_addc_u32 s15, s15, 0
	global_load_dword v101, v3, s[14:15] nt
	s_add_u32 s14, s14, 0x4000
	s_addc_u32 s15, s15, 0
	global_load_dword v102, v3, s[14:15] nt
	s_add_u32 s14, s14, 0x4000
	s_addc_u32 s15, s15, 0
	global_load_dword v103, v3, s[14:15] nt
	s_add_u32 s14, s14, 0x4000
	s_addc_u32 s15, s15, 0
	global_load_dword v104, v3, s[14:15] nt
	s_add_u32 s14, s14, 0x4000
	s_addc_u32 s15, s15, 0
	global_load_dword v105, v3, s[14:15] nt
	s_add_u32 s14, s14, 0x4000
	s_addc_u32 s15, s15, 0
	global_load_dword v106, v3, s[14:15] nt
	s_add_u32 s14, s14, 0x4000
	s_addc_u32 s15, s15, 0
	global_load_dword v107, v3, s[14:15] nt
	s_add_u32 s14, s14, 0x4000
	s_addc_u32 s15, s15, 0
	global_load_dword v108, v3, s[14:15] nt
	s_add_u32 s14, s14, 0x4000
	s_addc_u32 s15, s15, 0
	global_load_dword v109, v3, s[14:15] nt
	s_add_u32 s14, s14, 0x4000
	s_addc_u32 s15, s15, 0
	global_load_dword v110, v3, s[14:15] nt
	s_add_u32 s14, s14, 0x4000
	s_addc_u32 s15, s15, 0
	global_load_dword v111, v3, s[14:15] nt
	s_add_u32 s14, s14, 0x4000
	s_addc_u32 s15, s15, 0
	global_load_dword v112, v3, s[14:15] nt
	s_add_u32 s14, s14, 0x4000
	s_addc_u32 s15, s15, 0
	global_load_dword v113, v3, s[14:15] nt
	s_add_u32 s14, s14, 0x4000
	s_addc_u32 s15, s15, 0
	global_load_dword v114, v3, s[14:15] nt
	s_add_u32 s14, s14, 0x4000
	s_addc_u32 s15, s15, 0
	global_load_dword v115, v3, s[14:15] nt
	s_add_u32 s14, s14, 0x4000
	s_addc_u32 s15, s15, 0
	global_load_dword v116, v3, s[14:15] nt
	s_add_u32 s14, s14, 0x4000
	s_addc_u32 s15, s15, 0
	global_load_dword v117, v3, s[14:15] nt
	s_add_u32 s14, s14, 0x4000
	s_addc_u32 s15, s15, 0
	global_load_dword v118, v3, s[14:15] nt
	s_add_u32 s14, s14, 0x4000
	s_addc_u32 s15, s15, 0
	global_load_dword v119, v3, s[14:15] nt
	s_lshr_b32 s24, s12, 2
	s_mul_i32 s24, s24, 0x58
	s_add_u32 s24, s24, s11
	s_lshl_b32 s24, s24, 14
	s_and_b32 s25, s12, 3
	s_lshl_b32 s25, s25, 12
	s_add_u32 s24, s24, s25
	s_add_u32 s24, s6, s24
	s_addc_u32 s25, s7, 0
	s_waitcnt vmcnt(32)
	ds_write_b32 v4, v16
	ds_write_b32 v4, v17 offset:264
	ds_write_b32 v4, v18 offset:528
	ds_write_b32 v4, v19 offset:792
	ds_write_b32 v4, v20 offset:1056
	ds_write_b32 v4, v21 offset:1320
	ds_write_b32 v4, v22 offset:1584
	ds_write_b32 v4, v23 offset:1848
	ds_write_b32 v4, v24 offset:2112
	ds_write_b32 v4, v25 offset:2376
	ds_write_b32 v4, v26 offset:2640
	ds_write_b32 v4, v27 offset:2904
	ds_write_b32 v4, v28 offset:3168
	ds_write_b32 v4, v29 offset:3432
	ds_write_b32 v4, v30 offset:3696
	ds_write_b32 v4, v31 offset:3960
	ds_write_b32 v4, v32 offset:4224
	ds_write_b32 v4, v33 offset:4488
	ds_write_b32 v4, v34 offset:4752
	ds_write_b32 v4, v35 offset:5016
	ds_write_b32 v4, v36 offset:5280
	ds_write_b32 v4, v37 offset:5544
	ds_write_b32 v4, v38 offset:5808
	ds_write_b32 v4, v39 offset:6072
	ds_write_b32 v4, v40 offset:6336
	ds_write_b32 v4, v41 offset:6600
	ds_write_b32 v4, v42 offset:6864
	ds_write_b32 v4, v43 offset:7128
	ds_write_b32 v4, v44 offset:7392
	ds_write_b32 v4, v45 offset:7656
	ds_write_b32 v4, v46 offset:7920
	ds_write_b32 v4, v47 offset:8184
	s_waitcnt lgkmcnt(0)
	ds_read_b32 v48, v7
	ds_read_b32 v49, v7 offset:132
	ds_read_b32 v50, v7 offset:264
	ds_read_b32 v51, v7 offset:396
	ds_read_b32 v52, v7 offset:528
	ds_read_b32 v53, v7 offset:660
	ds_read_b32 v54, v7 offset:792
	ds_read_b32 v55, v7 offset:924
	ds_read_b32 v56, v7 offset:32
	ds_read_b32 v57, v7 offset:164
	ds_read_b32 v58, v7 offset:296
	ds_read_b32 v59, v7 offset:428
	ds_read_b32 v60, v7 offset:560
	ds_read_b32 v61, v7 offset:692
	ds_read_b32 v62, v7 offset:824
	ds_read_b32 v63, v7 offset:956
	ds_read_b32 v64, v7 offset:64
	ds_read_b32 v65, v7 offset:196
	ds_read_b32 v66, v7 offset:328
	ds_read_b32 v67, v7 offset:460
	ds_read_b32 v68, v7 offset:592
	ds_read_b32 v69, v7 offset:724
	ds_read_b32 v70, v7 offset:856
	ds_read_b32 v71, v7 offset:988
	ds_read_b32 v72, v7 offset:96
	ds_read_b32 v73, v7 offset:228
	ds_read_b32 v74, v7 offset:360
	ds_read_b32 v75, v7 offset:492
	ds_read_b32 v76, v7 offset:624
	ds_read_b32 v77, v7 offset:756
	ds_read_b32 v78, v7 offset:888
	ds_read_b32 v79, v7 offset:1020
	s_waitcnt lgkmcnt(0)
	v_cvt_pk_bf16_f32 v48, v48, v49
	v_cvt_pk_bf16_f32 v49, v50, v51
	v_cvt_pk_bf16_f32 v50, v52, v53
	v_cvt_pk_bf16_f32 v51, v54, v55
	global_store_dwordx4 v8, v[48:51], s[16:17]
	v_cvt_pk_bf16_f32 v56, v56, v57
	v_cvt_pk_bf16_f32 v57, v58, v59
	v_cvt_pk_bf16_f32 v58, v60, v61
	v_cvt_pk_bf16_f32 v59, v62, v63
	global_store_dwordx4 v9, v[56:59], s[16:17]
	v_cvt_pk_bf16_f32 v64, v64, v65
	v_cvt_pk_bf16_f32 v65, v66, v67
	v_cvt_pk_bf16_f32 v66, v68, v69
	v_cvt_pk_bf16_f32 v67, v70, v71
	global_store_dwordx4 v8, v[64:67], s[16:17] offset:2048
	v_cvt_pk_bf16_f32 v72, v72, v73
	v_cvt_pk_bf16_f32 v73, v74, v75
	v_cvt_pk_bf16_f32 v74, v76, v77
	v_cvt_pk_bf16_f32 v75, v78, v79
	global_store_dwordx4 v9, v[72:75], s[16:17] offset:2048
	s_add_u32 s9, s9, 0x400
	s_cmpk_ge_u32 s9, 0x1600
	s_cbranch_scc1 .Ltc1a_lastB
; __device__ __forceinline__ void tr_load(const float* W, int N, int item, int lane, float (&wv)[32]) {
;     const int nblk = N / 32, kb = item / nblk, nb = item % nblk, k0 = 64 * kb, n0 = 32 * nb;
; #pragma unroll
;     for (int i = 0; i < 32; ++i) { const int kk = 2 * i + (lane >> 5); wv[i] = __builtin_nontemporal_load(W + (size_t)(k0 + kk) * N + n0 + (lane & 31)); }
; }
; template <int MAP, bool HASG, bool PERMW>
; __device__ __forceinline__ void tr_store(int K, int N, bf16_t* WT, LAS float* scr, int item, int lane, const float* gk) {
;     const int nblk = N / 32, kb = item / nblk, nb = item % nblk, k0 = 64 * kb, n0 = 32 * nb;
;     asm volatile("s_waitcnt lgkmcnt(0)" ::: "memory");
;     const int c = lane & 7;
;     f32x4 g0 = {1.f, 1.f, 1.f, 1.f}, g1 = {1.f, 1.f, 1.f, 1.f};
;     if (HASG) { g0 = *(const f32x4*)(gk + k0 + 8 * c); g1 = *(const f32x4*)(gk + k0 + 8 * c + 4); }
; #pragma unroll
;     for (int j = 0; j < 4; ++j) { const int n = (lane >> 3) + 8 * j; const LAS float* s = scr + (8 * c) * 33 + n;
;         u32x4 o; o.x = pk2(s[0 * 33] * g0[0], s[1 * 33] * g0[1]); o.y = pk2(s[2 * 33] * g0[2], s[3 * 33] * g0[3]); o.z = pk2(s[4 * 33] * g1[0], s[5 * 33] * g1[1]); o.w = pk2(s[6 * 33] * g1[2], s[7 * 33] * g1[3]);
;         const int wr_ = rowmap<MAP>(n0 + n), slot_ = PERMW ? ((wr_ & ~31) + invperm32(wr_ & 31)) : wr_;
;         *(u32x4*)((char*)WT + tiled_off(slot_, k0 + 8 * c, K / 64)) = o; }
;     asm volatile("s_waitcnt lgkmcnt(0)" ::: "memory");
; }
; template <int MAP, bool HASG = false, bool PERMW = false>
; __device__ __forceinline__ void transpose_mat(const float* W, int K, int N, bf16_t* WT, LAS float* scr, int gw, int ngw, int lane, const float* gk = nullptr) {
;     const int nitems = (K / 64) * (N / 32);
;     int it = gw;
;     if (it >= nitems) return;
;     float wv[32];
;     tr_load(W, N, it, lane, wv);
;     for (;;) {
;         __builtin_amdgcn_sched_barrier(0);
; #pragma unroll
;         for (int i = 0; i < 32; ++i) { const int kk = 2 * i + (lane >> 5); scr[kk * 33 + (lane & 31)] = wv[i]; }
;         __builtin_amdgcn_sched_barrier(0);
;         const int nx = it + ngw;
;         if (nx < nitems) tr_load(W, N, nx, lane, wv);
;         __builtin_amdgcn_sched_barrier(0);
;         tr_store<MAP, HASG, PERMW>(K, N, WT, scr, it, lane, gk);
;         if (nx >= nitems) break;
;         it = nx;
	s_lshr_b32 s11, s9, 6
	s_and_b32 s12, s9, 63
	s_lshl_b32 s13, s11, 19
	s_lshl_b32 s14, s12, 7
	s_add_u32 s13, s13, s14
	s_add_u32 s14, s4, s13
	s_addc_u32 s15, s5, 0
	global_load_dword v16, v3, s[14:15] nt
	s_add_u32 s14, s14, 0x4000
	s_addc_u32 s15, s15, 0
	global_load_dword v17, v3, s[14:15] nt
	s_add_u32 s14, s14, 0x4000
	s_addc_u32 s15, s15, 0
	global_load_dword v18, v3, s[14:15] nt
	s_add_u32 s14, s14, 0x4000
	s_addc_u32 s15, s15, 0
	global_load_dword v19, v3, s[14:15] nt
	s_add_u32 s14, s14, 0x4000
	s_addc_u32 s15, s15, 0
	global_load_dword v20, v3, s[14:15] nt
	s_add_u32 s14, s14, 0x4000
	s_addc_u32 s15, s15, 0
	global_load_dword v21, v3, s[14:15] nt
	s_add_u32 s14, s14, 0x4000
	s_addc_u32 s15, s15, 0
	global_load_dword v22, v3, s[14:15] nt
	s_add_u32 s14, s14, 0x4000
	s_addc_u32 s15, s15, 0
	global_load_dword v23, v3, s[14:15] nt
	s_add_u32 s14, s14, 0x4000
	s_addc_u32 s15, s15, 0
	global_load_dword v24, v3, s[14:15] nt
	s_add_u32 s14, s14, 0x4000
	s_addc_u32 s15, s15, 0
	global_load_dword v25, v3, s[14:15] nt
	s_add_u32 s14, s14, 0x4000
	s_addc_u32 s15, s15, 0
	global_load_dword v26, v3, s[14:15] nt
	s_add_u32 s14, s14, 0x4000
	s_addc_u32 s15, s15, 0
	global_load_dword v27, v3, s[14:15] nt
	s_add_u32 s14, s14, 0x4000
	s_addc_u32 s15, s15, 0
	global_load_dword v28, v3, s[14:15] nt
	s_add_u32 s14, s14, 0x4000
	s_addc_u32 s15, s15, 0
	global_load_dword v29, v3, s[14:15] nt
	s_add_u32 s14, s14, 0x4000
	s_addc_u32 s15, s15, 0
	global_load_dword v30, v3, s[14:15] nt
	s_add_u32 s14, s14, 0x4000
	s_addc_u32 s15, s15, 0
	global_load_dword v31, v3, s[14:15] nt
	s_add_u32 s14, s14, 0x4000
	s_addc_u32 s15, s15, 0
	global_load_dword v32, v3, s[14:15] nt
	s_add_u32 s14, s14, 0x4000
	s_addc_u32 s15, s15, 0
	global_load_dword v33, v3, s[14:15] nt
	s_add_u32 s14, s14, 0x4000
	s_addc_u32 s15, s15, 0
	global_load_dword v34, v3, s[14:15] nt
	s_add_u32 s14, s14, 0x4000
	s_addc_u32 s15, s15, 0
	global_load_dword v35, v3, s[14:15] nt
	s_add_u32 s14, s14, 0x4000
	s_addc_u32 s15, s15, 0
	global_load_dword v36, v3, s[14:15] nt
	s_add_u32 s14, s14, 0x4000
	s_addc_u32 s15, s15, 0
	global_load_dword v37, v3, s[14:15] nt
	s_add_u32 s14, s14, 0x4000
	s_addc_u32 s15, s15, 0
	global_load_dword v38, v3, s[14:15] nt
	s_add_u32 s14, s14, 0x4000
	s_addc_u32 s15, s15, 0
	global_load_dword v39, v3, s[14:15] nt
	s_add_u32 s14, s14, 0x4000
	s_addc_u32 s15, s15, 0
	global_load_dword v40, v3, s[14:15] nt
	s_add_u32 s14, s14, 0x4000
	s_addc_u32 s15, s15, 0
	global_load_dword v41, v3, s[14:15] nt
	s_add_u32 s14, s14, 0x4000
	s_addc_u32 s15, s15, 0
	global_load_dword v42, v3, s[14:15] nt
	s_add_u32 s14, s14, 0x4000
	s_addc_u32 s15, s15, 0
	global_load_dword v43, v3, s[14:15] nt
	s_add_u32 s14, s14, 0x4000
	s_addc_u32 s15, s15, 0
	global_load_dword v44, v3, s[14:15] nt
	s_add_u32 s14, s14, 0x4000
	s_addc_u32 s15, s15, 0
	global_load_dword v45, v3, s[14:15] nt
	s_add_u32 s14, s14, 0x4000
	s_addc_u32 s15, s15, 0
	global_load_dword v46, v3, s[14:15] nt
	s_add_u32 s14, s14, 0x4000
	s_addc_u32 s15, s15, 0
	global_load_dword v47, v3, s[14:15] nt
	s_lshr_b32 s16, s12, 2
	s_mul_i32 s16, s16, 0x58
	s_add_u32 s16, s16, s11
	s_lshl_b32 s16, s16, 14
	s_and_b32 s17, s12, 3
	s_lshl_b32 s17, s17, 12
	s_add_u32 s16, s16, s17
	s_add_u32 s16, s6, s16
	s_addc_u32 s17, s7, 0
	s_waitcnt vmcnt(32)
	ds_write_b32 v4, v88
	ds_write_b32 v4, v89 offset:264
	ds_write_b32 v4, v90 offset:528
	ds_write_b32 v4, v91 offset:792
	ds_write_b32 v4, v92 offset:1056
	ds_write_b32 v4, v93 offset:1320
	ds_write_b32 v4, v94 offset:1584
	ds_write_b32 v4, v95 offset:1848
	ds_write_b32 v4, v96 offset:2112
	ds_write_b32 v4, v97 offset:2376
	ds_write_b32 v4, v98 offset:2640
	ds_write_b32 v4, v99 offset:2904
	ds_write_b32 v4, v100 offset:3168
	ds_write_b32 v4, v101 offset:3432
	ds_write_b32 v4, v102 offset:3696
	ds_write_b32 v4, v103 offset:3960
	ds_write_b32 v4, v104 offset:4224
	ds_write_b32 v4, v105 offset:4488
	ds_write_b32 v4, v106 offset:4752
	ds_write_b32 v4, v107 offset:5016
	ds_write_b32 v4, v108 offset:5280
	ds_write_b32 v4, v109 offset:5544
	ds_write_b32 v4, v110 offset:5808
	ds_write_b32 v4, v111 offset:6072
	ds_write_b32 v4, v112 offset:6336
	ds_write_b32 v4, v113 offset:6600
	ds_write_b32 v4, v114 offset:6864
	ds_write_b32 v4, v115 offset:7128
	ds_write_b32 v4, v116 offset:7392
	ds_write_b32 v4, v117 offset:7656
	ds_write_b32 v4, v118 offset:7920
	ds_write_b32 v4, v119 offset:8184
	s_waitcnt lgkmcnt(0)
	ds_read_b32 v48, v7
	ds_read_b32 v49, v7 offset:132
	ds_read_b32 v50, v7 offset:264
	ds_read_b32 v51, v7 offset:396
	ds_read_b32 v52, v7 offset:528
	ds_read_b32 v53, v7 offset:660
	ds_read_b32 v54, v7 offset:792
	ds_read_b32 v55, v7 offset:924
	ds_read_b32 v56, v7 offset:32
	ds_read_b32 v57, v7 offset:164
	ds_read_b32 v58, v7 offset:296
	ds_read_b32 v59, v7 offset:428
	ds_read_b32 v60, v7 offset:560
	ds_read_b32 v61, v7 offset:692
	ds_read_b32 v62, v7 offset:824
	ds_read_b32 v63, v7 offset:956
	ds_read_b32 v64, v7 offset:64
	ds_read_b32 v65, v7 offset:196
	ds_read_b32 v66, v7 offset:328
	ds_read_b32 v67, v7 offset:460
	ds_read_b32 v68, v7 offset:592
	ds_read_b32 v69, v7 offset:724
	ds_read_b32 v70, v7 offset:856
	ds_read_b32 v71, v7 offset:988
	ds_read_b32 v72, v7 offset:96
	ds_read_b32 v73, v7 offset:228
	ds_read_b32 v74, v7 offset:360
	ds_read_b32 v75, v7 offset:492
	ds_read_b32 v76, v7 offset:624
	ds_read_b32 v77, v7 offset:756
	ds_read_b32 v78, v7 offset:888
	ds_read_b32 v79, v7 offset:1020
	s_waitcnt lgkmcnt(0)
	v_cvt_pk_bf16_f32 v48, v48, v49
	v_cvt_pk_bf16_f32 v49, v50, v51
	v_cvt_pk_bf16_f32 v50, v52, v53
	v_cvt_pk_bf16_f32 v51, v54, v55
	global_store_dwordx4 v8, v[48:51], s[24:25]
	v_cvt_pk_bf16_f32 v56, v56, v57
	v_cvt_pk_bf16_f32 v57, v58, v59
	v_cvt_pk_bf16_f32 v58, v60, v61
	v_cvt_pk_bf16_f32 v59, v62, v63
	global_store_dwordx4 v9, v[56:59], s[24:25]
	v_cvt_pk_bf16_f32 v64, v64, v65
	v_cvt_pk_bf16_f32 v65, v66, v67
	v_cvt_pk_bf16_f32 v66, v68, v69
	v_cvt_pk_bf16_f32 v67, v70, v71
	global_store_dwordx4 v8, v[64:67], s[24:25] offset:2048
	v_cvt_pk_bf16_f32 v72, v72, v73
	v_cvt_pk_bf16_f32 v73, v74, v75
	v_cvt_pk_bf16_f32 v74, v76, v77
	v_cvt_pk_bf16_f32 v75, v78, v79
	global_store_dwordx4 v9, v[72:75], s[24:25] offset:2048
	s_branch .Ltc1a_loop
; #define LAS __attribute__((address_space(3)))
; __device__ __forceinline__ unsigned pk2(float lo, float hi) { f32x2 f = {lo, hi}; bf16x2_t b = __builtin_convertvector(f, bf16x2_t); return __builtin_bit_cast(unsigned, b); }
; template <int MAP, bool HASG, bool PERMW>
; __device__ __forceinline__ void tr_store(int K, int N, bf16_t* WT, LAS float* scr, int item, int lane, const float* gk) {
;     const int nblk = N / 32, kb = item / nblk, nb = item % nblk, k0 = 64 * kb, n0 = 32 * nb;
;     asm volatile("s_waitcnt lgkmcnt(0)" ::: "memory");
;     const int c = lane & 7;
;     f32x4 g0 = {1.f, 1.f, 1.f, 1.f}, g1 = {1.f, 1.f, 1.f, 1.f};
;     if (HASG) { g0 = *(const f32x4*)(gk + k0 + 8 * c); g1 = *(const f32x4*)(gk + k0 + 8 * c + 4); }
; #pragma unroll
;     for (int j = 0; j < 4; ++j) { const int n = (lane >> 3) + 8 * j; const LAS float* s = scr + (8 * c) * 33 + n;
;         u32x4 o; o.x = pk2(s[0 * 33] * g0[0], s[1 * 33] * g0[1]); o.y = pk2(s[2 * 33] * g0[2], s[3 * 33] * g0[3]); o.z = pk2(s[4 * 33] * g1[0], s[5 * 33] * g1[1]); o.w = pk2(s[6 * 33] * g1[2], s[7 * 33] * g1[3]);
;         const int wr_ = rowmap<MAP>(n0 + n), slot_ = PERMW ? ((wr_ & ~31) + invperm32(wr_ & 31)) : wr_;
;         *(u32x4*)((char*)WT + tiled_off(slot_, k0 + 8 * c, K / 64)) = o; }
;     asm volatile("s_waitcnt lgkmcnt(0)" ::: "memory");
; }
; template <int MAP, bool HASG = false, bool PERMW = false>
; __device__ __forceinline__ void transpose_mat(const float* W, int K, int N, bf16_t* WT, LAS float* scr, int gw, int ngw, int lane, const float* gk = nullptr) {
;     ...
;         for (int i = 0; i < 32; ++i) { const int kk = 2 * i + (lane >> 5); scr[kk * 33 + (lane & 31)] = wv[i]; }
.Ltc1a_lastA:
	s_waitcnt vmcnt(0)
	ds_write_b32 v4, v16
	ds_write_b32 v4, v17 offset:264
	ds_write_b32 v4, v18 offset:528
	ds_write_b32 v4, v19 offset:792
	ds_write_b32 v4, v20 offset:1056
	ds_write_b32 v4, v21 offset:1320
	ds_write_b32 v4, v22 offset:1584
	ds_write_b32 v4, v23 offset:1848
	ds_write_b32 v4, v24 offset:2112
	ds_write_b32 v4, v25 offset:2376
	ds_write_b32 v4, v26 offset:2640
	ds_write_b32 v4, v27 offset:2904
	ds_write_b32 v4, v28 offset:3168
	ds_write_b32 v4, v29 offset:3432
	ds_write_b32 v4, v30 offset:3696
	ds_write_b32 v4, v31 offset:3960
	ds_write_b32 v4, v32 offset:4224
	ds_write_b32 v4, v33 offset:4488
	ds_write_b32 v4, v34 offset:4752
	ds_write_b32 v4, v35 offset:5016
	ds_write_b32 v4, v36 offset:5280
	ds_write_b32 v4, v37 offset:5544
	ds_write_b32 v4, v38 offset:5808
	ds_write_b32 v4, v39 offset:6072
	ds_write_b32 v4, v40 offset:6336
	ds_write_b32 v4, v41 offset:6600
	ds_write_b32 v4, v42 offset:6864
	ds_write_b32 v4, v43 offset:7128
	ds_write_b32 v4, v44 offset:7392
	ds_write_b32 v4, v45 offset:7656
	ds_write_b32 v4, v46 offset:7920
	ds_write_b32 v4, v47 offset:8184
	s_waitcnt lgkmcnt(0)
	ds_read_b32 v48, v7
	ds_read_b32 v49, v7 offset:132
	ds_read_b32 v50, v7 offset:264
	ds_read_b32 v51, v7 offset:396
	ds_read_b32 v52, v7 offset:528
	ds_read_b32 v53, v7 offset:660
	ds_read_b32 v54, v7 offset:792
	ds_read_b32 v55, v7 offset:924
	ds_read_b32 v56, v7 offset:32
	ds_read_b32 v57, v7 offset:164
	ds_read_b32 v58, v7 offset:296
	ds_read_b32 v59, v7 offset:428
	ds_read_b32 v60, v7 offset:560
	ds_read_b32 v61, v7 offset:692
	ds_read_b32 v62, v7 offset:824
	ds_read_b32 v63, v7 offset:956
	ds_read_b32 v64, v7 offset:64
	ds_read_b32 v65, v7 offset:196
	ds_read_b32 v66, v7 offset:328
	ds_read_b32 v67, v7 offset:460
	ds_read_b32 v68, v7 offset:592
	ds_read_b32 v69, v7 offset:724
	ds_read_b32 v70, v7 offset:856
	ds_read_b32 v71, v7 offset:988
	ds_read_b32 v72, v7 offset:96
	ds_read_b32 v73, v7 offset:228
	ds_read_b32 v74, v7 offset:360
	ds_read_b32 v75, v7 offset:492
	ds_read_b32 v76, v7 offset:624
	ds_read_b32 v77, v7 offset:756
	ds_read_b32 v78, v7 offset:888
	ds_read_b32 v79, v7 offset:1020
	s_waitcnt lgkmcnt(0)
	v_cvt_pk_bf16_f32 v48, v48, v49
	v_cvt_pk_bf16_f32 v49, v50, v51
	v_cvt_pk_bf16_f32 v50, v52, v53
	v_cvt_pk_bf16_f32 v51, v54, v55
	global_store_dwordx4 v8, v[48:51], s[16:17]
	v_cvt_pk_bf16_f32 v56, v56, v57
	v_cvt_pk_bf16_f32 v57, v58, v59
	v_cvt_pk_bf16_f32 v58, v60, v61
	v_cvt_pk_bf16_f32 v59, v62, v63
	global_store_dwordx4 v9, v[56:59], s[16:17]
	v_cvt_pk_bf16_f32 v64, v64, v65
	v_cvt_pk_bf16_f32 v65, v66, v67
	v_cvt_pk_bf16_f32 v66, v68, v69
	v_cvt_pk_bf16_f32 v67, v70, v71
	global_store_dwordx4 v8, v[64:67], s[16:17] offset:2048
	v_cvt_pk_bf16_f32 v72, v72, v73
	v_cvt_pk_bf16_f32 v73, v74, v75
	v_cvt_pk_bf16_f32 v74, v76, v77
	v_cvt_pk_bf16_f32 v75, v78, v79
	global_store_dwordx4 v9, v[72:75], s[16:17] offset:2048
	s_branch .Ltc1a_exit
.Ltc1a_lastB:
	s_waitcnt vmcnt(0)
	ds_write_b32 v4, v88
	ds_write_b32 v4, v89 offset:264
	ds_write_b32 v4, v90 offset:528
	ds_write_b32 v4, v91 offset:792
	ds_write_b32 v4, v92 offset:1056
	ds_write_b32 v4, v93 offset:1320
	ds_write_b32 v4, v94 offset:1584
	ds_write_b32 v4, v95 offset:1848
	ds_write_b32 v4, v96 offset:2112
	ds_write_b32 v4, v97 offset:2376
	ds_write_b32 v4, v98 offset:2640
	ds_write_b32 v4, v99 offset:2904
	ds_write_b32 v4, v100 offset:3168
	ds_write_b32 v4, v101 offset:3432
	ds_write_b32 v4, v102 offset:3696
	ds_write_b32 v4, v103 offset:3960
	ds_write_b32 v4, v104 offset:4224
	ds_write_b32 v4, v105 offset:4488
	ds_write_b32 v4, v106 offset:4752
	ds_write_b32 v4, v107 offset:5016
	ds_write_b32 v4, v108 offset:5280
	ds_write_b32 v4, v109 offset:5544
	ds_write_b32 v4, v110 offset:5808
	ds_write_b32 v4, v111 offset:6072
	ds_write_b32 v4, v112 offset:6336
	ds_write_b32 v4, v113 offset:6600
	ds_write_b32 v4, v114 offset:6864
	ds_write_b32 v4, v115 offset:7128
	ds_write_b32 v4, v116 offset:7392
	ds_write_b32 v4, v117 offset:7656
	ds_write_b32 v4, v118 offset:7920
	ds_write_b32 v4, v119 offset:8184
	s_waitcnt lgkmcnt(0)
	ds_read_b32 v48, v7
	ds_read_b32 v49, v7 offset:132
	ds_read_b32 v50, v7 offset:264
	ds_read_b32 v51, v7 offset:396
	ds_read_b32 v52, v7 offset:528
	ds_read_b32 v53, v7 offset:660
	ds_read_b32 v54, v7 offset:792
	ds_read_b32 v55, v7 offset:924
	ds_read_b32 v56, v7 offset:32
	ds_read_b32 v57, v7 offset:164
	ds_read_b32 v58, v7 offset:296
	ds_read_b32 v59, v7 offset:428
	ds_read_b32 v60, v7 offset:560
	ds_read_b32 v61, v7 offset:692
	ds_read_b32 v62, v7 offset:824
	ds_read_b32 v63, v7 offset:956
	ds_read_b32 v64, v7 offset:64
	ds_read_b32 v65, v7 offset:196
	ds_read_b32 v66, v7 offset:328
	ds_read_b32 v67, v7 offset:460
	ds_read_b32 v68, v7 offset:592
	ds_read_b32 v69, v7 offset:724
	ds_read_b32 v70, v7 offset:856
	ds_read_b32 v71, v7 offset:988
	ds_read_b32 v72, v7 offset:96
	ds_read_b32 v73, v7 offset:228
	ds_read_b32 v74, v7 offset:360
	ds_read_b32 v75, v7 offset:492
	ds_read_b32 v76, v7 offset:624
	ds_read_b32 v77, v7 offset:756
	ds_read_b32 v78, v7 offset:888
	ds_read_b32 v79, v7 offset:1020
	s_waitcnt lgkmcnt(0)
	v_cvt_pk_bf16_f32 v48, v48, v49
	v_cvt_pk_bf16_f32 v49, v50, v51
	v_cvt_pk_bf16_f32 v50, v52, v53
	v_cvt_pk_bf16_f32 v51, v54, v55
	global_store_dwordx4 v8, v[48:51], s[24:25]
	v_cvt_pk_bf16_f32 v56, v56, v57
	v_cvt_pk_bf16_f32 v57, v58, v59
	v_cvt_pk_bf16_f32 v58, v60, v61
	v_cvt_pk_bf16_f32 v59, v62, v63
	global_store_dwordx4 v9, v[56:59], s[24:25]
	v_cvt_pk_bf16_f32 v64, v64, v65
	v_cvt_pk_bf16_f32 v65, v66, v67
	v_cvt_pk_bf16_f32 v66, v68, v69
	v_cvt_pk_bf16_f32 v67, v70, v71
	global_store_dwordx4 v8, v[64:67], s[24:25] offset:2048
	v_cvt_pk_bf16_f32 v72, v72, v73
	v_cvt_pk_bf16_f32 v73, v74, v75
	v_cvt_pk_bf16_f32 v74, v76, v77
	v_cvt_pk_bf16_f32 v75, v78, v79
	global_store_dwordx4 v9, v[72:75], s[24:25] offset:2048
; #define LAS __attribute__((address_space(3)))
; __device__ __forceinline__ unsigned pk2(float lo, float hi) { f32x2 f = {lo, hi}; bf16x2_t b = __builtin_convertvector(f, bf16x2_t); return __builtin_bit_cast(unsigned, b); }
; __device__ __forceinline__ void tr_load(const float* W, int N, int item, int lane, float (&wv)[32]) {
;     const int nblk = N / 32, kb = item / nblk, nb = item % nblk, k0 = 64 * kb, n0 = 32 * nb;
; #pragma unroll
;     for (int i = 0; i < 32; ++i) { const int kk = 2 * i + (lane >> 5); wv[i] = __builtin_nontemporal_load(W + (size_t)(k0 + kk) * N + n0 + (lane & 31)); }
; }
; template <int MAP, bool HASG, bool PERMW>
; __device__ __forceinline__ void tr_store(int K, int N, bf16_t* WT, LAS float* scr, int item, int lane, const float* gk) {
;     const int nblk = N / 32, kb = item / nblk, nb = item % nblk, k0 = 64 * kb, n0 = 32 * nb;
;     asm volatile("s_waitcnt lgkmcnt(0)" ::: "memory");
;     const int c = lane & 7;
;     f32x4 g0 = {1.f, 1.f, 1.f, 1.f}, g1 = {1.f, 1.f, 1.f, 1.f};
;     if (HASG) { g0 = *(const f32x4*)(gk + k0 + 8 * c); g1 = *(const f32x4*)(gk + k0 + 8 * c + 4); }
; #pragma unroll
;     for (int j = 0; j < 4; ++j) { const int n = (lane >> 3) + 8 * j; const LAS float* s = scr + (8 * c) * 33 + n;
;         u32x4 o; o.x = pk2(s[0 * 33] * g0[0], s[1 * 33] * g0[1]); o.y = pk2(s[2 * 33] * g0[2], s[3 * 33] * g0[3]); o.z = pk2(s[4 * 33] * g1[0], s[5 * 33] * g1[1]); o.w = pk2(s[6 * 33] * g1[2], s[7 * 33] * g1[3]);
;         const int wr_ = rowmap<MAP>(n0 + n), slot_ = PERMW ? ((wr_ & ~31) + invperm32(wr_ & 31)) : wr_;
;         *(u32x4*)((char*)WT + tiled_off(slot_, k0 + 8 * c, K / 64)) = o; }
; __global__ void __launch_bounds__(512, 2) mega_fwd(Params p) {
;     ...
;             transpose_mat<1, true, true>(p.in[11] + (size_t)l * D * DFF, D, DFF, P_W(WS_WGU2), scr, gw, ngw, lane, p.in[10] + l * D);
.Ltc1a_exit:
	v_readlane_b32 s4, v254, 6
	v_readlane_b32 s5, v254, 7
	v_readlane_b32 s20, v254, 4
	v_readlane_b32 s21, v254, 5
	s_nop 3
	s_and_b32 s6, s60, 0x2c00000
	s_add_u32 s4, s4, s6
	s_addc_u32 s5, s5, 0
	s_and_b32 s6, s60, 0x2000
	s_add_u32 s20, s20, s6
	s_addc_u32 s21, s21, 0
	s_add_u32 s6, s76, 0x8a00000
	s_addc_u32 s7, s77, 0
	s_mov_b32 s9, s18
	s_cmpk_ge_u32 s9, 0x1600
	s_cbranch_scc1 .Ltc1b_exit
	s_mul_hi_u32 s11, s9, 0x2e8ba2e9
	s_lshr_b32 s11, s11, 5
	s_mul_i32 s12, s11, 0xb0
	s_sub_u32 s12, s9, s12
	s_mul_i32 s13, s11, 0x160000
	s_lshl_b32 s14, s12, 7
	s_add_u32 s13, s13, s14
	s_add_u32 s14, s4, s13
	s_addc_u32 s15, s5, 0
	global_load_dword v16, v15, s[14:15] nt
	s_add_u32 s14, s14, 0xb000
	s_addc_u32 s15, s15, 0
	global_load_dword v17, v15, s[14:15] nt
	s_add_u32 s14, s14, 0xb000
	s_addc_u32 s15, s15, 0
	global_load_dword v18, v15, s[14:15] nt
	s_add_u32 s14, s14, 0xb000
	s_addc_u32 s15, s15, 0
	global_load_dword v19, v15, s[14:15] nt
	s_add_u32 s14, s14, 0xb000
	s_addc_u32 s15, s15, 0
	global_load_dword v20, v15, s[14:15] nt
	s_add_u32 s14, s14, 0xb000
	s_addc_u32 s15, s15, 0
	global_load_dword v21, v15, s[14:15] nt
	s_add_u32 s14, s14, 0xb000
	s_addc_u32 s15, s15, 0
	global_load_dword v22, v15, s[14:15] nt
	s_add_u32 s14, s14, 0xb000
	s_addc_u32 s15, s15, 0
	global_load_dword v23, v15, s[14:15] nt
	s_add_u32 s14, s14, 0xb000
	s_addc_u32 s15, s15, 0
	global_load_dword v24, v15, s[14:15] nt
	s_add_u32 s14, s14, 0xb000
	s_addc_u32 s15, s15, 0
	global_load_dword v25, v15, s[14:15] nt
	s_add_u32 s14, s14, 0xb000
	s_addc_u32 s15, s15, 0
	global_load_dword v26, v15, s[14:15] nt
	s_add_u32 s14, s14, 0xb000
	s_addc_u32 s15, s15, 0
	global_load_dword v27, v15, s[14:15] nt
	s_add_u32 s14, s14, 0xb000
	s_addc_u32 s15, s15, 0
	global_load_dword v28, v15, s[14:15] nt
	s_add_u32 s14, s14, 0xb000
	s_addc_u32 s15, s15, 0
	global_load_dword v29, v15, s[14:15] nt
	s_add_u32 s14, s14, 0xb000
	s_addc_u32 s15, s15, 0
	global_load_dword v30, v15, s[14:15] nt
	s_add_u32 s14, s14, 0xb000
	s_addc_u32 s15, s15, 0
	global_load_dword v31, v15, s[14:15] nt
	s_add_u32 s14, s14, 0xb000
	s_addc_u32 s15, s15, 0
	global_load_dword v32, v15, s[14:15] nt
	s_add_u32 s14, s14, 0xb000
	s_addc_u32 s15, s15, 0
	global_load_dword v33, v15, s[14:15] nt
	s_add_u32 s14, s14, 0xb000
	s_addc_u32 s15, s15, 0
	global_load_dword v34, v15, s[14:15] nt
	s_add_u32 s14, s14, 0xb000
	s_addc_u32 s15, s15, 0
	global_load_dword v35, v15, s[14:15] nt
	s_add_u32 s14, s14, 0xb000
	s_addc_u32 s15, s15, 0
	global_load_dword v36, v15, s[14:15] nt
	s_add_u32 s14, s14, 0xb000
	s_addc_u32 s15, s15, 0
	global_load_dword v37, v15, s[14:15] nt
	s_add_u32 s14, s14, 0xb000
	s_addc_u32 s15, s15, 0
	global_load_dword v38, v15, s[14:15] nt
	s_add_u32 s14, s14, 0xb000
	s_addc_u32 s15, s15, 0
	global_load_dword v39, v15, s[14:15] nt
	s_add_u32 s14, s14, 0xb000
	s_addc_u32 s15, s15, 0
	global_load_dword v40, v15, s[14:15] nt
	s_add_u32 s14, s14, 0xb000
	s_addc_u32 s15, s15, 0
	global_load_dword v41, v15, s[14:15] nt
	s_add_u32 s14, s14, 0xb000
	s_addc_u32 s15, s15, 0
	global_load_dword v42, v15, s[14:15] nt
	s_add_u32 s14, s14, 0xb000
	s_addc_u32 s15, s15, 0
	global_load_dword v43, v15, s[14:15] nt
	s_add_u32 s14, s14, 0xb000
	s_addc_u32 s15, s15, 0
	global_load_dword v44, v15, s[14:15] nt
	s_add_u32 s14, s14, 0xb000
	s_addc_u32 s15, s15, 0
	global_load_dword v45, v15, s[14:15] nt
	s_add_u32 s14, s14, 0xb000
	s_addc_u32 s15, s15, 0
	global_load_dword v46, v15, s[14:15] nt
	s_add_u32 s14, s14, 0xb000
	s_addc_u32 s15, s15, 0
	global_load_dword v47, v15, s[14:15] nt
	s_lshl_b32 s14, s11, 8
	s_add_u32 s14, s20, s14
	s_addc_u32 s15, s21, 0
	global_load_dwordx4 v[80:83], v14, s[14:15]
	global_load_dwordx4 v[84:87], v14, s[14:15] offset:16
	s_lshr_b32 s16, s12, 2
	s_lshl_b32 s16, s16, 1
	s_lshl_b32 s16, s16, 5
	s_add_u32 s16, s16, s11
	s_lshl_b32 s16, s16, 14
	s_and_b32 s17, s12, 3
	s_lshl_b32 s17, s17, 12
	s_add_u32 s16, s16, s17
	s_add_u32 s16, s6, s16
	s_addc_u32 s17, s7, 0
.Ltc1b_loop:
	s_add_u32 s9, s9, 0x400
	s_cmpk_ge_u32 s9, 0x1600
	s_cbranch_scc1 .Ltc1b_lastA
	s_mul_hi_u32 s11, s9, 0x2e8ba2e9
	s_lshr_b32 s11, s11, 5
	s_mul_i32 s12, s11, 0xb0
	s_sub_u32 s12, s9, s12
	s_mul_i32 s13, s11, 0x160000
	s_lshl_b32 s14, s12, 7
	s_add_u32 s13, s13, s14
	s_add_u32 s14, s4, s13
	s_addc_u32 s15, s5, 0
	global_load_dword v88, v15, s[14:15] nt
	s_add_u32 s14, s14, 0xb000
	s_addc_u32 s15, s15, 0
	global_load_dword v89, v15, s[14:15] nt
	s_add_u32 s14, s14, 0xb000
	s_addc_u32 s15, s15, 0
	global_load_dword v90, v15, s[14:15] nt
	s_add_u32 s14, s14, 0xb000
	s_addc_u32 s15, s15, 0
	global_load_dword v91, v15, s[14:15] nt
	s_add_u32 s14, s14, 0xb000
	s_addc_u32 s15, s15, 0
	global_load_dword v92, v15, s[14:15] nt
	s_add_u32 s14, s14, 0xb000
	s_addc_u32 s15, s15, 0
	global_load_dword v93, v15, s[14:15] nt
	s_add_u32 s14, s14, 0xb000
	s_addc_u32 s15, s15, 0
	global_load_dword v94, v15, s[14:15] nt
	s_add_u32 s14, s14, 0xb000
	s_addc_u32 s15, s15, 0
	global_load_dword v95, v15, s[14:15] nt
	s_add_u32 s14, s14, 0xb000
	s_addc_u32 s15, s15, 0
	global_load_dword v96, v15, s[14:15] nt
	s_add_u32 s14, s14, 0xb000
	s_addc_u32 s15, s15, 0
	global_load_dword v97, v15, s[14:15] nt
	s_add_u32 s14, s14, 0xb000
	s_addc_u32 s15, s15, 0
	global_load_dword v98, v15, s[14:15] nt
	s_add_u32 s14, s14, 0xb000
	s_addc_u32 s15, s15, 0
	global_load_dword v99, v15, s[14:15] nt
	s_add_u32 s14, s14, 0xb000
	s_addc_u32 s15, s15, 0
	global_load_dword v100, v15, s[14:15] nt
	s_add_u32 s14, s14, 0xb000
	s_addc_u32 s15, s15, 0
	global_load_dword v101, v15, s[14:15] nt
	s_add_u32 s14, s14, 0xb000
	s_addc_u32 s15, s15, 0
	global_load_dword v102, v15, s[14:15] nt
; __device__ __forceinline__ void tr_load(const float* W, int N, int item, int lane, float (&wv)[32]) {
;     const int nblk = N / 32, kb = item / nblk, nb = item % nblk, k0 = 64 * kb, n0 = 32 * nb;
; #pragma unroll
;     for (int i = 0; i < 32; ++i) { const int kk = 2 * i + (lane >> 5); wv[i] = __builtin_nontemporal_load(W + (size_t)(k0 + kk) * N + n0 + (lane & 31)); }
; }
; template <int MAP, bool HASG, bool PERMW>
; __device__ __forceinline__ void tr_store(int K, int N, bf16_t* WT, LAS float* scr, int item, int lane, const float* gk) {
;     const int nblk = N / 32, kb = item / nblk, nb = item % nblk, k0 = 64 * kb, n0 = 32 * nb;
;     asm volatile("s_waitcnt lgkmcnt(0)" ::: "memory");
;     const int c = lane & 7;
;     f32x4 g0 = {1.f, 1.f, 1.f, 1.f}, g1 = {1.f, 1.f, 1.f, 1.f};
;     if (HASG) { g0 = *(const f32x4*)(gk + k0 + 8 * c); g1 = *(const f32x4*)(gk + k0 + 8 * c + 4); }
; #pragma unroll
;     for (int j = 0; j < 4; ++j) { const int n = (lane >> 3) + 8 * j; const LAS float* s = scr + (8 * c) * 33 + n;
;         u32x4 o; o.x = pk2(s[0 * 33] * g0[0], s[1 * 33] * g0[1]); o.y = pk2(s[2 * 33] * g0[2], s[3 * 33] * g0[3]); o.z = pk2(s[4 * 33] * g1[0], s[5 * 33] * g1[1]); o.w = pk2(s[6 * 33] * g1[2], s[7 * 33] * g1[3]);
;         const int wr_ = rowmap<MAP>(n0 + n), slot_ = PERMW ? ((wr_ & ~31) + invperm32(wr_ & 31)) : wr_;
;         *(u32x4*)((char*)WT + tiled_off(slot_, k0 + 8 * c, K / 64)) = o; }
;     asm volatile("s_waitcnt lgkmcnt(0)" ::: "memory");
; }
; template <int MAP, bool HASG = false, bool PERMW = false>
; __device__ __forceinline__ void transpose_mat(const float* W, int K, int N, bf16_t* WT, LAS float* scr, int gw, int ngw, int lane, const float* gk = nullptr) {
;     const int nitems = (K / 64) * (N / 32);
;     int it = gw;
;     if (it >= nitems) return;
;     float wv[32];
;     tr_load(W, N, it, lane, wv);
;     for (;;) {
;         __builtin_amdgcn_sched_barrier(0);
; #pragma unroll
;         for (int i = 0; i < 32; ++i) { const int kk = 2 * i + (lane >> 5); scr[kk * 33 + (lane & 31)] = wv[i]; }
;         __builtin_amdgcn_sched_barrier(0);
;         const int nx = it + ngw;
;         if (nx < nitems) tr_load(W, N, nx, lane, wv);
;         __builtin_amdgcn_sched_barrier(0);
;         tr_store<MAP, HASG, PERMW>(K, N, WT, scr, it, lane, gk);
;         if (nx >= nitems) break;
;         it = nx;
	s_add_u32 s14, s14, 0xb000
	s_addc_u32 s15, s15, 0
	global_load_dword v103, v15, s[14:15] nt
	s_add_u32 s14, s14, 0xb000
	s_addc_u32 s15, s15, 0
	global_load_dword v104, v15, s[14:15] nt
	s_add_u32 s14, s14, 0xb000
	s_addc_u32 s15, s15, 0
	global_load_dword v105, v15, s[14:15] nt
	s_add_u32 s14, s14, 0xb000
	s_addc_u32 s15, s15, 0
	global_load_dword v106, v15, s[14:15] nt
	s_add_u32 s14, s14, 0xb000
	s_addc_u32 s15, s15, 0
	global_load_dword v107, v15, s[14:15] nt
	s_add_u32 s14, s14, 0xb000
	s_addc_u32 s15, s15, 0
	global_load_dword v108, v15, s[14:15] nt
	s_add_u32 s14, s14, 0xb000
	s_addc_u32 s15, s15, 0
	global_load_dword v109, v15, s[14:15] nt
	s_add_u32 s14, s14, 0xb000
	s_addc_u32 s15, s15, 0
	global_load_dword v110, v15, s[14:15] nt
	s_add_u32 s14, s14, 0xb000
	s_addc_u32 s15, s15, 0
	global_load_dword v111, v15, s[14:15] nt
	s_add_u32 s14, s14, 0xb000
	s_addc_u32 s15, s15, 0
	global_load_dword v112, v15, s[14:15] nt
	s_add_u32 s14, s14, 0xb000
	s_addc_u32 s15, s15, 0
	global_load_dword v113, v15, s[14:15] nt
	s_add_u32 s14, s14, 0xb000
	s_addc_u32 s15, s15, 0
	global_load_dword v114, v15, s[14:15] nt
	s_add_u32 s14, s14, 0xb000
	s_addc_u32 s15, s15, 0
	global_load_dword v115, v15, s[14:15] nt
	s_add_u32 s14, s14, 0xb000
	s_addc_u32 s15, s15, 0
	global_load_dword v116, v15, s[14:15] nt
	s_add_u32 s14, s14, 0xb000
	s_addc_u32 s15, s15, 0
	global_load_dword v117, v15, s[14:15] nt
	s_add_u32 s14, s14, 0xb000
	s_addc_u32 s15, s15, 0
	global_load_dword v118, v15, s[14:15] nt
	s_add_u32 s14, s14, 0xb000
	s_addc_u32 s15, s15, 0
	global_load_dword v119, v15, s[14:15] nt
	s_lshl_b32 s14, s11, 8
	s_add_u32 s14, s20, s14
	s_addc_u32 s15, s21, 0
	global_load_dwordx4 v[120:123], v14, s[14:15]
	global_load_dwordx4 v[124:127], v14, s[14:15] offset:16
	s_lshr_b32 s24, s12, 2
	s_lshl_b32 s24, s24, 1
	s_lshl_b32 s24, s24, 5
	s_add_u32 s24, s24, s11
	s_lshl_b32 s24, s24, 14
	s_and_b32 s25, s12, 3
	s_lshl_b32 s25, s25, 12
	s_add_u32 s24, s24, s25
	s_add_u32 s24, s6, s24
	s_addc_u32 s25, s7, 0
	s_waitcnt vmcnt(34)
	ds_write_b32 v4, v16
	ds_write_b32 v4, v17 offset:264
	ds_write_b32 v4, v18 offset:528
	ds_write_b32 v4, v19 offset:792
	ds_write_b32 v4, v20 offset:1056
	ds_write_b32 v4, v21 offset:1320
	ds_write_b32 v4, v22 offset:1584
	ds_write_b32 v4, v23 offset:1848
	ds_write_b32 v4, v24 offset:2112
	ds_write_b32 v4, v25 offset:2376
	ds_write_b32 v4, v26 offset:2640
	ds_write_b32 v4, v27 offset:2904
	ds_write_b32 v4, v28 offset:3168
	ds_write_b32 v4, v29 offset:3432
	ds_write_b32 v4, v30 offset:3696
	ds_write_b32 v4, v31 offset:3960
	ds_write_b32 v4, v32 offset:4224
	ds_write_b32 v4, v33 offset:4488
	ds_write_b32 v4, v34 offset:4752
	ds_write_b32 v4, v35 offset:5016
	ds_write_b32 v4, v36 offset:5280
	ds_write_b32 v4, v37 offset:5544
	ds_write_b32 v4, v38 offset:5808
	ds_write_b32 v4, v39 offset:6072
	ds_write_b32 v4, v40 offset:6336
	ds_write_b32 v4, v41 offset:6600
	ds_write_b32 v4, v42 offset:6864
	ds_write_b32 v4, v43 offset:7128
	ds_write_b32 v4, v44 offset:7392
	ds_write_b32 v4, v45 offset:7656
	ds_write_b32 v4, v46 offset:7920
	ds_write_b32 v4, v47 offset:8184
	s_waitcnt lgkmcnt(0)
	ds_read_b32 v48, v7
	ds_read_b32 v49, v7 offset:132
	ds_read_b32 v50, v7 offset:264
	ds_read_b32 v51, v7 offset:396
	ds_read_b32 v52, v7 offset:528
	ds_read_b32 v53, v7 offset:660
	ds_read_b32 v54, v7 offset:792
	ds_read_b32 v55, v7 offset:924
	ds_read_b32 v56, v7 offset:32
	ds_read_b32 v57, v7 offset:164
	ds_read_b32 v58, v7 offset:296
	ds_read_b32 v59, v7 offset:428
	ds_read_b32 v60, v7 offset:560
	ds_read_b32 v61, v7 offset:692
	ds_read_b32 v62, v7 offset:824
	ds_read_b32 v63, v7 offset:956
	ds_read_b32 v64, v7 offset:64
	ds_read_b32 v65, v7 offset:196
	ds_read_b32 v66, v7 offset:328
	ds_read_b32 v67, v7 offset:460
	ds_read_b32 v68, v7 offset:592
	ds_read_b32 v69, v7 offset:724
	ds_read_b32 v70, v7 offset:856
	ds_read_b32 v71, v7 offset:988
	ds_read_b32 v72, v7 offset:96
	ds_read_b32 v73, v7 offset:228
	ds_read_b32 v74, v7 offset:360
	ds_read_b32 v75, v7 offset:492
	ds_read_b32 v76, v7 offset:624
	ds_read_b32 v77, v7 offset:756
	ds_read_b32 v78, v7 offset:888
	ds_read_b32 v79, v7 offset:1020
	s_waitcnt lgkmcnt(0)
	v_mul_f32_e32 v48, v48, v80
	v_mul_f32_e32 v49, v49, v81
	v_mul_f32_e32 v50, v50, v82
	v_mul_f32_e32 v51, v51, v83
	v_mul_f32_e32 v52, v52, v84
	v_mul_f32_e32 v53, v53, v85
	v_mul_f32_e32 v54, v54, v86
	v_mul_f32_e32 v55, v55, v87
	v_cvt_pk_bf16_f32 v48, v48, v49
	v_cvt_pk_bf16_f32 v49, v50, v51
	v_cvt_pk_bf16_f32 v50, v52, v53
	v_cvt_pk_bf16_f32 v51, v54, v55
	global_store_dwordx4 v10, v[48:51], s[16:17]
	v_mul_f32_e32 v56, v56, v80
	v_mul_f32_e32 v57, v57, v81
	v_mul_f32_e32 v58, v58, v82
	v_mul_f32_e32 v59, v59, v83
	v_mul_f32_e32 v60, v60, v84
	v_mul_f32_e32 v61, v61, v85
	v_mul_f32_e32 v62, v62, v86
	v_mul_f32_e32 v63, v63, v87
	v_cvt_pk_bf16_f32 v56, v56, v57
	v_cvt_pk_bf16_f32 v57, v58, v59
	v_cvt_pk_bf16_f32 v58, v60, v61
	v_cvt_pk_bf16_f32 v59, v62, v63
	global_store_dwordx4 v10, v[56:59], s[16:17] offset:256
	v_mul_f32_e32 v64, v64, v80
	v_mul_f32_e32 v65, v65, v81
	v_mul_f32_e32 v66, v66, v82
	v_mul_f32_e32 v67, v67, v83
	v_mul_f32_e32 v68, v68, v84
	v_mul_f32_e32 v69, v69, v85
	v_mul_f32_e32 v70, v70, v86
	v_mul_f32_e32 v71, v71, v87
	v_cvt_pk_bf16_f32 v64, v64, v65
	v_cvt_pk_bf16_f32 v65, v66, v67
	v_cvt_pk_bf16_f32 v66, v68, v69
	v_cvt_pk_bf16_f32 v67, v70, v71
	global_store_dwordx4 v11, v[64:67], s[16:17] offset:512
	v_mul_f32_e32 v72, v72, v80
	v_mul_f32_e32 v73, v73, v81
	v_mul_f32_e32 v74, v74, v82
	v_mul_f32_e32 v75, v75, v83
	v_mul_f32_e32 v76, v76, v84
	v_mul_f32_e32 v77, v77, v85
	v_mul_f32_e32 v78, v78, v86
	v_mul_f32_e32 v79, v79, v87
	v_cvt_pk_bf16_f32 v72, v72, v73
	v_cvt_pk_bf16_f32 v73, v74, v75
	v_cvt_pk_bf16_f32 v74, v76, v77
	v_cvt_pk_bf16_f32 v75, v78, v79
	global_store_dwordx4 v11, v[72:75], s[16:17] offset:768
	s_add_u32 s9, s9, 0x400
	s_cmpk_ge_u32 s9, 0x1600
	s_cbranch_scc1 .Ltc1b_lastB
; __device__ __forceinline__ void tr_load(const float* W, int N, int item, int lane, float (&wv)[32]) {
;     const int nblk = N / 32, kb = item / nblk, nb = item % nblk, k0 = 64 * kb, n0 = 32 * nb;
; #pragma unroll
;     for (int i = 0; i < 32; ++i) { const int kk = 2 * i + (lane >> 5); wv[i] = __builtin_nontemporal_load(W + (size_t)(k0 + kk) * N + n0 + (lane & 31)); }
; }
; template <int MAP, bool HASG, bool PERMW>
; __device__ __forceinline__ void tr_store(int K, int N, bf16_t* WT, LAS float* scr, int item, int lane, const float* gk) {
;     const int nblk = N / 32, kb = item / nblk, nb = item % nblk, k0 = 64 * kb, n0 = 32 * nb;
;     asm volatile("s_waitcnt lgkmcnt(0)" ::: "memory");
;     const int c = lane & 7;
;     f32x4 g0 = {1.f, 1.f, 1.f, 1.f}, g1 = {1.f, 1.f, 1.f, 1.f};
;     if (HASG) { g0 = *(const f32x4*)(gk + k0 + 8 * c); g1 = *(const f32x4*)(gk + k0 + 8 * c + 4); }
; #pragma unroll
;     for (int j = 0; j < 4; ++j) { const int n = (lane >> 3) + 8 * j; const LAS float* s = scr + (8 * c) * 33 + n;
;         u32x4 o; o.x = pk2(s[0 * 33] * g0[0], s[1 * 33] * g0[1]); o.y = pk2(s[2 * 33] * g0[2], s[3 * 33] * g0[3]); o.z = pk2(s[4 * 33] * g1[0], s[5 * 33] * g1[1]); o.w = pk2(s[6 * 33] * g1[2], s[7 * 33] * g1[3]);
;         const int wr_ = rowmap<MAP>(n0 + n), slot_ = PERMW ? ((wr_ & ~31) + invperm32(wr_ & 31)) : wr_;
;         *(u32x4*)((char*)WT + tiled_off(slot_, k0 + 8 * c, K / 64)) = o; }
;     asm volatile("s_waitcnt lgkmcnt(0)" ::: "memory");
; }
; template <int MAP, bool HASG = false, bool PERMW = false>
; __device__ __forceinline__ void transpose_mat(const float* W, int K, int N, bf16_t* WT, LAS float* scr, int gw, int ngw, int lane, const float* gk = nullptr) {
;     const int nitems = (K / 64) * (N / 32);
;     int it = gw;
;     if (it >= nitems) return;
;     float wv[32];
;     tr_load(W, N, it, lane, wv);
;     for (;;) {
;         __builtin_amdgcn_sched_barrier(0);
; #pragma unroll
;         for (int i = 0; i < 32; ++i) { const int kk = 2 * i + (lane >> 5); scr[kk * 33 + (lane & 31)] = wv[i]; }
;         __builtin_amdgcn_sched_barrier(0);
;         const int nx = it + ngw;
;         if (nx < nitems) tr_load(W, N, nx, lane, wv);
;         __builtin_amdgcn_sched_barrier(0);
;         tr_store<MAP, HASG, PERMW>(K, N, WT, scr, it, lane, gk);
;         if (nx >= nitems) break;
;         it = nx;
	s_mul_hi_u32 s11, s9, 0x2e8ba2e9
	s_lshr_b32 s11, s11, 5
	s_mul_i32 s12, s11, 0xb0
	s_sub_u32 s12, s9, s12
	s_mul_i32 s13, s11, 0x160000
	s_lshl_b32 s14, s12, 7
	s_add_u32 s13, s13, s14
	s_add_u32 s14, s4, s13
	s_addc_u32 s15, s5, 0
	global_load_dword v16, v15, s[14:15] nt
	s_add_u32 s14, s14, 0xb000
	s_addc_u32 s15, s15, 0
	global_load_dword v17, v15, s[14:15] nt
	s_add_u32 s14, s14, 0xb000
	s_addc_u32 s15, s15, 0
	global_load_dword v18, v15, s[14:15] nt
	s_add_u32 s14, s14, 0xb000
	s_addc_u32 s15, s15, 0
	global_load_dword v19, v15, s[14:15] nt
	s_add_u32 s14, s14, 0xb000
	s_addc_u32 s15, s15, 0
	global_load_dword v20, v15, s[14:15] nt
	s_add_u32 s14, s14, 0xb000
	s_addc_u32 s15, s15, 0
	global_load_dword v21, v15, s[14:15] nt
	s_add_u32 s14, s14, 0xb000
	s_addc_u32 s15, s15, 0
	global_load_dword v22, v15, s[14:15] nt
	s_add_u32 s14, s14, 0xb000
	s_addc_u32 s15, s15, 0
	global_load_dword v23, v15, s[14:15] nt
	s_add_u32 s14, s14, 0xb000
	s_addc_u32 s15, s15, 0
	global_load_dword v24, v15, s[14:15] nt
	s_add_u32 s14, s14, 0xb000
	s_addc_u32 s15, s15, 0
	global_load_dword v25, v15, s[14:15] nt
	s_add_u32 s14, s14, 0xb000
	s_addc_u32 s15, s15, 0
	global_load_dword v26, v15, s[14:15] nt
	s_add_u32 s14, s14, 0xb000
	s_addc_u32 s15, s15, 0
	global_load_dword v27, v15, s[14:15] nt
	s_add_u32 s14, s14, 0xb000
	s_addc_u32 s15, s15, 0
	global_load_dword v28, v15, s[14:15] nt
	s_add_u32 s14, s14, 0xb000
	s_addc_u32 s15, s15, 0
	global_load_dword v29, v15, s[14:15] nt
	s_add_u32 s14, s14, 0xb000
	s_addc_u32 s15, s15, 0
	global_load_dword v30, v15, s[14:15] nt
	s_add_u32 s14, s14, 0xb000
	s_addc_u32 s15, s15, 0
	global_load_dword v31, v15, s[14:15] nt
	s_add_u32 s14, s14, 0xb000
	s_addc_u32 s15, s15, 0
	global_load_dword v32, v15, s[14:15] nt
	s_add_u32 s14, s14, 0xb000
	s_addc_u32 s15, s15, 0
	global_load_dword v33, v15, s[14:15] nt
	s_add_u32 s14, s14, 0xb000
	s_addc_u32 s15, s15, 0
	global_load_dword v34, v15, s[14:15] nt
	s_add_u32 s14, s14, 0xb000
	s_addc_u32 s15, s15, 0
	global_load_dword v35, v15, s[14:15] nt
	s_add_u32 s14, s14, 0xb000
	s_addc_u32 s15, s15, 0
	global_load_dword v36, v15, s[14:15] nt
	s_add_u32 s14, s14, 0xb000
	s_addc_u32 s15, s15, 0
	global_load_dword v37, v15, s[14:15] nt
	s_add_u32 s14, s14, 0xb000
	s_addc_u32 s15, s15, 0
	global_load_dword v38, v15, s[14:15] nt
	s_add_u32 s14, s14, 0xb000
	s_addc_u32 s15, s15, 0
	global_load_dword v39, v15, s[14:15] nt
	s_add_u32 s14, s14, 0xb000
	s_addc_u32 s15, s15, 0
	global_load_dword v40, v15, s[14:15] nt
	s_add_u32 s14, s14, 0xb000
	s_addc_u32 s15, s15, 0
	global_load_dword v41, v15, s[14:15] nt
	s_add_u32 s14, s14, 0xb000
	s_addc_u32 s15, s15, 0
	global_load_dword v42, v15, s[14:15] nt
	s_add_u32 s14, s14, 0xb000
	s_addc_u32 s15, s15, 0
	global_load_dword v43, v15, s[14:15] nt
	s_add_u32 s14, s14, 0xb000
	s_addc_u32 s15, s15, 0
	global_load_dword v44, v15, s[14:15] nt
	s_add_u32 s14, s14, 0xb000
	s_addc_u32 s15, s15, 0
	global_load_dword v45, v15, s[14:15] nt
	s_add_u32 s14, s14, 0xb000
	s_addc_u32 s15, s15, 0
	global_load_dword v46, v15, s[14:15] nt
	s_add_u32 s14, s14, 0xb000
	s_addc_u32 s15, s15, 0
	global_load_dword v47, v15, s[14:15] nt
	s_lshl_b32 s14, s11, 8
	s_add_u32 s14, s20, s14
	s_addc_u32 s15, s21, 0
	global_load_dwordx4 v[80:83], v14, s[14:15]
	global_load_dwordx4 v[84:87], v14, s[14:15] offset:16
	s_lshr_b32 s16, s12, 2
	s_lshl_b32 s16, s16, 1
	s_lshl_b32 s16, s16, 5
	s_add_u32 s16, s16, s11
	s_lshl_b32 s16, s16, 14
	s_and_b32 s17, s12, 3
	s_lshl_b32 s17, s17, 12
	s_add_u32 s16, s16, s17
	s_add_u32 s16, s6, s16
	s_addc_u32 s17, s7, 0
	s_waitcnt vmcnt(34)
	ds_write_b32 v4, v88
	ds_write_b32 v4, v89 offset:264
	ds_write_b32 v4, v90 offset:528
	ds_write_b32 v4, v91 offset:792
	ds_write_b32 v4, v92 offset:1056
	ds_write_b32 v4, v93 offset:1320
	ds_write_b32 v4, v94 offset:1584
	ds_write_b32 v4, v95 offset:1848
	ds_write_b32 v4, v96 offset:2112
	ds_write_b32 v4, v97 offset:2376
	ds_write_b32 v4, v98 offset:2640
	ds_write_b32 v4, v99 offset:2904
	ds_write_b32 v4, v100 offset:3168
	ds_write_b32 v4, v101 offset:3432
	ds_write_b32 v4, v102 offset:3696
	ds_write_b32 v4, v103 offset:3960
	ds_write_b32 v4, v104 offset:4224
	ds_write_b32 v4, v105 offset:4488
	ds_write_b32 v4, v106 offset:4752
	ds_write_b32 v4, v107 offset:5016
	ds_write_b32 v4, v108 offset:5280
	ds_write_b32 v4, v109 offset:5544
	ds_write_b32 v4, v110 offset:5808
	ds_write_b32 v4, v111 offset:6072
	ds_write_b32 v4, v112 offset:6336
	ds_write_b32 v4, v113 offset:6600
	ds_write_b32 v4, v114 offset:6864
	ds_write_b32 v4, v115 offset:7128
	ds_write_b32 v4, v116 offset:7392
	ds_write_b32 v4, v117 offset:7656
	ds_write_b32 v4, v118 offset:7920
	ds_write_b32 v4, v119 offset:8184
	s_waitcnt lgkmcnt(0)
	ds_read_b32 v48, v7
	ds_read_b32 v49, v7 offset:132
	ds_read_b32 v50, v7 offset:264
	ds_read_b32 v51, v7 offset:396
	ds_read_b32 v52, v7 offset:528
	ds_read_b32 v53, v7 offset:660
	ds_read_b32 v54, v7 offset:792
	ds_read_b32 v55, v7 offset:924
	ds_read_b32 v56, v7 offset:32
	ds_read_b32 v57, v7 offset:164
	ds_read_b32 v58, v7 offset:296
	ds_read_b32 v59, v7 offset:428
	ds_read_b32 v60, v7 offset:560
	ds_read_b32 v61, v7 offset:692
	ds_read_b32 v62, v7 offset:824
	ds_read_b32 v63, v7 offset:956
	ds_read_b32 v64, v7 offset:64
	ds_read_b32 v65, v7 offset:196
	ds_read_b32 v66, v7 offset:328
	ds_read_b32 v67, v7 offset:460
	ds_read_b32 v68, v7 offset:592
	ds_read_b32 v69, v7 offset:724
	ds_read_b32 v70, v7 offset:856
	ds_read_b32 v71, v7 offset:988
	ds_read_b32 v72, v7 offset:96
	ds_read_b32 v73, v7 offset:228
	ds_read_b32 v74, v7 offset:360
	ds_read_b32 v75, v7 offset:492
	ds_read_b32 v76, v7 offset:624
	ds_read_b32 v77, v7 offset:756
	ds_read_b32 v78, v7 offset:888
	ds_read_b32 v79, v7 offset:1020
	s_waitcnt lgkmcnt(0)
; #define LAS __attribute__((address_space(3)))
; __device__ __forceinline__ unsigned pk2(float lo, float hi) { f32x2 f = {lo, hi}; bf16x2_t b = __builtin_convertvector(f, bf16x2_t); return __builtin_bit_cast(unsigned, b); }
; template <int MAP, bool HASG, bool PERMW>
; __device__ __forceinline__ void tr_store(int K, int N, bf16_t* WT, LAS float* scr, int item, int lane, const float* gk) {
;     const int nblk = N / 32, kb = item / nblk, nb = item % nblk, k0 = 64 * kb, n0 = 32 * nb;
;     asm volatile("s_waitcnt lgkmcnt(0)" ::: "memory");
;     const int c = lane & 7;
;     f32x4 g0 = {1.f, 1.f, 1.f, 1.f}, g1 = {1.f, 1.f, 1.f, 1.f};
;     if (HASG) { g0 = *(const f32x4*)(gk + k0 + 8 * c); g1 = *(const f32x4*)(gk + k0 + 8 * c + 4); }
; #pragma unroll
;     for (int j = 0; j < 4; ++j) { const int n = (lane >> 3) + 8 * j; const LAS float* s = scr + (8 * c) * 33 + n;
;         u32x4 o; o.x = pk2(s[0 * 33] * g0[0], s[1 * 33] * g0[1]); o.y = pk2(s[2 * 33] * g0[2], s[3 * 33] * g0[3]); o.z = pk2(s[4 * 33] * g1[0], s[5 * 33] * g1[1]); o.w = pk2(s[6 * 33] * g1[2], s[7 * 33] * g1[3]);
;         const int wr_ = rowmap<MAP>(n0 + n), slot_ = PERMW ? ((wr_ & ~31) + invperm32(wr_ & 31)) : wr_;
;         *(u32x4*)((char*)WT + tiled_off(slot_, k0 + 8 * c, K / 64)) = o; }
;     asm volatile("s_waitcnt lgkmcnt(0)" ::: "memory");
; }
	v_mul_f32_e32 v48, v48, v120
	v_mul_f32_e32 v49, v49, v121
	v_mul_f32_e32 v50, v50, v122
	v_mul_f32_e32 v51, v51, v123
	v_mul_f32_e32 v52, v52, v124
	v_mul_f32_e32 v53, v53, v125
	v_mul_f32_e32 v54, v54, v126
	v_mul_f32_e32 v55, v55, v127
	v_cvt_pk_bf16_f32 v48, v48, v49
	v_cvt_pk_bf16_f32 v49, v50, v51
	v_cvt_pk_bf16_f32 v50, v52, v53
	v_cvt_pk_bf16_f32 v51, v54, v55
	global_store_dwordx4 v10, v[48:51], s[24:25]
	v_mul_f32_e32 v56, v56, v120
	v_mul_f32_e32 v57, v57, v121
	v_mul_f32_e32 v58, v58, v122
	v_mul_f32_e32 v59, v59, v123
	v_mul_f32_e32 v60, v60, v124
	v_mul_f32_e32 v61, v61, v125
	v_mul_f32_e32 v62, v62, v126
	v_mul_f32_e32 v63, v63, v127
	v_cvt_pk_bf16_f32 v56, v56, v57
	v_cvt_pk_bf16_f32 v57, v58, v59
	v_cvt_pk_bf16_f32 v58, v60, v61
	v_cvt_pk_bf16_f32 v59, v62, v63
	global_store_dwordx4 v10, v[56:59], s[24:25] offset:256
	v_mul_f32_e32 v64, v64, v120
	v_mul_f32_e32 v65, v65, v121
	v_mul_f32_e32 v66, v66, v122
	v_mul_f32_e32 v67, v67, v123
	v_mul_f32_e32 v68, v68, v124
	v_mul_f32_e32 v69, v69, v125
	v_mul_f32_e32 v70, v70, v126
	v_mul_f32_e32 v71, v71, v127
	v_cvt_pk_bf16_f32 v64, v64, v65
	v_cvt_pk_bf16_f32 v65, v66, v67
	v_cvt_pk_bf16_f32 v66, v68, v69
	v_cvt_pk_bf16_f32 v67, v70, v71
	global_store_dwordx4 v11, v[64:67], s[24:25] offset:512
	v_mul_f32_e32 v72, v72, v120
	v_mul_f32_e32 v73, v73, v121
	v_mul_f32_e32 v74, v74, v122
	v_mul_f32_e32 v75, v75, v123
	v_mul_f32_e32 v76, v76, v124
	v_mul_f32_e32 v77, v77, v125
	v_mul_f32_e32 v78, v78, v126
	v_mul_f32_e32 v79, v79, v127
	v_cvt_pk_bf16_f32 v72, v72, v73
	v_cvt_pk_bf16_f32 v73, v74, v75
	v_cvt_pk_bf16_f32 v74, v76, v77
	v_cvt_pk_bf16_f32 v75, v78, v79
	global_store_dwordx4 v11, v[72:75], s[24:25] offset:768
	s_branch .Ltc1b_loop
.Ltc1b_lastA:
	s_waitcnt vmcnt(0)
	ds_write_b32 v4, v16
	ds_write_b32 v4, v17 offset:264
	ds_write_b32 v4, v18 offset:528
	ds_write_b32 v4, v19 offset:792
	ds_write_b32 v4, v20 offset:1056
	ds_write_b32 v4, v21 offset:1320
	ds_write_b32 v4, v22 offset:1584
	ds_write_b32 v4, v23 offset:1848
	ds_write_b32 v4, v24 offset:2112
	ds_write_b32 v4, v25 offset:2376
	ds_write_b32 v4, v26 offset:2640
	ds_write_b32 v4, v27 offset:2904
	ds_write_b32 v4, v28 offset:3168
	ds_write_b32 v4, v29 offset:3432
	ds_write_b32 v4, v30 offset:3696
	ds_write_b32 v4, v31 offset:3960
	ds_write_b32 v4, v32 offset:4224
	ds_write_b32 v4, v33 offset:4488
	ds_write_b32 v4, v34 offset:4752
	ds_write_b32 v4, v35 offset:5016
	ds_write_b32 v4, v36 offset:5280
	ds_write_b32 v4, v37 offset:5544
	ds_write_b32 v4, v38 offset:5808
	ds_write_b32 v4, v39 offset:6072
	ds_write_b32 v4, v40 offset:6336
	ds_write_b32 v4, v41 offset:6600
	ds_write_b32 v4, v42 offset:6864
	ds_write_b32 v4, v43 offset:7128
	ds_write_b32 v4, v44 offset:7392
	ds_write_b32 v4, v45 offset:7656
	ds_write_b32 v4, v46 offset:7920
	ds_write_b32 v4, v47 offset:8184
	s_waitcnt lgkmcnt(0)
	ds_read_b32 v48, v7
	ds_read_b32 v49, v7 offset:132
	ds_read_b32 v50, v7 offset:264
	ds_read_b32 v51, v7 offset:396
	ds_read_b32 v52, v7 offset:528
	ds_read_b32 v53, v7 offset:660
	ds_read_b32 v54, v7 offset:792
	ds_read_b32 v55, v7 offset:924
	ds_read_b32 v56, v7 offset:32
	ds_read_b32 v57, v7 offset:164
	ds_read_b32 v58, v7 offset:296
	ds_read_b32 v59, v7 offset:428
	ds_read_b32 v60, v7 offset:560
	ds_read_b32 v61, v7 offset:692
	ds_read_b32 v62, v7 offset:824
	ds_read_b32 v63, v7 offset:956
	ds_read_b32 v64, v7 offset:64
	ds_read_b32 v65, v7 offset:196
	ds_read_b32 v66, v7 offset:328
	ds_read_b32 v67, v7 offset:460
	ds_read_b32 v68, v7 offset:592
	ds_read_b32 v69, v7 offset:724
	ds_read_b32 v70, v7 offset:856
	ds_read_b32 v71, v7 offset:988
	ds_read_b32 v72, v7 offset:96
	ds_read_b32 v73, v7 offset:228
	ds_read_b32 v74, v7 offset:360
	ds_read_b32 v75, v7 offset:492
	ds_read_b32 v76, v7 offset:624
	ds_read_b32 v77, v7 offset:756
	ds_read_b32 v78, v7 offset:888
	ds_read_b32 v79, v7 offset:1020
	s_waitcnt lgkmcnt(0)
	v_mul_f32_e32 v48, v48, v80
	v_mul_f32_e32 v49, v49, v81
	v_mul_f32_e32 v50, v50, v82
	v_mul_f32_e32 v51, v51, v83
	v_mul_f32_e32 v52, v52, v84
	v_mul_f32_e32 v53, v53, v85
	v_mul_f32_e32 v54, v54, v86
	v_mul_f32_e32 v55, v55, v87
	v_cvt_pk_bf16_f32 v48, v48, v49
	v_cvt_pk_bf16_f32 v49, v50, v51
	v_cvt_pk_bf16_f32 v50, v52, v53
	v_cvt_pk_bf16_f32 v51, v54, v55
	global_store_dwordx4 v10, v[48:51], s[16:17]
	v_mul_f32_e32 v56, v56, v80
	v_mul_f32_e32 v57, v57, v81
	v_mul_f32_e32 v58, v58, v82
	v_mul_f32_e32 v59, v59, v83
	v_mul_f32_e32 v60, v60, v84
	v_mul_f32_e32 v61, v61, v85
	v_mul_f32_e32 v62, v62, v86
	v_mul_f32_e32 v63, v63, v87
	v_cvt_pk_bf16_f32 v56, v56, v57
	v_cvt_pk_bf16_f32 v57, v58, v59
	v_cvt_pk_bf16_f32 v58, v60, v61
	v_cvt_pk_bf16_f32 v59, v62, v63
	global_store_dwordx4 v10, v[56:59], s[16:17] offset:256
	v_mul_f32_e32 v64, v64, v80
	v_mul_f32_e32 v65, v65, v81
	v_mul_f32_e32 v66, v66, v82
	v_mul_f32_e32 v67, v67, v83
	v_mul_f32_e32 v68, v68, v84
	v_mul_f32_e32 v69, v69, v85
	v_mul_f32_e32 v70, v70, v86
	v_mul_f32_e32 v71, v71, v87
	v_cvt_pk_bf16_f32 v64, v64, v65
	v_cvt_pk_bf16_f32 v65, v66, v67
	v_cvt_pk_bf16_f32 v66, v68, v69
	v_cvt_pk_bf16_f32 v67, v70, v71
	global_store_dwordx4 v11, v[64:67], s[16:17] offset:512
	v_mul_f32_e32 v72, v72, v80
	v_mul_f32_e32 v73, v73, v81
	v_mul_f32_e32 v74, v74, v82
	v_mul_f32_e32 v75, v75, v83
	v_mul_f32_e32 v76, v76, v84
	v_mul_f32_e32 v77, v77, v85
	v_mul_f32_e32 v78, v78, v86
	v_mul_f32_e32 v79, v79, v87
	v_cvt_pk_bf16_f32 v72, v72, v73
	v_cvt_pk_bf16_f32 v73, v74, v75
	v_cvt_pk_bf16_f32 v74, v76, v77
	v_cvt_pk_bf16_f32 v75, v78, v79
	global_store_dwordx4 v11, v[72:75], s[16:17] offset:768
	s_branch .Ltc1b_exit
; #define LAS __attribute__((address_space(3)))
; __device__ __forceinline__ unsigned pk2(float lo, float hi) { f32x2 f = {lo, hi}; bf16x2_t b = __builtin_convertvector(f, bf16x2_t); return __builtin_bit_cast(unsigned, b); }
; template <int MAP, bool HASG, bool PERMW>
; __device__ __forceinline__ void tr_store(int K, int N, bf16_t* WT, LAS float* scr, int item, int lane, const float* gk) {
;     const int nblk = N / 32, kb = item / nblk, nb = item % nblk, k0 = 64 * kb, n0 = 32 * nb;
;     asm volatile("s_waitcnt lgkmcnt(0)" ::: "memory");
;     const int c = lane & 7;
;     f32x4 g0 = {1.f, 1.f, 1.f, 1.f}, g1 = {1.f, 1.f, 1.f, 1.f};
;     if (HASG) { g0 = *(const f32x4*)(gk + k0 + 8 * c); g1 = *(const f32x4*)(gk + k0 + 8 * c + 4); }
; #pragma unroll
;     for (int j = 0; j < 4; ++j) { const int n = (lane >> 3) + 8 * j; const LAS float* s = scr + (8 * c) * 33 + n;
;         u32x4 o; o.x = pk2(s[0 * 33] * g0[0], s[1 * 33] * g0[1]); o.y = pk2(s[2 * 33] * g0[2], s[3 * 33] * g0[3]); o.z = pk2(s[4 * 33] * g1[0], s[5 * 33] * g1[1]); o.w = pk2(s[6 * 33] * g1[2], s[7 * 33] * g1[3]);
;         const int wr_ = rowmap<MAP>(n0 + n), slot_ = PERMW ? ((wr_ & ~31) + invperm32(wr_ & 31)) : wr_;
;         *(u32x4*)((char*)WT + tiled_off(slot_, k0 + 8 * c, K / 64)) = o; }
;     asm volatile("s_waitcnt lgkmcnt(0)" ::: "memory");
; }
; __global__ void __launch_bounds__(512, 2) mega_fwd(Params p) {
;     ...
;             transpose_mat<3, true, true>(p.in[6] + (size_t)l * D * INW, D, INW, P_W(WS_WIN), scr, gw, ngw, lane, p.in[5] + l * D);
.Ltc1b_lastB:
	s_waitcnt vmcnt(0)
	ds_write_b32 v4, v88
	ds_write_b32 v4, v89 offset:264
	ds_write_b32 v4, v90 offset:528
	ds_write_b32 v4, v91 offset:792
	ds_write_b32 v4, v92 offset:1056
	ds_write_b32 v4, v93 offset:1320
	ds_write_b32 v4, v94 offset:1584
	ds_write_b32 v4, v95 offset:1848
	ds_write_b32 v4, v96 offset:2112
	ds_write_b32 v4, v97 offset:2376
	ds_write_b32 v4, v98 offset:2640
	ds_write_b32 v4, v99 offset:2904
	ds_write_b32 v4, v100 offset:3168
	ds_write_b32 v4, v101 offset:3432
	ds_write_b32 v4, v102 offset:3696
	ds_write_b32 v4, v103 offset:3960
	ds_write_b32 v4, v104 offset:4224
	ds_write_b32 v4, v105 offset:4488
	ds_write_b32 v4, v106 offset:4752
	ds_write_b32 v4, v107 offset:5016
	ds_write_b32 v4, v108 offset:5280
	ds_write_b32 v4, v109 offset:5544
	ds_write_b32 v4, v110 offset:5808
	ds_write_b32 v4, v111 offset:6072
	ds_write_b32 v4, v112 offset:6336
	ds_write_b32 v4, v113 offset:6600
	ds_write_b32 v4, v114 offset:6864
	ds_write_b32 v4, v115 offset:7128
	ds_write_b32 v4, v116 offset:7392
	ds_write_b32 v4, v117 offset:7656
	ds_write_b32 v4, v118 offset:7920
	ds_write_b32 v4, v119 offset:8184
	s_waitcnt lgkmcnt(0)
	ds_read_b32 v48, v7
	ds_read_b32 v49, v7 offset:132
	ds_read_b32 v50, v7 offset:264
	ds_read_b32 v51, v7 offset:396
	ds_read_b32 v52, v7 offset:528
	ds_read_b32 v53, v7 offset:660
	ds_read_b32 v54, v7 offset:792
	ds_read_b32 v55, v7 offset:924
	ds_read_b32 v56, v7 offset:32
	ds_read_b32 v57, v7 offset:164
	ds_read_b32 v58, v7 offset:296
	ds_read_b32 v59, v7 offset:428
	ds_read_b32 v60, v7 offset:560
	ds_read_b32 v61, v7 offset:692
	ds_read_b32 v62, v7 offset:824
	ds_read_b32 v63, v7 offset:956
	ds_read_b32 v64, v7 offset:64
	ds_read_b32 v65, v7 offset:196
	ds_read_b32 v66, v7 offset:328
	ds_read_b32 v67, v7 offset:460
	ds_read_b32 v68, v7 offset:592
	ds_read_b32 v69, v7 offset:724
	ds_read_b32 v70, v7 offset:856
	ds_read_b32 v71, v7 offset:988
	ds_read_b32 v72, v7 offset:96
	ds_read_b32 v73, v7 offset:228
	ds_read_b32 v74, v7 offset:360
	ds_read_b32 v75, v7 offset:492
	ds_read_b32 v76, v7 offset:624
	ds_read_b32 v77, v7 offset:756
	ds_read_b32 v78, v7 offset:888
	ds_read_b32 v79, v7 offset:1020
	s_waitcnt lgkmcnt(0)
	v_mul_f32_e32 v48, v48, v120
	v_mul_f32_e32 v49, v49, v121
	v_mul_f32_e32 v50, v50, v122
	v_mul_f32_e32 v51, v51, v123
	v_mul_f32_e32 v52, v52, v124
	v_mul_f32_e32 v53, v53, v125
	v_mul_f32_e32 v54, v54, v126
	v_mul_f32_e32 v55, v55, v127
	v_cvt_pk_bf16_f32 v48, v48, v49
	v_cvt_pk_bf16_f32 v49, v50, v51
	v_cvt_pk_bf16_f32 v50, v52, v53
	v_cvt_pk_bf16_f32 v51, v54, v55
	global_store_dwordx4 v10, v[48:51], s[24:25]
	v_mul_f32_e32 v56, v56, v120
	v_mul_f32_e32 v57, v57, v121
	v_mul_f32_e32 v58, v58, v122
	v_mul_f32_e32 v59, v59, v123
	v_mul_f32_e32 v60, v60, v124
	v_mul_f32_e32 v61, v61, v125
	v_mul_f32_e32 v62, v62, v126
	v_mul_f32_e32 v63, v63, v127
	v_cvt_pk_bf16_f32 v56, v56, v57
	v_cvt_pk_bf16_f32 v57, v58, v59
	v_cvt_pk_bf16_f32 v58, v60, v61
	v_cvt_pk_bf16_f32 v59, v62, v63
	global_store_dwordx4 v10, v[56:59], s[24:25] offset:256
	v_mul_f32_e32 v64, v64, v120
	v_mul_f32_e32 v65, v65, v121
	v_mul_f32_e32 v66, v66, v122
	v_mul_f32_e32 v67, v67, v123
	v_mul_f32_e32 v68, v68, v124
	v_mul_f32_e32 v69, v69, v125
	v_mul_f32_e32 v70, v70, v126
	v_mul_f32_e32 v71, v71, v127
	v_cvt_pk_bf16_f32 v64, v64, v65
	v_cvt_pk_bf16_f32 v65, v66, v67
	v_cvt_pk_bf16_f32 v66, v68, v69
	v_cvt_pk_bf16_f32 v67, v70, v71
	global_store_dwordx4 v11, v[64:67], s[24:25] offset:512
	v_mul_f32_e32 v72, v72, v120
	v_mul_f32_e32 v73, v73, v121
	v_mul_f32_e32 v74, v74, v122
	v_mul_f32_e32 v75, v75, v123
	v_mul_f32_e32 v76, v76, v124
	v_mul_f32_e32 v77, v77, v125
	v_mul_f32_e32 v78, v78, v126
	v_mul_f32_e32 v79, v79, v127
	v_cvt_pk_bf16_f32 v72, v72, v73
	v_cvt_pk_bf16_f32 v73, v74, v75
	v_cvt_pk_bf16_f32 v74, v76, v77
	v_cvt_pk_bf16_f32 v75, v78, v79
	global_store_dwordx4 v11, v[72:75], s[24:25] offset:768
.Ltc1b_exit:
	v_readlane_b32 s4, v255, 8
	v_readlane_b32 s5, v255, 9
	v_readlane_b32 s20, v255, 6
	v_readlane_b32 s21, v255, 7
	s_nop 3
	s_and_b32 s6, s60, 0x6800000
	s_add_u32 s4, s4, s6
	s_addc_u32 s5, s5, 0
	s_and_b32 s6, s60, 0x2000
	s_add_u32 s20, s20, s6
	s_addc_u32 s21, s21, 0
	s_add_u32 s6, s76, 0x4200000
	s_addc_u32 s7, s77, 0
	s_mov_b32 s9, s18
	s_cmpk_ge_u32 s9, 0x3400
	s_cbranch_scc1 .Ltc1c_exit
; #define LAS __attribute__((address_space(3)))
; __device__ __forceinline__ unsigned pk2(float lo, float hi) { f32x2 f = {lo, hi}; bf16x2_t b = __builtin_convertvector(f, bf16x2_t); return __builtin_bit_cast(unsigned, b); }
; template <int MAP> __device__ __forceinline__ int rowmap(int n) {
;     if (MAP == 1) return (n >> 7) * 256 + (n & 127);
;     if (MAP == 2) return (n >> 7) * 256 + 128 + (n & 127);
;     if (MAP == 3) {
;         const bool rot = (n < 2048) || (n >= 3072 && n < 5120);
;         if (!rot) return n;
;         const int c = n & 127, i = c & 63, half = c >> 6;
;         return (n & ~127) + 32 * (i >> 4) + 8 * ((i >> 2) & 3) + 4 * half + (i & 3);
;     }
;     return n;
; }
; __device__ __forceinline__ void tr_load(const float* W, int N, int item, int lane, float (&wv)[32]) {
;     const int nblk = N / 32, kb = item / nblk, nb = item % nblk, k0 = 64 * kb, n0 = 32 * nb;
; #pragma unroll
;     for (int i = 0; i < 32; ++i) { const int kk = 2 * i + (lane >> 5); wv[i] = __builtin_nontemporal_load(W + (size_t)(k0 + kk) * N + n0 + (lane & 31)); }
; }
; template <int MAP, bool HASG, bool PERMW>
; __device__ __forceinline__ void tr_store(int K, int N, bf16_t* WT, LAS float* scr, int item, int lane, const float* gk) {
;     const int nblk = N / 32, kb = item / nblk, nb = item % nblk, k0 = 64 * kb, n0 = 32 * nb;
;     asm volatile("s_waitcnt lgkmcnt(0)" ::: "memory");
;     const int c = lane & 7;
;     f32x4 g0 = {1.f, 1.f, 1.f, 1.f}, g1 = {1.f, 1.f, 1.f, 1.f};
;     if (HASG) { g0 = *(const f32x4*)(gk + k0 + 8 * c); g1 = *(const f32x4*)(gk + k0 + 8 * c + 4); }
; #pragma unroll
;     for (int j = 0; j < 4; ++j) { const int n = (lane >> 3) + 8 * j; const LAS float* s = scr + (8 * c) * 33 + n;
;         u32x4 o; o.x = pk2(s[0 * 33] * g0[0], s[1 * 33] * g0[1]); o.y = pk2(s[2 * 33] * g0[2], s[3 * 33] * g0[3]); o.z = pk2(s[4 * 33] * g1[0], s[5 * 33] * g1[1]); o.w = pk2(s[6 * 33] * g1[2], s[7 * 33] * g1[3]);
;         const int wr_ = rowmap<MAP>(n0 + n), slot_ = PERMW ? ((wr_ & ~31) + invperm32(wr_ & 31)) : wr_;
;         *(u32x4*)((char*)WT + tiled_off(slot_, k0 + 8 * c, K / 64)) = o; }
;     asm volatile("s_waitcnt lgkmcnt(0)" ::: "memory");
; }
	s_mul_hi_u32 s11, s9, 0x4ec4ec4f
	s_lshr_b32 s11, s11, 7
	s_mul_i32 s12, s11, 0x1a0
	s_sub_u32 s12, s9, s12
	s_mul_i32 s13, s11, 0x340000
	s_lshl_b32 s14, s12, 7
	s_add_u32 s13, s13, s14
	s_add_u32 s14, s4, s13
	s_addc_u32 s15, s5, 0
	global_load_dword v16, v12, s[14:15] nt
	s_add_u32 s14, s14, 0x1a000
	s_addc_u32 s15, s15, 0
	global_load_dword v17, v12, s[14:15] nt
	s_add_u32 s14, s14, 0x1a000
	s_addc_u32 s15, s15, 0
	global_load_dword v18, v12, s[14:15] nt
	s_add_u32 s14, s14, 0x1a000
	s_addc_u32 s15, s15, 0
	global_load_dword v19, v12, s[14:15] nt
	s_add_u32 s14, s14, 0x1a000
	s_addc_u32 s15, s15, 0
	global_load_dword v20, v12, s[14:15] nt
	s_add_u32 s14, s14, 0x1a000
	s_addc_u32 s15, s15, 0
	global_load_dword v21, v12, s[14:15] nt
	s_add_u32 s14, s14, 0x1a000
	s_addc_u32 s15, s15, 0
	global_load_dword v22, v12, s[14:15] nt
	s_add_u32 s14, s14, 0x1a000
	s_addc_u32 s15, s15, 0
	global_load_dword v23, v12, s[14:15] nt
	s_add_u32 s14, s14, 0x1a000
	s_addc_u32 s15, s15, 0
	global_load_dword v24, v12, s[14:15] nt
	s_add_u32 s14, s14, 0x1a000
	s_addc_u32 s15, s15, 0
	global_load_dword v25, v12, s[14:15] nt
	s_add_u32 s14, s14, 0x1a000
	s_addc_u32 s15, s15, 0
	global_load_dword v26, v12, s[14:15] nt
	s_add_u32 s14, s14, 0x1a000
	s_addc_u32 s15, s15, 0
	global_load_dword v27, v12, s[14:15] nt
	s_add_u32 s14, s14, 0x1a000
	s_addc_u32 s15, s15, 0
	global_load_dword v28, v12, s[14:15] nt
	s_add_u32 s14, s14, 0x1a000
	s_addc_u32 s15, s15, 0
	global_load_dword v29, v12, s[14:15] nt
	s_add_u32 s14, s14, 0x1a000
	s_addc_u32 s15, s15, 0
	global_load_dword v30, v12, s[14:15] nt
	s_add_u32 s14, s14, 0x1a000
	s_addc_u32 s15, s15, 0
	global_load_dword v31, v12, s[14:15] nt
	s_add_u32 s14, s14, 0x1a000
	s_addc_u32 s15, s15, 0
	global_load_dword v32, v12, s[14:15] nt
	s_add_u32 s14, s14, 0x1a000
	s_addc_u32 s15, s15, 0
	global_load_dword v33, v12, s[14:15] nt
	s_add_u32 s14, s14, 0x1a000
	s_addc_u32 s15, s15, 0
	global_load_dword v34, v12, s[14:15] nt
	s_add_u32 s14, s14, 0x1a000
	s_addc_u32 s15, s15, 0
	global_load_dword v35, v12, s[14:15] nt
	s_add_u32 s14, s14, 0x1a000
	s_addc_u32 s15, s15, 0
	global_load_dword v36, v12, s[14:15] nt
	s_add_u32 s14, s14, 0x1a000
	s_addc_u32 s15, s15, 0
	global_load_dword v37, v12, s[14:15] nt
	s_add_u32 s14, s14, 0x1a000
	s_addc_u32 s15, s15, 0
	global_load_dword v38, v12, s[14:15] nt
	s_add_u32 s14, s14, 0x1a000
	s_addc_u32 s15, s15, 0
	global_load_dword v39, v12, s[14:15] nt
	s_add_u32 s14, s14, 0x1a000
	s_addc_u32 s15, s15, 0
	global_load_dword v40, v12, s[14:15] nt
	s_add_u32 s14, s14, 0x1a000
	s_addc_u32 s15, s15, 0
	global_load_dword v41, v12, s[14:15] nt
	s_add_u32 s14, s14, 0x1a000
	s_addc_u32 s15, s15, 0
	global_load_dword v42, v12, s[14:15] nt
	s_add_u32 s14, s14, 0x1a000
	s_addc_u32 s15, s15, 0
	global_load_dword v43, v12, s[14:15] nt
	s_add_u32 s14, s14, 0x1a000
	s_addc_u32 s15, s15, 0
	global_load_dword v44, v12, s[14:15] nt
	s_add_u32 s14, s14, 0x1a000
	s_addc_u32 s15, s15, 0
	global_load_dword v45, v12, s[14:15] nt
	s_add_u32 s14, s14, 0x1a000
	s_addc_u32 s15, s15, 0
	global_load_dword v46, v12, s[14:15] nt
	s_add_u32 s14, s14, 0x1a000
	s_addc_u32 s15, s15, 0
	global_load_dword v47, v12, s[14:15] nt
	s_lshl_b32 s14, s11, 8
	s_add_u32 s14, s20, s14
	s_addc_u32 s15, s21, 0
	global_load_dwordx4 v[80:83], v14, s[14:15]
	global_load_dwordx4 v[84:87], v14, s[14:15] offset:16
	s_sub_u32 s13, s12, 0x60
	s_cmp_lt_u32 s13, 0x40
	s_cselect_b32 s28, 1, 0
	s_cmp_lt_u32 s12, 0x40
	s_cselect_b32 s13, 1, 0
	s_or_b32 s28, s28, s13
	s_lshr_b32 s16, s12, 2
	s_lshl_b32 s16, s16, 5
	s_add_u32 s16, s16, s11
	s_lshl_b32 s16, s16, 14
	s_and_b32 s13, s12, 1
	s_lshl_b32 s13, s13, 13
	s_bfe_u32 s14, s12, 0x10001
	s_lshl_b32 s14, s14, 11
	s_add_u32 s13, s13, s14
	s_and_b32 s14, s12, 3
	s_lshl_b32 s14, s14, 12
	s_cmp_lg_u32 s28, 0
	s_cselect_b32 s13, s13, s14
	s_add_u32 s16, s16, s13
	s_add_u32 s16, s6, s16
	s_addc_u32 s17, s7, 0
	s_add_u32 s22, s16, 0x1000
	s_addc_u32 s23, s17, 0
.Ltc1c_loop:
	s_add_u32 s9, s9, 0x400
	s_cmpk_ge_u32 s9, 0x3400
	s_cbranch_scc1 .Ltc1c_lastA
	s_mul_hi_u32 s11, s9, 0x4ec4ec4f
	s_lshr_b32 s11, s11, 7
	s_mul_i32 s12, s11, 0x1a0
	s_sub_u32 s12, s9, s12
	s_mul_i32 s13, s11, 0x340000
	s_lshl_b32 s14, s12, 7
	s_add_u32 s13, s13, s14
	s_add_u32 s14, s4, s13
	s_addc_u32 s15, s5, 0
	global_load_dword v88, v12, s[14:15] nt
	s_add_u32 s14, s14, 0x1a000
	s_addc_u32 s15, s15, 0
	global_load_dword v89, v12, s[14:15] nt
	s_add_u32 s14, s14, 0x1a000
	s_addc_u32 s15, s15, 0
	global_load_dword v90, v12, s[14:15] nt
	s_add_u32 s14, s14, 0x1a000
	s_addc_u32 s15, s15, 0
	global_load_dword v91, v12, s[14:15] nt
	s_add_u32 s14, s14, 0x1a000
	s_addc_u32 s15, s15, 0
	global_load_dword v92, v12, s[14:15] nt
	s_add_u32 s14, s14, 0x1a000
	s_addc_u32 s15, s15, 0
	global_load_dword v93, v12, s[14:15] nt
	s_add_u32 s14, s14, 0x1a000
	s_addc_u32 s15, s15, 0
	global_load_dword v94, v12, s[14:15] nt
	s_add_u32 s14, s14, 0x1a000
	s_addc_u32 s15, s15, 0
	global_load_dword v95, v12, s[14:15] nt
	s_add_u32 s14, s14, 0x1a000
	s_addc_u32 s15, s15, 0
	global_load_dword v96, v12, s[14:15] nt
	s_add_u32 s14, s14, 0x1a000
	s_addc_u32 s15, s15, 0
	global_load_dword v97, v12, s[14:15] nt
	s_add_u32 s14, s14, 0x1a000
	s_addc_u32 s15, s15, 0
	global_load_dword v98, v12, s[14:15] nt
	s_add_u32 s14, s14, 0x1a000
	s_addc_u32 s15, s15, 0
	global_load_dword v99, v12, s[14:15] nt
	s_add_u32 s14, s14, 0x1a000
	s_addc_u32 s15, s15, 0
	global_load_dword v100, v12, s[14:15] nt
	s_add_u32 s14, s14, 0x1a000
	s_addc_u32 s15, s15, 0
	global_load_dword v101, v12, s[14:15] nt
	s_add_u32 s14, s14, 0x1a000
	s_addc_u32 s15, s15, 0
	global_load_dword v102, v12, s[14:15] nt
; #define LAS __attribute__((address_space(3)))
; __device__ __forceinline__ unsigned pk2(float lo, float hi) { f32x2 f = {lo, hi}; bf16x2_t b = __builtin_convertvector(f, bf16x2_t); return __builtin_bit_cast(unsigned, b); }
; template <int MAP> __device__ __forceinline__ int rowmap(int n) {
;     if (MAP == 1) return (n >> 7) * 256 + (n & 127);
;     if (MAP == 2) return (n >> 7) * 256 + 128 + (n & 127);
;     if (MAP == 3) {
;         const bool rot = (n < 2048) || (n >= 3072 && n < 5120);
;         if (!rot) return n;
;         const int c = n & 127, i = c & 63, half = c >> 6;
;         return (n & ~127) + 32 * (i >> 4) + 8 * ((i >> 2) & 3) + 4 * half + (i & 3);
;     }
;     return n;
; }
; __device__ __forceinline__ void tr_load(const float* W, int N, int item, int lane, float (&wv)[32]) {
;     const int nblk = N / 32, kb = item / nblk, nb = item % nblk, k0 = 64 * kb, n0 = 32 * nb;
; #pragma unroll
;     for (int i = 0; i < 32; ++i) { const int kk = 2 * i + (lane >> 5); wv[i] = __builtin_nontemporal_load(W + (size_t)(k0 + kk) * N + n0 + (lane & 31)); }
; }
; template <int MAP, bool HASG, bool PERMW>
; __device__ __forceinline__ void tr_store(int K, int N, bf16_t* WT, LAS float* scr, int item, int lane, const float* gk) {
;     const int nblk = N / 32, kb = item / nblk, nb = item % nblk, k0 = 64 * kb, n0 = 32 * nb;
;     asm volatile("s_waitcnt lgkmcnt(0)" ::: "memory");
;     const int c = lane & 7;
;     f32x4 g0 = {1.f, 1.f, 1.f, 1.f}, g1 = {1.f, 1.f, 1.f, 1.f};
;     if (HASG) { g0 = *(const f32x4*)(gk + k0 + 8 * c); g1 = *(const f32x4*)(gk + k0 + 8 * c + 4); }
; #pragma unroll
;     for (int j = 0; j < 4; ++j) { const int n = (lane >> 3) + 8 * j; const LAS float* s = scr + (8 * c) * 33 + n;
;         u32x4 o; o.x = pk2(s[0 * 33] * g0[0], s[1 * 33] * g0[1]); o.y = pk2(s[2 * 33] * g0[2], s[3 * 33] * g0[3]); o.z = pk2(s[4 * 33] * g1[0], s[5 * 33] * g1[1]); o.w = pk2(s[6 * 33] * g1[2], s[7 * 33] * g1[3]);
;         const int wr_ = rowmap<MAP>(n0 + n), slot_ = PERMW ? ((wr_ & ~31) + invperm32(wr_ & 31)) : wr_;
;         *(u32x4*)((char*)WT + tiled_off(slot_, k0 + 8 * c, K / 64)) = o; }
;     asm volatile("s_waitcnt lgkmcnt(0)" ::: "memory");
; }
	s_add_u32 s14, s14, 0x1a000
	s_addc_u32 s15, s15, 0
	global_load_dword v103, v12, s[14:15] nt
	s_add_u32 s14, s14, 0x1a000
	s_addc_u32 s15, s15, 0
	global_load_dword v104, v12, s[14:15] nt
	s_add_u32 s14, s14, 0x1a000
	s_addc_u32 s15, s15, 0
	global_load_dword v105, v12, s[14:15] nt
	s_add_u32 s14, s14, 0x1a000
	s_addc_u32 s15, s15, 0
	global_load_dword v106, v12, s[14:15] nt
	s_add_u32 s14, s14, 0x1a000
	s_addc_u32 s15, s15, 0
	global_load_dword v107, v12, s[14:15] nt
	s_add_u32 s14, s14, 0x1a000
	s_addc_u32 s15, s15, 0
	global_load_dword v108, v12, s[14:15] nt
	s_add_u32 s14, s14, 0x1a000
	s_addc_u32 s15, s15, 0
	global_load_dword v109, v12, s[14:15] nt
	s_add_u32 s14, s14, 0x1a000
	s_addc_u32 s15, s15, 0
	global_load_dword v110, v12, s[14:15] nt
	s_add_u32 s14, s14, 0x1a000
	s_addc_u32 s15, s15, 0
	global_load_dword v111, v12, s[14:15] nt
	s_add_u32 s14, s14, 0x1a000
	s_addc_u32 s15, s15, 0
	global_load_dword v112, v12, s[14:15] nt
	s_add_u32 s14, s14, 0x1a000
	s_addc_u32 s15, s15, 0
	global_load_dword v113, v12, s[14:15] nt
	s_add_u32 s14, s14, 0x1a000
	s_addc_u32 s15, s15, 0
	global_load_dword v114, v12, s[14:15] nt
	s_add_u32 s14, s14, 0x1a000
	s_addc_u32 s15, s15, 0
	global_load_dword v115, v12, s[14:15] nt
	s_add_u32 s14, s14, 0x1a000
	s_addc_u32 s15, s15, 0
	global_load_dword v116, v12, s[14:15] nt
	s_add_u32 s14, s14, 0x1a000
	s_addc_u32 s15, s15, 0
	global_load_dword v117, v12, s[14:15] nt
	s_add_u32 s14, s14, 0x1a000
	s_addc_u32 s15, s15, 0
	global_load_dword v118, v12, s[14:15] nt
	s_add_u32 s14, s14, 0x1a000
	s_addc_u32 s15, s15, 0
	global_load_dword v119, v12, s[14:15] nt
	s_lshl_b32 s14, s11, 8
	s_add_u32 s14, s20, s14
	s_addc_u32 s15, s21, 0
	global_load_dwordx4 v[120:123], v14, s[14:15]
	global_load_dwordx4 v[124:127], v14, s[14:15] offset:16
	s_sub_u32 s13, s12, 0x60
	s_cmp_lt_u32 s13, 0x40
	s_cselect_b32 s29, 1, 0
	s_cmp_lt_u32 s12, 0x40
	s_cselect_b32 s13, 1, 0
	s_or_b32 s29, s29, s13
	s_lshr_b32 s24, s12, 2
	s_lshl_b32 s24, s24, 5
	s_add_u32 s24, s24, s11
	s_lshl_b32 s24, s24, 14
	s_and_b32 s13, s12, 1
	s_lshl_b32 s13, s13, 13
	s_bfe_u32 s14, s12, 0x10001
	s_lshl_b32 s14, s14, 11
	s_add_u32 s13, s13, s14
	s_and_b32 s14, s12, 3
	s_lshl_b32 s14, s14, 12
	s_cmp_lg_u32 s29, 0
	s_cselect_b32 s13, s13, s14
	s_add_u32 s24, s24, s13
	s_add_u32 s24, s6, s24
	s_addc_u32 s25, s7, 0
	s_add_u32 s26, s24, 0x1000
	s_addc_u32 s27, s25, 0
	s_waitcnt vmcnt(34)
	ds_write_b32 v4, v16
	ds_write_b32 v4, v17 offset:264
	ds_write_b32 v4, v18 offset:528
	ds_write_b32 v4, v19 offset:792
	ds_write_b32 v4, v20 offset:1056
	ds_write_b32 v4, v21 offset:1320
	ds_write_b32 v4, v22 offset:1584
	ds_write_b32 v4, v23 offset:1848
	ds_write_b32 v4, v24 offset:2112
	ds_write_b32 v4, v25 offset:2376
	ds_write_b32 v4, v26 offset:2640
	ds_write_b32 v4, v27 offset:2904
	ds_write_b32 v4, v28 offset:3168
	ds_write_b32 v4, v29 offset:3432
	ds_write_b32 v4, v30 offset:3696
	ds_write_b32 v4, v31 offset:3960
	ds_write_b32 v4, v32 offset:4224
	ds_write_b32 v4, v33 offset:4488
	ds_write_b32 v4, v34 offset:4752
	ds_write_b32 v4, v35 offset:5016
	ds_write_b32 v4, v36 offset:5280
	ds_write_b32 v4, v37 offset:5544
	ds_write_b32 v4, v38 offset:5808
	ds_write_b32 v4, v39 offset:6072
	ds_write_b32 v4, v40 offset:6336
	ds_write_b32 v4, v41 offset:6600
	ds_write_b32 v4, v42 offset:6864
	ds_write_b32 v4, v43 offset:7128
	ds_write_b32 v4, v44 offset:7392
	ds_write_b32 v4, v45 offset:7656
	ds_write_b32 v4, v46 offset:7920
	ds_write_b32 v4, v47 offset:8184
	s_waitcnt lgkmcnt(0)
	ds_read_b32 v48, v7
	ds_read_b32 v49, v7 offset:132
	ds_read_b32 v50, v7 offset:264
	ds_read_b32 v51, v7 offset:396
	ds_read_b32 v52, v7 offset:528
	ds_read_b32 v53, v7 offset:660
	ds_read_b32 v54, v7 offset:792
	ds_read_b32 v55, v7 offset:924
	ds_read_b32 v56, v7 offset:32
	ds_read_b32 v57, v7 offset:164
	ds_read_b32 v58, v7 offset:296
	ds_read_b32 v59, v7 offset:428
	ds_read_b32 v60, v7 offset:560
	ds_read_b32 v61, v7 offset:692
	ds_read_b32 v62, v7 offset:824
	ds_read_b32 v63, v7 offset:956
	ds_read_b32 v64, v7 offset:64
	ds_read_b32 v65, v7 offset:196
	ds_read_b32 v66, v7 offset:328
	ds_read_b32 v67, v7 offset:460
	ds_read_b32 v68, v7 offset:592
	ds_read_b32 v69, v7 offset:724
	ds_read_b32 v70, v7 offset:856
	ds_read_b32 v71, v7 offset:988
	ds_read_b32 v72, v7 offset:96
	ds_read_b32 v73, v7 offset:228
	ds_read_b32 v74, v7 offset:360
	ds_read_b32 v75, v7 offset:492
	ds_read_b32 v76, v7 offset:624
	ds_read_b32 v77, v7 offset:756
	ds_read_b32 v78, v7 offset:888
	ds_read_b32 v79, v7 offset:1020
	s_waitcnt lgkmcnt(0)
	v_mul_f32_e32 v48, v48, v80
	v_mul_f32_e32 v49, v49, v81
	v_mul_f32_e32 v50, v50, v82
	v_mul_f32_e32 v51, v51, v83
	v_mul_f32_e32 v52, v52, v84
	v_mul_f32_e32 v53, v53, v85
	v_mul_f32_e32 v54, v54, v86
	v_mul_f32_e32 v55, v55, v87
	v_cvt_pk_bf16_f32 v48, v48, v49
	v_cvt_pk_bf16_f32 v49, v50, v51
	v_cvt_pk_bf16_f32 v50, v52, v53
	v_cvt_pk_bf16_f32 v51, v54, v55
	v_mul_f32_e32 v56, v56, v80
	v_mul_f32_e32 v57, v57, v81
	v_mul_f32_e32 v58, v58, v82
	v_mul_f32_e32 v59, v59, v83
	v_mul_f32_e32 v60, v60, v84
	v_mul_f32_e32 v61, v61, v85
	v_mul_f32_e32 v62, v62, v86
	v_mul_f32_e32 v63, v63, v87
	v_cvt_pk_bf16_f32 v56, v56, v57
	v_cvt_pk_bf16_f32 v57, v58, v59
	v_cvt_pk_bf16_f32 v58, v60, v61
	v_cvt_pk_bf16_f32 v59, v62, v63
	v_mul_f32_e32 v64, v64, v80
	v_mul_f32_e32 v65, v65, v81
	v_mul_f32_e32 v66, v66, v82
	v_mul_f32_e32 v67, v67, v83
	v_mul_f32_e32 v68, v68, v84
	v_mul_f32_e32 v69, v69, v85
	v_mul_f32_e32 v70, v70, v86
	v_mul_f32_e32 v71, v71, v87
	v_cvt_pk_bf16_f32 v64, v64, v65
	v_cvt_pk_bf16_f32 v65, v66, v67
	v_cvt_pk_bf16_f32 v66, v68, v69
	v_cvt_pk_bf16_f32 v67, v70, v71
	v_mul_f32_e32 v72, v72, v80
	v_mul_f32_e32 v73, v73, v81
	v_mul_f32_e32 v74, v74, v82
	v_mul_f32_e32 v75, v75, v83
	v_mul_f32_e32 v76, v76, v84
	v_mul_f32_e32 v77, v77, v85
	v_mul_f32_e32 v78, v78, v86
	v_mul_f32_e32 v79, v79, v87
	v_cvt_pk_bf16_f32 v72, v72, v73
	v_cvt_pk_bf16_f32 v73, v74, v75
	v_cvt_pk_bf16_f32 v74, v76, v77
	v_cvt_pk_bf16_f32 v75, v78, v79
	s_cmp_lg_u32 s28, 0
	s_cbranch_scc1 .Ltcw1_rot
	global_store_dwordx4 v10, v[48:51], s[16:17]
	global_store_dwordx4 v10, v[56:59], s[16:17] offset:256
	global_store_dwordx4 v11, v[64:67], s[16:17] offset:512
	global_store_dwordx4 v11, v[72:75], s[16:17] offset:768
	s_branch .Ltcw1_done
; template <int MAP> __device__ __forceinline__ int rowmap(int n) {
;     if (MAP == 1) return (n >> 7) * 256 + (n & 127);
;     if (MAP == 2) return (n >> 7) * 256 + 128 + (n & 127);
;     if (MAP == 3) {
;         const bool rot = (n < 2048) || (n >= 3072 && n < 5120);
;         if (!rot) return n;
;         const int c = n & 127, i = c & 63, half = c >> 6;
;         return (n & ~127) + 32 * (i >> 4) + 8 * ((i >> 2) & 3) + 4 * half + (i & 3);
;     }
;     return n;
; }
; __device__ __forceinline__ void tr_load(const float* W, int N, int item, int lane, float (&wv)[32]) {
;     const int nblk = N / 32, kb = item / nblk, nb = item % nblk, k0 = 64 * kb, n0 = 32 * nb;
; #pragma unroll
;     for (int i = 0; i < 32; ++i) { const int kk = 2 * i + (lane >> 5); wv[i] = __builtin_nontemporal_load(W + (size_t)(k0 + kk) * N + n0 + (lane & 31)); }
; }
; template <int MAP, bool HASG, bool PERMW>
; __device__ __forceinline__ void tr_store(int K, int N, bf16_t* WT, LAS float* scr, int item, int lane, const float* gk) {
;     const int nblk = N / 32, kb = item / nblk, nb = item % nblk, k0 = 64 * kb, n0 = 32 * nb;
;     asm volatile("s_waitcnt lgkmcnt(0)" ::: "memory");
;     const int c = lane & 7;
;     f32x4 g0 = {1.f, 1.f, 1.f, 1.f}, g1 = {1.f, 1.f, 1.f, 1.f};
;     if (HASG) { g0 = *(const f32x4*)(gk + k0 + 8 * c); g1 = *(const f32x4*)(gk + k0 + 8 * c + 4); }
; #pragma unroll
;     for (int j = 0; j < 4; ++j) { const int n = (lane >> 3) + 8 * j; const LAS float* s = scr + (8 * c) * 33 + n;
;         u32x4 o; o.x = pk2(s[0 * 33] * g0[0], s[1 * 33] * g0[1]); o.y = pk2(s[2 * 33] * g0[2], s[3 * 33] * g0[3]); o.z = pk2(s[4 * 33] * g1[0], s[5 * 33] * g1[1]); o.w = pk2(s[6 * 33] * g1[2], s[7 * 33] * g1[3]);
;         const int wr_ = rowmap<MAP>(n0 + n), slot_ = PERMW ? ((wr_ & ~31) + invperm32(wr_ & 31)) : wr_;
;         *(u32x4*)((char*)WT + tiled_off(slot_, k0 + 8 * c, K / 64)) = o; }
;     asm volatile("s_waitcnt lgkmcnt(0)" ::: "memory");
; }
; template <int MAP, bool HASG = false, bool PERMW = false>
; __device__ __forceinline__ void transpose_mat(const float* W, int K, int N, bf16_t* WT, LAS float* scr, int gw, int ngw, int lane, const float* gk = nullptr) {
;     const int nitems = (K / 64) * (N / 32);
;     int it = gw;
;     if (it >= nitems) return;
;     float wv[32];
;     tr_load(W, N, it, lane, wv);
;     for (;;) {
;         __builtin_amdgcn_sched_barrier(0);
.Ltcw1_rot:
	global_store_dwordx4 v8, v[48:51], s[16:17]
	global_store_dwordx4 v9, v[56:59], s[16:17]
	global_store_dwordx4 v8, v[64:67], s[22:23]
	global_store_dwordx4 v9, v[72:75], s[22:23]
.Ltcw1_done:
	s_add_u32 s9, s9, 0x400
	s_cmpk_ge_u32 s9, 0x3400
	s_cbranch_scc1 .Ltc1c_lastB
	s_mul_hi_u32 s11, s9, 0x4ec4ec4f
	s_lshr_b32 s11, s11, 7
	s_mul_i32 s12, s11, 0x1a0
	s_sub_u32 s12, s9, s12
	s_mul_i32 s13, s11, 0x340000
	s_lshl_b32 s14, s12, 7
	s_add_u32 s13, s13, s14
	s_add_u32 s14, s4, s13
	s_addc_u32 s15, s5, 0
	global_load_dword v16, v12, s[14:15] nt
	s_add_u32 s14, s14, 0x1a000
	s_addc_u32 s15, s15, 0
	global_load_dword v17, v12, s[14:15] nt
	s_add_u32 s14, s14, 0x1a000
	s_addc_u32 s15, s15, 0
	global_load_dword v18, v12, s[14:15] nt
	s_add_u32 s14, s14, 0x1a000
	s_addc_u32 s15, s15, 0
	global_load_dword v19, v12, s[14:15] nt
	s_add_u32 s14, s14, 0x1a000
	s_addc_u32 s15, s15, 0
	global_load_dword v20, v12, s[14:15] nt
	s_add_u32 s14, s14, 0x1a000
	s_addc_u32 s15, s15, 0
	global_load_dword v21, v12, s[14:15] nt
	s_add_u32 s14, s14, 0x1a000
	s_addc_u32 s15, s15, 0
	global_load_dword v22, v12, s[14:15] nt
	s_add_u32 s14, s14, 0x1a000
	s_addc_u32 s15, s15, 0
	global_load_dword v23, v12, s[14:15] nt
	s_add_u32 s14, s14, 0x1a000
	s_addc_u32 s15, s15, 0
	global_load_dword v24, v12, s[14:15] nt
	s_add_u32 s14, s14, 0x1a000
	s_addc_u32 s15, s15, 0
	global_load_dword v25, v12, s[14:15] nt
	s_add_u32 s14, s14, 0x1a000
	s_addc_u32 s15, s15, 0
	global_load_dword v26, v12, s[14:15] nt
	s_add_u32 s14, s14, 0x1a000
	s_addc_u32 s15, s15, 0
	global_load_dword v27, v12, s[14:15] nt
	s_add_u32 s14, s14, 0x1a000
	s_addc_u32 s15, s15, 0
	global_load_dword v28, v12, s[14:15] nt
	s_add_u32 s14, s14, 0x1a000
	s_addc_u32 s15, s15, 0
	global_load_dword v29, v12, s[14:15] nt
	s_add_u32 s14, s14, 0x1a000
	s_addc_u32 s15, s15, 0
	global_load_dword v30, v12, s[14:15] nt
	s_add_u32 s14, s14, 0x1a000
	s_addc_u32 s15, s15, 0
	global_load_dword v31, v12, s[14:15] nt
	s_add_u32 s14, s14, 0x1a000
	s_addc_u32 s15, s15, 0
	global_load_dword v32, v12, s[14:15] nt
	s_add_u32 s14, s14, 0x1a000
	s_addc_u32 s15, s15, 0
	global_load_dword v33, v12, s[14:15] nt
	s_add_u32 s14, s14, 0x1a000
	s_addc_u32 s15, s15, 0
	global_load_dword v34, v12, s[14:15] nt
	s_add_u32 s14, s14, 0x1a000
	s_addc_u32 s15, s15, 0
	global_load_dword v35, v12, s[14:15] nt
	s_add_u32 s14, s14, 0x1a000
	s_addc_u32 s15, s15, 0
	global_load_dword v36, v12, s[14:15] nt
	s_add_u32 s14, s14, 0x1a000
	s_addc_u32 s15, s15, 0
	global_load_dword v37, v12, s[14:15] nt
	s_add_u32 s14, s14, 0x1a000
	s_addc_u32 s15, s15, 0
	global_load_dword v38, v12, s[14:15] nt
	s_add_u32 s14, s14, 0x1a000
	s_addc_u32 s15, s15, 0
	global_load_dword v39, v12, s[14:15] nt
	s_add_u32 s14, s14, 0x1a000
	s_addc_u32 s15, s15, 0
	global_load_dword v40, v12, s[14:15] nt
	s_add_u32 s14, s14, 0x1a000
	s_addc_u32 s15, s15, 0
	global_load_dword v41, v12, s[14:15] nt
	s_add_u32 s14, s14, 0x1a000
	s_addc_u32 s15, s15, 0
	global_load_dword v42, v12, s[14:15] nt
	s_add_u32 s14, s14, 0x1a000
	s_addc_u32 s15, s15, 0
	global_load_dword v43, v12, s[14:15] nt
	s_add_u32 s14, s14, 0x1a000
	s_addc_u32 s15, s15, 0
	global_load_dword v44, v12, s[14:15] nt
	s_add_u32 s14, s14, 0x1a000
	s_addc_u32 s15, s15, 0
	global_load_dword v45, v12, s[14:15] nt
	s_add_u32 s14, s14, 0x1a000
	s_addc_u32 s15, s15, 0
	global_load_dword v46, v12, s[14:15] nt
	s_add_u32 s14, s14, 0x1a000
	s_addc_u32 s15, s15, 0
	global_load_dword v47, v12, s[14:15] nt
	s_lshl_b32 s14, s11, 8
	s_add_u32 s14, s20, s14
	s_addc_u32 s15, s21, 0
	global_load_dwordx4 v[80:83], v14, s[14:15]
	global_load_dwordx4 v[84:87], v14, s[14:15] offset:16
	s_sub_u32 s13, s12, 0x60
	s_cmp_lt_u32 s13, 0x40
	s_cselect_b32 s28, 1, 0
	s_cmp_lt_u32 s12, 0x40
	s_cselect_b32 s13, 1, 0
	s_or_b32 s28, s28, s13
	s_lshr_b32 s16, s12, 2
	s_lshl_b32 s16, s16, 5
	s_add_u32 s16, s16, s11
	s_lshl_b32 s16, s16, 14
	s_and_b32 s13, s12, 1
	s_lshl_b32 s13, s13, 13
	s_bfe_u32 s14, s12, 0x10001
	s_lshl_b32 s14, s14, 11
	s_add_u32 s13, s13, s14
	s_and_b32 s14, s12, 3
	s_lshl_b32 s14, s14, 12
	s_cmp_lg_u32 s28, 0
	s_cselect_b32 s13, s13, s14
	s_add_u32 s16, s16, s13
	s_add_u32 s16, s6, s16
	s_addc_u32 s17, s7, 0
	s_add_u32 s22, s16, 0x1000
	s_addc_u32 s23, s17, 0
	s_waitcnt vmcnt(34)
; #define LAS __attribute__((address_space(3)))
; __device__ __forceinline__ unsigned pk2(float lo, float hi) { f32x2 f = {lo, hi}; bf16x2_t b = __builtin_convertvector(f, bf16x2_t); return __builtin_bit_cast(unsigned, b); }
; template <int MAP> __device__ __forceinline__ int rowmap(int n) {
;     if (MAP == 1) return (n >> 7) * 256 + (n & 127);
;     if (MAP == 2) return (n >> 7) * 256 + 128 + (n & 127);
;     if (MAP == 3) {
;         const bool rot = (n < 2048) || (n >= 3072 && n < 5120);
;         if (!rot) return n;
;         const int c = n & 127, i = c & 63, half = c >> 6;
;         return (n & ~127) + 32 * (i >> 4) + 8 * ((i >> 2) & 3) + 4 * half + (i & 3);
;     }
;     return n;
; }
; __device__ __forceinline__ void tr_load(const float* W, int N, int item, int lane, float (&wv)[32]) {
;     const int nblk = N / 32, kb = item / nblk, nb = item % nblk, k0 = 64 * kb, n0 = 32 * nb;
; #pragma unroll
;     for (int i = 0; i < 32; ++i) { const int kk = 2 * i + (lane >> 5); wv[i] = __builtin_nontemporal_load(W + (size_t)(k0 + kk) * N + n0 + (lane & 31)); }
; }
; template <int MAP, bool HASG, bool PERMW>
; __device__ __forceinline__ void tr_store(int K, int N, bf16_t* WT, LAS float* scr, int item, int lane, const float* gk) {
;     const int nblk = N / 32, kb = item / nblk, nb = item % nblk, k0 = 64 * kb, n0 = 32 * nb;
;     asm volatile("s_waitcnt lgkmcnt(0)" ::: "memory");
;     const int c = lane & 7;
;     f32x4 g0 = {1.f, 1.f, 1.f, 1.f}, g1 = {1.f, 1.f, 1.f, 1.f};
;     if (HASG) { g0 = *(const f32x4*)(gk + k0 + 8 * c); g1 = *(const f32x4*)(gk + k0 + 8 * c + 4); }
; #pragma unroll
;     for (int j = 0; j < 4; ++j) { const int n = (lane >> 3) + 8 * j; const LAS float* s = scr + (8 * c) * 33 + n;
;         u32x4 o; o.x = pk2(s[0 * 33] * g0[0], s[1 * 33] * g0[1]); o.y = pk2(s[2 * 33] * g0[2], s[3 * 33] * g0[3]); o.z = pk2(s[4 * 33] * g1[0], s[5 * 33] * g1[1]); o.w = pk2(s[6 * 33] * g1[2], s[7 * 33] * g1[3]);
;         const int wr_ = rowmap<MAP>(n0 + n), slot_ = PERMW ? ((wr_ & ~31) + invperm32(wr_ & 31)) : wr_;
;         *(u32x4*)((char*)WT + tiled_off(slot_, k0 + 8 * c, K / 64)) = o; }
;     asm volatile("s_waitcnt lgkmcnt(0)" ::: "memory");
; }
	ds_write_b32 v4, v88
	ds_write_b32 v4, v89 offset:264
	ds_write_b32 v4, v90 offset:528
	ds_write_b32 v4, v91 offset:792
	ds_write_b32 v4, v92 offset:1056
	ds_write_b32 v4, v93 offset:1320
	ds_write_b32 v4, v94 offset:1584
	ds_write_b32 v4, v95 offset:1848
	ds_write_b32 v4, v96 offset:2112
	ds_write_b32 v4, v97 offset:2376
	ds_write_b32 v4, v98 offset:2640
	ds_write_b32 v4, v99 offset:2904
	ds_write_b32 v4, v100 offset:3168
	ds_write_b32 v4, v101 offset:3432
	ds_write_b32 v4, v102 offset:3696
	ds_write_b32 v4, v103 offset:3960
	ds_write_b32 v4, v104 offset:4224
	ds_write_b32 v4, v105 offset:4488
	ds_write_b32 v4, v106 offset:4752
	ds_write_b32 v4, v107 offset:5016
	ds_write_b32 v4, v108 offset:5280
	ds_write_b32 v4, v109 offset:5544
	ds_write_b32 v4, v110 offset:5808
	ds_write_b32 v4, v111 offset:6072
	ds_write_b32 v4, v112 offset:6336
	ds_write_b32 v4, v113 offset:6600
	ds_write_b32 v4, v114 offset:6864
	ds_write_b32 v4, v115 offset:7128
	ds_write_b32 v4, v116 offset:7392
	ds_write_b32 v4, v117 offset:7656
	ds_write_b32 v4, v118 offset:7920
	ds_write_b32 v4, v119 offset:8184
	s_waitcnt lgkmcnt(0)
	ds_read_b32 v48, v7
	ds_read_b32 v49, v7 offset:132
	ds_read_b32 v50, v7 offset:264
	ds_read_b32 v51, v7 offset:396
	ds_read_b32 v52, v7 offset:528
	ds_read_b32 v53, v7 offset:660
	ds_read_b32 v54, v7 offset:792
	ds_read_b32 v55, v7 offset:924
	ds_read_b32 v56, v7 offset:32
	ds_read_b32 v57, v7 offset:164
	ds_read_b32 v58, v7 offset:296
	ds_read_b32 v59, v7 offset:428
	ds_read_b32 v60, v7 offset:560
	ds_read_b32 v61, v7 offset:692
	ds_read_b32 v62, v7 offset:824
	ds_read_b32 v63, v7 offset:956
	ds_read_b32 v64, v7 offset:64
	ds_read_b32 v65, v7 offset:196
	ds_read_b32 v66, v7 offset:328
	ds_read_b32 v67, v7 offset:460
	ds_read_b32 v68, v7 offset:592
	ds_read_b32 v69, v7 offset:724
	ds_read_b32 v70, v7 offset:856
	ds_read_b32 v71, v7 offset:988
	ds_read_b32 v72, v7 offset:96
	ds_read_b32 v73, v7 offset:228
	ds_read_b32 v74, v7 offset:360
	ds_read_b32 v75, v7 offset:492
	ds_read_b32 v76, v7 offset:624
	ds_read_b32 v77, v7 offset:756
	ds_read_b32 v78, v7 offset:888
	ds_read_b32 v79, v7 offset:1020
	s_waitcnt lgkmcnt(0)
	v_mul_f32_e32 v48, v48, v120
	v_mul_f32_e32 v49, v49, v121
	v_mul_f32_e32 v50, v50, v122
	v_mul_f32_e32 v51, v51, v123
	v_mul_f32_e32 v52, v52, v124
	v_mul_f32_e32 v53, v53, v125
	v_mul_f32_e32 v54, v54, v126
	v_mul_f32_e32 v55, v55, v127
	v_cvt_pk_bf16_f32 v48, v48, v49
	v_cvt_pk_bf16_f32 v49, v50, v51
	v_cvt_pk_bf16_f32 v50, v52, v53
	v_cvt_pk_bf16_f32 v51, v54, v55
	v_mul_f32_e32 v56, v56, v120
	v_mul_f32_e32 v57, v57, v121
	v_mul_f32_e32 v58, v58, v122
	v_mul_f32_e32 v59, v59, v123
	v_mul_f32_e32 v60, v60, v124
	v_mul_f32_e32 v61, v61, v125
	v_mul_f32_e32 v62, v62, v126
	v_mul_f32_e32 v63, v63, v127
	v_cvt_pk_bf16_f32 v56, v56, v57
	v_cvt_pk_bf16_f32 v57, v58, v59
	v_cvt_pk_bf16_f32 v58, v60, v61
	v_cvt_pk_bf16_f32 v59, v62, v63
	v_mul_f32_e32 v64, v64, v120
	v_mul_f32_e32 v65, v65, v121
	v_mul_f32_e32 v66, v66, v122
	v_mul_f32_e32 v67, v67, v123
	v_mul_f32_e32 v68, v68, v124
	v_mul_f32_e32 v69, v69, v125
	v_mul_f32_e32 v70, v70, v126
	v_mul_f32_e32 v71, v71, v127
	v_cvt_pk_bf16_f32 v64, v64, v65
	v_cvt_pk_bf16_f32 v65, v66, v67
	v_cvt_pk_bf16_f32 v66, v68, v69
	v_cvt_pk_bf16_f32 v67, v70, v71
	v_mul_f32_e32 v72, v72, v120
	v_mul_f32_e32 v73, v73, v121
	v_mul_f32_e32 v74, v74, v122
	v_mul_f32_e32 v75, v75, v123
	v_mul_f32_e32 v76, v76, v124
	v_mul_f32_e32 v77, v77, v125
	v_mul_f32_e32 v78, v78, v126
	v_mul_f32_e32 v79, v79, v127
	v_cvt_pk_bf16_f32 v72, v72, v73
	v_cvt_pk_bf16_f32 v73, v74, v75
	v_cvt_pk_bf16_f32 v74, v76, v77
	v_cvt_pk_bf16_f32 v75, v78, v79
	s_cmp_lg_u32 s29, 0
	s_cbranch_scc1 .Ltcw2_rot
	global_store_dwordx4 v10, v[48:51], s[24:25]
	global_store_dwordx4 v10, v[56:59], s[24:25] offset:256
	global_store_dwordx4 v11, v[64:67], s[24:25] offset:512
	global_store_dwordx4 v11, v[72:75], s[24:25] offset:768
	s_branch .Ltcw2_done
.Ltcw2_rot:
	global_store_dwordx4 v8, v[48:51], s[24:25]
	global_store_dwordx4 v9, v[56:59], s[24:25]
	global_store_dwordx4 v8, v[64:67], s[26:27]
	global_store_dwordx4 v9, v[72:75], s[26:27]

; #define LAS __attribute__((address_space(3)))
; __device__ __forceinline__ unsigned pk2(float lo, float hi) { f32x2 f = {lo, hi}; bf16x2_t b = __builtin_convertvector(f, bf16x2_t); return __builtin_bit_cast(unsigned, b); }
; template <int MAP> __device__ __forceinline__ int rowmap(int n) {
;     if (MAP == 1) return (n >> 7) * 256 + (n & 127);
;     if (MAP == 2) return (n >> 7) * 256 + 128 + (n & 127);
;     if (MAP == 3) {
;         const bool rot = (n < 2048) || (n >= 3072 && n < 5120);
;         if (!rot) return n;
;         const int c = n & 127, i = c & 63, half = c >> 6;
;         return (n & ~127) + 32 * (i >> 4) + 8 * ((i >> 2) & 3) + 4 * half + (i & 3);
;     }
; template <int MAP, bool HASG, bool PERMW>
; __device__ __forceinline__ void tr_store(int K, int N, bf16_t* WT, LAS float* scr, int item, int lane, const float* gk) {
;     const int nblk = N / 32, kb = item / nblk, nb = item % nblk, k0 = 64 * kb, n0 = 32 * nb;
;     asm volatile("s_waitcnt lgkmcnt(0)" ::: "memory");
;     const int c = lane & 7;
;     f32x4 g0 = {1.f, 1.f, 1.f, 1.f}, g1 = {1.f, 1.f, 1.f, 1.f};
;     if (HASG) { g0 = *(const f32x4*)(gk + k0 + 8 * c); g1 = *(const f32x4*)(gk + k0 + 8 * c + 4); }
; #pragma unroll
;     for (int j = 0; j < 4; ++j) { const int n = (lane >> 3) + 8 * j; const LAS float* s = scr + (8 * c) * 33 + n;
;         u32x4 o; o.x = pk2(s[0 * 33] * g0[0], s[1 * 33] * g0[1]); o.y = pk2(s[2 * 33] * g0[2], s[3 * 33] * g0[3]); o.z = pk2(s[4 * 33] * g1[0], s[5 * 33] * g1[1]); o.w = pk2(s[6 * 33] * g1[2], s[7 * 33] * g1[3]);
;         const int wr_ = rowmap<MAP>(n0 + n), slot_ = PERMW ? ((wr_ & ~31) + invperm32(wr_ & 31)) : wr_;
;         *(u32x4*)((char*)WT + tiled_off(slot_, k0 + 8 * c, K / 64)) = o; }
;     asm volatile("s_waitcnt lgkmcnt(0)" ::: "memory");
; }
.Ltc1c_lastA:
	s_waitcnt vmcnt(0)
	ds_write_b32 v4, v16
	ds_write_b32 v4, v17 offset:264
	ds_write_b32 v4, v18 offset:528
	ds_write_b32 v4, v19 offset:792
	ds_write_b32 v4, v20 offset:1056
	ds_write_b32 v4, v21 offset:1320
	ds_write_b32 v4, v22 offset:1584
	ds_write_b32 v4, v23 offset:1848
	ds_write_b32 v4, v24 offset:2112
	ds_write_b32 v4, v25 offset:2376
	ds_write_b32 v4, v26 offset:2640
	ds_write_b32 v4, v27 offset:2904
	ds_write_b32 v4, v28 offset:3168
	ds_write_b32 v4, v29 offset:3432
	ds_write_b32 v4, v30 offset:3696
	ds_write_b32 v4, v31 offset:3960
	ds_write_b32 v4, v32 offset:4224
	ds_write_b32 v4, v33 offset:4488
	ds_write_b32 v4, v34 offset:4752
	ds_write_b32 v4, v35 offset:5016
	ds_write_b32 v4, v36 offset:5280
	ds_write_b32 v4, v37 offset:5544
	ds_write_b32 v4, v38 offset:5808
	ds_write_b32 v4, v39 offset:6072
	ds_write_b32 v4, v40 offset:6336
	ds_write_b32 v4, v41 offset:6600
	ds_write_b32 v4, v42 offset:6864
	ds_write_b32 v4, v43 offset:7128
	ds_write_b32 v4, v44 offset:7392
	ds_write_b32 v4, v45 offset:7656
	ds_write_b32 v4, v46 offset:7920
	ds_write_b32 v4, v47 offset:8184
	s_waitcnt lgkmcnt(0)
	ds_read_b32 v48, v7
	ds_read_b32 v49, v7 offset:132
	ds_read_b32 v50, v7 offset:264
	ds_read_b32 v51, v7 offset:396
	ds_read_b32 v52, v7 offset:528
	ds_read_b32 v53, v7 offset:660
	ds_read_b32 v54, v7 offset:792
	ds_read_b32 v55, v7 offset:924
	ds_read_b32 v56, v7 offset:32
	ds_read_b32 v57, v7 offset:164
	ds_read_b32 v58, v7 offset:296
	ds_read_b32 v59, v7 offset:428
	ds_read_b32 v60, v7 offset:560
	ds_read_b32 v61, v7 offset:692
	ds_read_b32 v62, v7 offset:824
	ds_read_b32 v63, v7 offset:956
	ds_read_b32 v64, v7 offset:64
	ds_read_b32 v65, v7 offset:196
	ds_read_b32 v66, v7 offset:328
	ds_read_b32 v67, v7 offset:460
	ds_read_b32 v68, v7 offset:592
	ds_read_b32 v69, v7 offset:724
	ds_read_b32 v70, v7 offset:856
	ds_read_b32 v71, v7 offset:988
	ds_read_b32 v72, v7 offset:96
	ds_read_b32 v73, v7 offset:228
	ds_read_b32 v74, v7 offset:360
	ds_read_b32 v75, v7 offset:492
	ds_read_b32 v76, v7 offset:624
	ds_read_b32 v77, v7 offset:756
	ds_read_b32 v78, v7 offset:888
	ds_read_b32 v79, v7 offset:1020
	s_waitcnt lgkmcnt(0)
	v_mul_f32_e32 v48, v48, v80
	v_mul_f32_e32 v49, v49, v81
	v_mul_f32_e32 v50, v50, v82
	v_mul_f32_e32 v51, v51, v83
	v_mul_f32_e32 v52, v52, v84
	v_mul_f32_e32 v53, v53, v85
	v_mul_f32_e32 v54, v54, v86
	v_mul_f32_e32 v55, v55, v87
	v_cvt_pk_bf16_f32 v48, v48, v49
	v_cvt_pk_bf16_f32 v49, v50, v51
	v_cvt_pk_bf16_f32 v50, v52, v53
	v_cvt_pk_bf16_f32 v51, v54, v55
	v_mul_f32_e32 v56, v56, v80
	v_mul_f32_e32 v57, v57, v81
	v_mul_f32_e32 v58, v58, v82
	v_mul_f32_e32 v59, v59, v83
	v_mul_f32_e32 v60, v60, v84
	v_mul_f32_e32 v61, v61, v85
	v_mul_f32_e32 v62, v62, v86
	v_mul_f32_e32 v63, v63, v87
	v_cvt_pk_bf16_f32 v56, v56, v57
	v_cvt_pk_bf16_f32 v57, v58, v59
	v_cvt_pk_bf16_f32 v58, v60, v61
	v_cvt_pk_bf16_f32 v59, v62, v63
	v_mul_f32_e32 v64, v64, v80
	v_mul_f32_e32 v65, v65, v81
	v_mul_f32_e32 v66, v66, v82
	v_mul_f32_e32 v67, v67, v83
	v_mul_f32_e32 v68, v68, v84
	v_mul_f32_e32 v69, v69, v85
	v_mul_f32_e32 v70, v70, v86
	v_mul_f32_e32 v71, v71, v87
	v_cvt_pk_bf16_f32 v64, v64, v65
	v_cvt_pk_bf16_f32 v65, v66, v67
	v_cvt_pk_bf16_f32 v66, v68, v69
	v_cvt_pk_bf16_f32 v67, v70, v71
	v_mul_f32_e32 v72, v72, v80
	v_mul_f32_e32 v73, v73, v81
	v_mul_f32_e32 v74, v74, v82
	v_mul_f32_e32 v75, v75, v83
	v_mul_f32_e32 v76, v76, v84
	v_mul_f32_e32 v77, v77, v85
	v_mul_f32_e32 v78, v78, v86
	v_mul_f32_e32 v79, v79, v87
	v_cvt_pk_bf16_f32 v72, v72, v73
	v_cvt_pk_bf16_f32 v73, v74, v75
	v_cvt_pk_bf16_f32 v74, v76, v77
	v_cvt_pk_bf16_f32 v75, v78, v79
	s_cmp_lg_u32 s28, 0
	s_cbranch_scc1 .Ltcw3_rot
	global_store_dwordx4 v10, v[48:51], s[16:17]
	global_store_dwordx4 v10, v[56:59], s[16:17] offset:256
	global_store_dwordx4 v11, v[64:67], s[16:17] offset:512
	global_store_dwordx4 v11, v[72:75], s[16:17] offset:768
	s_branch .Ltcw3_done

; #define LAS __attribute__((address_space(3)))
; __device__ __forceinline__ unsigned pk2(float lo, float hi) { f32x2 f = {lo, hi}; bf16x2_t b = __builtin_convertvector(f, bf16x2_t); return __builtin_bit_cast(unsigned, b); }
; template <int MAP> __device__ __forceinline__ int rowmap(int n) {
;     if (MAP == 1) return (n >> 7) * 256 + (n & 127);
;     if (MAP == 2) return (n >> 7) * 256 + 128 + (n & 127);
;     if (MAP == 3) {
;         const bool rot = (n < 2048) || (n >= 3072 && n < 5120);
;         if (!rot) return n;
;         const int c = n & 127, i = c & 63, half = c >> 6;
;         return (n & ~127) + 32 * (i >> 4) + 8 * ((i >> 2) & 3) + 4 * half + (i & 3);
;     }
; template <int MAP, bool HASG, bool PERMW>
; __device__ __forceinline__ void tr_store(int K, int N, bf16_t* WT, LAS float* scr, int item, int lane, const float* gk) {
;     const int nblk = N / 32, kb = item / nblk, nb = item % nblk, k0 = 64 * kb, n0 = 32 * nb;
;     asm volatile("s_waitcnt lgkmcnt(0)" ::: "memory");
;     const int c = lane & 7;
;     f32x4 g0 = {1.f, 1.f, 1.f, 1.f}, g1 = {1.f, 1.f, 1.f, 1.f};
;     if (HASG) { g0 = *(const f32x4*)(gk + k0 + 8 * c); g1 = *(const f32x4*)(gk + k0 + 8 * c + 4); }
; #pragma unroll
;     for (int j = 0; j < 4; ++j) { const int n = (lane >> 3) + 8 * j; const LAS float* s = scr + (8 * c) * 33 + n;
;         u32x4 o; o.x = pk2(s[0 * 33] * g0[0], s[1 * 33] * g0[1]); o.y = pk2(s[2 * 33] * g0[2], s[3 * 33] * g0[3]); o.z = pk2(s[4 * 33] * g1[0], s[5 * 33] * g1[1]); o.w = pk2(s[6 * 33] * g1[2], s[7 * 33] * g1[3]);
;         const int wr_ = rowmap<MAP>(n0 + n), slot_ = PERMW ? ((wr_ & ~31) + invperm32(wr_ & 31)) : wr_;
;         *(u32x4*)((char*)WT + tiled_off(slot_, k0 + 8 * c, K / 64)) = o; }
;     asm volatile("s_waitcnt lgkmcnt(0)" ::: "memory");
; }
.Ltc1c_lastB:
	s_waitcnt vmcnt(0)
	ds_write_b32 v4, v88
	ds_write_b32 v4, v89 offset:264
	ds_write_b32 v4, v90 offset:528
	ds_write_b32 v4, v91 offset:792
	ds_write_b32 v4, v92 offset:1056
	ds_write_b32 v4, v93 offset:1320
	ds_write_b32 v4, v94 offset:1584
	ds_write_b32 v4, v95 offset:1848
	ds_write_b32 v4, v96 offset:2112
	ds_write_b32 v4, v97 offset:2376
	ds_write_b32 v4, v98 offset:2640
	ds_write_b32 v4, v99 offset:2904
	ds_write_b32 v4, v100 offset:3168
	ds_write_b32 v4, v101 offset:3432
	ds_write_b32 v4, v102 offset:3696
	ds_write_b32 v4, v103 offset:3960
	ds_write_b32 v4, v104 offset:4224
	ds_write_b32 v4, v105 offset:4488
	ds_write_b32 v4, v106 offset:4752
	ds_write_b32 v4, v107 offset:5016
	ds_write_b32 v4, v108 offset:5280
	ds_write_b32 v4, v109 offset:5544
	ds_write_b32 v4, v110 offset:5808
	ds_write_b32 v4, v111 offset:6072
	ds_write_b32 v4, v112 offset:6336
	ds_write_b32 v4, v113 offset:6600
	ds_write_b32 v4, v114 offset:6864
	ds_write_b32 v4, v115 offset:7128
	ds_write_b32 v4, v116 offset:7392
	ds_write_b32 v4, v117 offset:7656
	ds_write_b32 v4, v118 offset:7920
	ds_write_b32 v4, v119 offset:8184
	s_waitcnt lgkmcnt(0)
	ds_read_b32 v48, v7
	ds_read_b32 v49, v7 offset:132
	ds_read_b32 v50, v7 offset:264
	ds_read_b32 v51, v7 offset:396
	ds_read_b32 v52, v7 offset:528
	ds_read_b32 v53, v7 offset:660
	ds_read_b32 v54, v7 offset:792
	ds_read_b32 v55, v7 offset:924
	ds_read_b32 v56, v7 offset:32
	ds_read_b32 v57, v7 offset:164
	ds_read_b32 v58, v7 offset:296
	ds_read_b32 v59, v7 offset:428
	ds_read_b32 v60, v7 offset:560
	ds_read_b32 v61, v7 offset:692
	ds_read_b32 v62, v7 offset:824
	ds_read_b32 v63, v7 offset:956
	ds_read_b32 v64, v7 offset:64
	ds_read_b32 v65, v7 offset:196
	ds_read_b32 v66, v7 offset:328
	ds_read_b32 v67, v7 offset:460
	ds_read_b32 v68, v7 offset:592
	ds_read_b32 v69, v7 offset:724
	ds_read_b32 v70, v7 offset:856
	ds_read_b32 v71, v7 offset:988
	ds_read_b32 v72, v7 offset:96
	ds_read_b32 v73, v7 offset:228
	ds_read_b32 v74, v7 offset:360
	ds_read_b32 v75, v7 offset:492
	ds_read_b32 v76, v7 offset:624
	ds_read_b32 v77, v7 offset:756
	ds_read_b32 v78, v7 offset:888
	ds_read_b32 v79, v7 offset:1020
	s_waitcnt lgkmcnt(0)
	v_mul_f32_e32 v48, v48, v120
	v_mul_f32_e32 v49, v49, v121
	v_mul_f32_e32 v50, v50, v122
	v_mul_f32_e32 v51, v51, v123
	v_mul_f32_e32 v52, v52, v124
	v_mul_f32_e32 v53, v53, v125
	v_mul_f32_e32 v54, v54, v126
	v_mul_f32_e32 v55, v55, v127
	v_cvt_pk_bf16_f32 v48, v48, v49
	v_cvt_pk_bf16_f32 v49, v50, v51
	v_cvt_pk_bf16_f32 v50, v52, v53
	v_cvt_pk_bf16_f32 v51, v54, v55
	v_mul_f32_e32 v56, v56, v120
	v_mul_f32_e32 v57, v57, v121
	v_mul_f32_e32 v58, v58, v122
	v_mul_f32_e32 v59, v59, v123
	v_mul_f32_e32 v60, v60, v124
	v_mul_f32_e32 v61, v61, v125
	v_mul_f32_e32 v62, v62, v126
	v_mul_f32_e32 v63, v63, v127
	v_cvt_pk_bf16_f32 v56, v56, v57
	v_cvt_pk_bf16_f32 v57, v58, v59
	v_cvt_pk_bf16_f32 v58, v60, v61
	v_cvt_pk_bf16_f32 v59, v62, v63
	v_mul_f32_e32 v64, v64, v120
	v_mul_f32_e32 v65, v65, v121
	v_mul_f32_e32 v66, v66, v122
	v_mul_f32_e32 v67, v67, v123
	v_mul_f32_e32 v68, v68, v124
	v_mul_f32_e32 v69, v69, v125
	v_mul_f32_e32 v70, v70, v126
	v_mul_f32_e32 v71, v71, v127
	v_cvt_pk_bf16_f32 v64, v64, v65
	v_cvt_pk_bf16_f32 v65, v66, v67
	v_cvt_pk_bf16_f32 v66, v68, v69
	v_cvt_pk_bf16_f32 v67, v70, v71
	v_mul_f32_e32 v72, v72, v120
	v_mul_f32_e32 v73, v73, v121
	v_mul_f32_e32 v74, v74, v122
	v_mul_f32_e32 v75, v75, v123
	v_mul_f32_e32 v76, v76, v124
	v_mul_f32_e32 v77, v77, v125
	v_mul_f32_e32 v78, v78, v126
	v_mul_f32_e32 v79, v79, v127
	v_cvt_pk_bf16_f32 v72, v72, v73
	v_cvt_pk_bf16_f32 v73, v74, v75
	v_cvt_pk_bf16_f32 v74, v76, v77
	v_cvt_pk_bf16_f32 v75, v78, v79
	s_cmp_lg_u32 s29, 0
	s_cbranch_scc1 .Ltcw4_rot
	global_store_dwordx4 v10, v[48:51], s[24:25]
	global_store_dwordx4 v10, v[56:59], s[24:25] offset:256
	global_store_dwordx4 v11, v[64:67], s[24:25] offset:512
	global_store_dwordx4 v11, v[72:75], s[24:25] offset:768
	s_branch .Ltcw4_done

; __global__ void __launch_bounds__(512, 2) mega_fwd(Params p) {
;     ...
;             transpose_mat<1, true, true>(p.in[2] + (size_t)l * D * DFF, D, DFF, P_W(WS_WGU1), scr, gw, ngw, lane, p.in[1] + l * D);
;             transpose_mat<2, true, true>(p.in[3] + (size_t)l * D * DFF, D, DFF, P_W(WS_WGU1), scr, gw, ngw, lane, p.in[1] + l * D);
;             transpose_mat<0>(p.in[4] + (size_t)l * DFF * D, DFF, D, P_W(WS_WD1), scr, gw, ngw, lane);
;             transpose_mat<3, true, true>(p.in[6] + (size_t)l * D * INW, D, INW, P_W(WS_WIN), scr, gw, ngw, lane, p.in[5] + l * D);
;             transpose_mat<0, false, true>(p.in[7] + (size_t)l * 1024 * D, 1024, D, P_W(WS_WA), scr, gw, ngw, lane);
;             transpose_mat<0, false, true>(p.in[8] + (size_t)l * 2048 * D, 2048, D, P_W(WS_WB), scr, gw, ngw, lane);
;             transpose_mat<0>(p.in[9] + (size_t)l * D * D, D, D, P_W(WS_WO), scr, gw, ngw, lane);
;             transpose_mat<1, true, true>(p.in[11] + (size_t)l * D * DFF, D, DFF, P_W(WS_WGU2), scr, gw, ngw, lane, p.in[10] + l * D);
;             transpose_mat<2, true, true>(p.in[12] + (size_t)l * D * DFF, D, DFF, P_W(WS_WGU2), scr, gw, ngw, lane, p.in[10] + l * D);
;             transpose_mat<0>(p.in[13] + (size_t)l * DFF * D, DFF, D, P_W(WS_WD2), scr, gw, ngw, lane);
.Ltcw4_done:
.Ltc1c_exit:
	v_readlane_b32 s4, v255, 24
	v_readlane_b32 s5, v255, 25
	v_readlane_b32 s6, v255, 26
	v_readlane_b32 s7, v255, 27
	v_readlane_b32 s8, v255, 28
	v_readlane_b32 s9, v255, 29
	v_readlane_b32 s10, v255, 30
	v_readlane_b32 s11, v255, 31
	v_readlane_b32 s12, v255, 32
	v_readlane_b32 s13, v255, 33
	v_readlane_b32 s14, v255, 34
	v_readlane_b32 s15, v255, 35
	v_readlane_b32 s16, v255, 36
	v_readlane_b32 s17, v255, 37
	v_readlane_b32 s18, v255, 38
	v_readlane_b32 s19, v255, 39
	v_readlane_b32 s20, v255, 40
	v_readlane_b32 s21, v255, 41
	v_readlane_b32 s22, v255, 42
	v_readlane_b32 s23, v255, 43
	v_readlane_b32 s24, v255, 44
	v_readlane_b32 s25, v255, 45
	v_readlane_b32 s26, v255, 46
	v_readlane_b32 s27, v255, 47
	v_readlane_b32 s28, v255, 48
	v_readlane_b32 s29, v255, 49
	s_nop 3

; #define LAS __attribute__((address_space(3)))
; __device__ __forceinline__ unsigned pk2(float lo, float hi) { f32x2 f = {lo, hi}; bf16x2_t b = __builtin_convertvector(f, bf16x2_t); return __builtin_bit_cast(unsigned, b); }
; __device__ __forceinline__ void tr_load(const float* W, int N, int item, int lane, float (&wv)[32]) {
;     const int nblk = N / 32, kb = item / nblk, nb = item % nblk, k0 = 64 * kb, n0 = 32 * nb;
; #pragma unroll
;     for (int i = 0; i < 32; ++i) { const int kk = 2 * i + (lane >> 5); wv[i] = __builtin_nontemporal_load(W + (size_t)(k0 + kk) * N + n0 + (lane & 31)); }
; }
; template <int MAP, bool HASG, bool PERMW>
; __device__ __forceinline__ void tr_store(int K, int N, bf16_t* WT, LAS float* scr, int item, int lane, const float* gk) {
;     const int nblk = N / 32, kb = item / nblk, nb = item % nblk, k0 = 64 * kb, n0 = 32 * nb;
;     asm volatile("s_waitcnt lgkmcnt(0)" ::: "memory");
;     const int c = lane & 7;
;     f32x4 g0 = {1.f, 1.f, 1.f, 1.f}, g1 = {1.f, 1.f, 1.f, 1.f};
;     if (HASG) { g0 = *(const f32x4*)(gk + k0 + 8 * c); g1 = *(const f32x4*)(gk + k0 + 8 * c + 4); }
; #pragma unroll
;     for (int j = 0; j < 4; ++j) { const int n = (lane >> 3) + 8 * j; const LAS float* s = scr + (8 * c) * 33 + n;
;         u32x4 o; o.x = pk2(s[0 * 33] * g0[0], s[1 * 33] * g0[1]); o.y = pk2(s[2 * 33] * g0[2], s[3 * 33] * g0[3]); o.z = pk2(s[4 * 33] * g1[0], s[5 * 33] * g1[1]); o.w = pk2(s[6 * 33] * g1[2], s[7 * 33] * g1[3]);
;         const int wr_ = rowmap<MAP>(n0 + n), slot_ = PERMW ? ((wr_ & ~31) + invperm32(wr_ & 31)) : wr_;
;         *(u32x4*)((char*)WT + tiled_off(slot_, k0 + 8 * c, K / 64)) = o; }
; __global__ void __launch_bounds__(512, 2) mega_fwd(Params p) {
;     ...
;             transpose_mat<0, false, true>(p.in[7] + (size_t)l * 1024 * D, 1024, D, P_W(WS_WA), scr, gw, ngw, lane);
.LBB0_378:
	s_cmpk_lt_u32 s2, 0x80
	s_cbranch_scc1 .Ltc3_done
	v_writelane_b32 v255, s4, 24
	v_writelane_b32 v255, s5, 25
	v_writelane_b32 v255, s6, 26
	v_writelane_b32 v255, s7, 27
	v_writelane_b32 v255, s8, 28
	v_writelane_b32 v255, s9, 29
	v_writelane_b32 v255, s10, 30
	v_writelane_b32 v255, s11, 31
	v_writelane_b32 v255, s12, 32
	v_writelane_b32 v255, s13, 33
	v_writelane_b32 v255, s14, 34
	v_writelane_b32 v255, s15, 35
	v_writelane_b32 v255, s16, 36
	v_writelane_b32 v255, s17, 37
	v_writelane_b32 v255, s18, 38
	v_writelane_b32 v255, s19, 39
	v_writelane_b32 v255, s20, 40
	v_writelane_b32 v255, s21, 41
	v_writelane_b32 v255, s22, 42
	v_writelane_b32 v255, s23, 43
	v_writelane_b32 v255, s24, 44
	v_writelane_b32 v255, s25, 45
	v_writelane_b32 v255, s26, 46
	v_writelane_b32 v255, s27, 47
	v_writelane_b32 v255, s28, 48
	v_writelane_b32 v255, s29, 49
	v_readfirstlane_b32 s8, v234
	s_nop 3
	s_lshr_b32 s8, s8, 6
	s_sub_u32 s18, s2, 0x80
	s_lshl_b32 s18, s18, 3
	s_add_u32 s18, s18, s8
	s_mul_i32 s10, s8, 0x2100
	v_and_b32_e32 v0, 63, v234
	v_and_b32_e32 v1, 31, v0
	v_lshrrev_b32_e32 v2, 5, v0
	v_lshlrev_b32_e32 v3, 13, v2
	v_lshl_add_u32 v3, v1, 2, v3
	v_mul_u32_u24_e32 v4, 33, v2
	v_add_u32_e32 v4, v4, v1
	v_lshl_add_u32 v4, v4, 2, s10
	v_and_b32_e32 v5, 7, v0
	v_lshrrev_b32_e32 v6, 3, v0
	v_mul_u32_u24_e32 v7, 0x108, v5
	v_add_u32_e32 v7, v7, v6
	v_lshl_add_u32 v7, v7, 2, s10
	v_lshrrev_b32_e32 v12, 2, v5
	v_lshlrev_b32_e32 v12, 10, v12
	v_and_b32_e32 v13, 3, v5
	v_lshl_add_u32 v12, v13, 4, v12
	v_lshl_add_u32 v8, v6, 6, v12
	v_xor_b32_e32 v9, 32, v8
	v_add_u32_e32 v9, 0x200, v9
	v_and_b32_e32 v13, 3, v6
	v_lshl_add_u32 v10, v13, 6, v12
	v_bfe_u32 v13, v6, 2, 1
	v_lshl_add_u32 v10, v13, 11, v10
	v_xor_b32_e32 v11, 32, v10
	v_lshlrev_b32_e32 v14, 5, v5
	v_mul_u32_u24_e32 v15, 0x5800, v2
	v_lshl_add_u32 v15, v1, 2, v15
	v_mul_u32_u24_e32 v12, 0xd000, v2
	v_lshl_add_u32 v12, v1, 2, v12
	v_readlane_b32 s4, v255, 10
	v_readlane_b32 s5, v255, 11
	s_nop 3
	s_and_b32 s6, s60, 0x800000
	s_add_u32 s4, s4, s6
	s_addc_u32 s5, s5, 0
	s_add_u32 s6, s76, 0x7600000
	s_addc_u32 s7, s77, 0
	s_mov_b32 s9, s18
	s_cmpk_ge_u32 s9, 0x400
	s_cbranch_scc1 .Ltc3a_exit
	s_lshr_b32 s11, s9, 6
	s_and_b32 s12, s9, 63
	s_lshl_b32 s13, s11, 19
	s_lshl_b32 s14, s12, 7
	s_add_u32 s13, s13, s14
	s_add_u32 s14, s4, s13
	s_addc_u32 s15, s5, 0
	global_load_dword v16, v3, s[14:15] nt
	s_add_u32 s14, s14, 0x4000
	s_addc_u32 s15, s15, 0
	global_load_dword v17, v3, s[14:15] nt
	s_add_u32 s14, s14, 0x4000
	s_addc_u32 s15, s15, 0
	global_load_dword v18, v3, s[14:15] nt
	s_add_u32 s14, s14, 0x4000
	s_addc_u32 s15, s15, 0
	global_load_dword v19, v3, s[14:15] nt
	s_add_u32 s14, s14, 0x4000
	s_addc_u32 s15, s15, 0
	global_load_dword v20, v3, s[14:15] nt
	s_add_u32 s14, s14, 0x4000
	s_addc_u32 s15, s15, 0
	global_load_dword v21, v3, s[14:15] nt
	s_add_u32 s14, s14, 0x4000
	s_addc_u32 s15, s15, 0
	global_load_dword v22, v3, s[14:15] nt
	s_add_u32 s14, s14, 0x4000
	s_addc_u32 s15, s15, 0
	global_load_dword v23, v3, s[14:15] nt
	s_add_u32 s14, s14, 0x4000
	s_addc_u32 s15, s15, 0
	global_load_dword v24, v3, s[14:15] nt
	s_add_u32 s14, s14, 0x4000
	s_addc_u32 s15, s15, 0
	global_load_dword v25, v3, s[14:15] nt
	s_add_u32 s14, s14, 0x4000
	s_addc_u32 s15, s15, 0
	global_load_dword v26, v3, s[14:15] nt
	s_add_u32 s14, s14, 0x4000
	s_addc_u32 s15, s15, 0
	global_load_dword v27, v3, s[14:15] nt
	s_add_u32 s14, s14, 0x4000
	s_addc_u32 s15, s15, 0
	global_load_dword v28, v3, s[14:15] nt
	s_add_u32 s14, s14, 0x4000
	s_addc_u32 s15, s15, 0
	global_load_dword v29, v3, s[14:15] nt
	s_add_u32 s14, s14, 0x4000
	s_addc_u32 s15, s15, 0
	global_load_dword v30, v3, s[14:15] nt
	s_add_u32 s14, s14, 0x4000
	s_addc_u32 s15, s15, 0
	global_load_dword v31, v3, s[14:15] nt
	s_add_u32 s14, s14, 0x4000
	s_addc_u32 s15, s15, 0
	global_load_dword v32, v3, s[14:15] nt
	s_add_u32 s14, s14, 0x4000
	s_addc_u32 s15, s15, 0
	global_load_dword v33, v3, s[14:15] nt
	s_add_u32 s14, s14, 0x4000
	s_addc_u32 s15, s15, 0
	global_load_dword v34, v3, s[14:15] nt
	s_add_u32 s14, s14, 0x4000
	s_addc_u32 s15, s15, 0
	global_load_dword v35, v3, s[14:15] nt
	s_add_u32 s14, s14, 0x4000
	s_addc_u32 s15, s15, 0
	global_load_dword v36, v3, s[14:15] nt
	s_add_u32 s14, s14, 0x4000
	s_addc_u32 s15, s15, 0
	global_load_dword v37, v3, s[14:15] nt
	s_add_u32 s14, s14, 0x4000
	s_addc_u32 s15, s15, 0
	global_load_dword v38, v3, s[14:15] nt
	s_add_u32 s14, s14, 0x4000
	s_addc_u32 s15, s15, 0
	global_load_dword v39, v3, s[14:15] nt
	s_add_u32 s14, s14, 0x4000
	s_addc_u32 s15, s15, 0
	global_load_dword v40, v3, s[14:15] nt
	s_add_u32 s14, s14, 0x4000
	s_addc_u32 s15, s15, 0
	global_load_dword v41, v3, s[14:15] nt
	s_add_u32 s14, s14, 0x4000
	s_addc_u32 s15, s15, 0
	global_load_dword v42, v3, s[14:15] nt
	s_add_u32 s14, s14, 0x4000
	s_addc_u32 s15, s15, 0
	global_load_dword v43, v3, s[14:15] nt
	s_add_u32 s14, s14, 0x4000
	s_addc_u32 s15, s15, 0
	global_load_dword v44, v3, s[14:15] nt
	s_add_u32 s14, s14, 0x4000
	s_addc_u32 s15, s15, 0
	global_load_dword v45, v3, s[14:15] nt
	s_add_u32 s14, s14, 0x4000
	s_addc_u32 s15, s15, 0
	global_load_dword v46, v3, s[14:15] nt
	s_add_u32 s14, s14, 0x4000
	s_addc_u32 s15, s15, 0
	global_load_dword v47, v3, s[14:15] nt
	s_lshr_b32 s16, s12, 2
	s_mul_i32 s16, s16, 0x10
	s_add_u32 s16, s16, s11
	s_lshl_b32 s16, s16, 14
	s_and_b32 s17, s12, 3
	s_lshl_b32 s17, s17, 12
	s_add_u32 s16, s16, s17
	s_add_u32 s16, s6, s16
	s_addc_u32 s17, s7, 0
; __device__ __forceinline__ void tr_load(const float* W, int N, int item, int lane, float (&wv)[32]) {
;     const int nblk = N / 32, kb = item / nblk, nb = item % nblk, k0 = 64 * kb, n0 = 32 * nb;
; #pragma unroll
;     for (int i = 0; i < 32; ++i) { const int kk = 2 * i + (lane >> 5); wv[i] = __builtin_nontemporal_load(W + (size_t)(k0 + kk) * N + n0 + (lane & 31)); }
; }
; template <int MAP, bool HASG, bool PERMW>
; __device__ __forceinline__ void tr_store(int K, int N, bf16_t* WT, LAS float* scr, int item, int lane, const float* gk) {
;     const int nblk = N / 32, kb = item / nblk, nb = item % nblk, k0 = 64 * kb, n0 = 32 * nb;
;     asm volatile("s_waitcnt lgkmcnt(0)" ::: "memory");
;     const int c = lane & 7;
;     f32x4 g0 = {1.f, 1.f, 1.f, 1.f}, g1 = {1.f, 1.f, 1.f, 1.f};
;     if (HASG) { g0 = *(const f32x4*)(gk + k0 + 8 * c); g1 = *(const f32x4*)(gk + k0 + 8 * c + 4); }
; #pragma unroll
;     for (int j = 0; j < 4; ++j) { const int n = (lane >> 3) + 8 * j; const LAS float* s = scr + (8 * c) * 33 + n;
;         u32x4 o; o.x = pk2(s[0 * 33] * g0[0], s[1 * 33] * g0[1]); o.y = pk2(s[2 * 33] * g0[2], s[3 * 33] * g0[3]); o.z = pk2(s[4 * 33] * g1[0], s[5 * 33] * g1[1]); o.w = pk2(s[6 * 33] * g1[2], s[7 * 33] * g1[3]);
;         const int wr_ = rowmap<MAP>(n0 + n), slot_ = PERMW ? ((wr_ & ~31) + invperm32(wr_ & 31)) : wr_;
;         *(u32x4*)((char*)WT + tiled_off(slot_, k0 + 8 * c, K / 64)) = o; }
;     asm volatile("s_waitcnt lgkmcnt(0)" ::: "memory");
; }
; template <int MAP, bool HASG = false, bool PERMW = false>
; __device__ __forceinline__ void transpose_mat(const float* W, int K, int N, bf16_t* WT, LAS float* scr, int gw, int ngw, int lane, const float* gk = nullptr) {
;     const int nitems = (K / 64) * (N / 32);
;     int it = gw;
;     if (it >= nitems) return;
;     float wv[32];
;     tr_load(W, N, it, lane, wv);
;     for (;;) {
;         __builtin_amdgcn_sched_barrier(0);
; #pragma unroll
;         for (int i = 0; i < 32; ++i) { const int kk = 2 * i + (lane >> 5); scr[kk * 33 + (lane & 31)] = wv[i]; }
;         __builtin_amdgcn_sched_barrier(0);
;         const int nx = it + ngw;
;         if (nx < nitems) tr_load(W, N, nx, lane, wv);
;         __builtin_amdgcn_sched_barrier(0);
;         tr_store<MAP, HASG, PERMW>(K, N, WT, scr, it, lane, gk);
;         if (nx >= nitems) break;
;         it = nx;
.Ltc3a_loop:
	s_add_u32 s9, s9, 0x400
	s_cmpk_ge_u32 s9, 0x400
	s_cbranch_scc1 .Ltc3a_lastA
	s_lshr_b32 s11, s9, 6
	s_and_b32 s12, s9, 63
	s_lshl_b32 s13, s11, 19
	s_lshl_b32 s14, s12, 7
	s_add_u32 s13, s13, s14
	s_add_u32 s14, s4, s13
	s_addc_u32 s15, s5, 0
	global_load_dword v88, v3, s[14:15] nt
	s_add_u32 s14, s14, 0x4000
	s_addc_u32 s15, s15, 0
	global_load_dword v89, v3, s[14:15] nt
	s_add_u32 s14, s14, 0x4000
	s_addc_u32 s15, s15, 0
	global_load_dword v90, v3, s[14:15] nt
	s_add_u32 s14, s14, 0x4000
	s_addc_u32 s15, s15, 0
	global_load_dword v91, v3, s[14:15] nt
	s_add_u32 s14, s14, 0x4000
	s_addc_u32 s15, s15, 0
	global_load_dword v92, v3, s[14:15] nt
	s_add_u32 s14, s14, 0x4000
	s_addc_u32 s15, s15, 0
	global_load_dword v93, v3, s[14:15] nt
	s_add_u32 s14, s14, 0x4000
	s_addc_u32 s15, s15, 0
	global_load_dword v94, v3, s[14:15] nt
	s_add_u32 s14, s14, 0x4000
	s_addc_u32 s15, s15, 0
	global_load_dword v95, v3, s[14:15] nt
	s_add_u32 s14, s14, 0x4000
	s_addc_u32 s15, s15, 0
	global_load_dword v96, v3, s[14:15] nt
	s_add_u32 s14, s14, 0x4000
	s_addc_u32 s15, s15, 0
	global_load_dword v97, v3, s[14:15] nt
	s_add_u32 s14, s14, 0x4000
	s_addc_u32 s15, s15, 0
	global_load_dword v98, v3, s[14:15] nt
	s_add_u32 s14, s14, 0x4000
	s_addc_u32 s15, s15, 0
	global_load_dword v99, v3, s[14:15] nt
	s_add_u32 s14, s14, 0x4000
	s_addc_u32 s15, s15, 0
	global_load_dword v100, v3, s[14:15] nt
	s_add_u32 s14, s14, 0x4000
	s_addc_u32 s15, s15, 0
	global_load_dword v101, v3, s[14:15] nt
	s_add_u32 s14, s14, 0x4000
	s_addc_u32 s15, s15, 0
	global_load_dword v102, v3, s[14:15] nt
	s_add_u32 s14, s14, 0x4000
	s_addc_u32 s15, s15, 0
	global_load_dword v103, v3, s[14:15] nt
	s_add_u32 s14, s14, 0x4000
	s_addc_u32 s15, s15, 0
	global_load_dword v104, v3, s[14:15] nt
	s_add_u32 s14, s14, 0x4000
	s_addc_u32 s15, s15, 0
	global_load_dword v105, v3, s[14:15] nt
	s_add_u32 s14, s14, 0x4000
	s_addc_u32 s15, s15, 0
	global_load_dword v106, v3, s[14:15] nt
	s_add_u32 s14, s14, 0x4000
	s_addc_u32 s15, s15, 0
	global_load_dword v107, v3, s[14:15] nt
	s_add_u32 s14, s14, 0x4000
	s_addc_u32 s15, s15, 0
	global_load_dword v108, v3, s[14:15] nt
	s_add_u32 s14, s14, 0x4000
	s_addc_u32 s15, s15, 0
	global_load_dword v109, v3, s[14:15] nt
	s_add_u32 s14, s14, 0x4000
	s_addc_u32 s15, s15, 0
	global_load_dword v110, v3, s[14:15] nt
	s_add_u32 s14, s14, 0x4000
	s_addc_u32 s15, s15, 0
	global_load_dword v111, v3, s[14:15] nt
	s_add_u32 s14, s14, 0x4000
	s_addc_u32 s15, s15, 0
	global_load_dword v112, v3, s[14:15] nt
	s_add_u32 s14, s14, 0x4000
	s_addc_u32 s15, s15, 0
	global_load_dword v113, v3, s[14:15] nt
	s_add_u32 s14, s14, 0x4000
	s_addc_u32 s15, s15, 0
	global_load_dword v114, v3, s[14:15] nt
	s_add_u32 s14, s14, 0x4000
	s_addc_u32 s15, s15, 0
	global_load_dword v115, v3, s[14:15] nt
	s_add_u32 s14, s14, 0x4000
	s_addc_u32 s15, s15, 0
	global_load_dword v116, v3, s[14:15] nt
	s_add_u32 s14, s14, 0x4000
	s_addc_u32 s15, s15, 0
	global_load_dword v117, v3, s[14:15] nt
	s_add_u32 s14, s14, 0x4000
	s_addc_u32 s15, s15, 0
	global_load_dword v118, v3, s[14:15] nt
	s_add_u32 s14, s14, 0x4000
	s_addc_u32 s15, s15, 0
	global_load_dword v119, v3, s[14:15] nt
	s_lshr_b32 s24, s12, 2
	s_mul_i32 s24, s24, 0x10
	s_add_u32 s24, s24, s11
	s_lshl_b32 s24, s24, 14
	s_and_b32 s25, s12, 3
	s_lshl_b32 s25, s25, 12
	s_add_u32 s24, s24, s25
	s_add_u32 s24, s6, s24
	s_addc_u32 s25, s7, 0
	s_waitcnt vmcnt(32)
	ds_write_b32 v4, v16
	ds_write_b32 v4, v17 offset:264
	ds_write_b32 v4, v18 offset:528
	ds_write_b32 v4, v19 offset:792
	ds_write_b32 v4, v20 offset:1056
	ds_write_b32 v4, v21 offset:1320
	ds_write_b32 v4, v22 offset:1584
	ds_write_b32 v4, v23 offset:1848
	ds_write_b32 v4, v24 offset:2112
	ds_write_b32 v4, v25 offset:2376
	ds_write_b32 v4, v26 offset:2640
	ds_write_b32 v4, v27 offset:2904
	ds_write_b32 v4, v28 offset:3168
	ds_write_b32 v4, v29 offset:3432
	ds_write_b32 v4, v30 offset:3696
	ds_write_b32 v4, v31 offset:3960
	ds_write_b32 v4, v32 offset:4224
	ds_write_b32 v4, v33 offset:4488
	ds_write_b32 v4, v34 offset:4752
	ds_write_b32 v4, v35 offset:5016
	ds_write_b32 v4, v36 offset:5280
	ds_write_b32 v4, v37 offset:5544
	ds_write_b32 v4, v38 offset:5808
	ds_write_b32 v4, v39 offset:6072
	ds_write_b32 v4, v40 offset:6336
	ds_write_b32 v4, v41 offset:6600
	ds_write_b32 v4, v42 offset:6864
	ds_write_b32 v4, v43 offset:7128
	ds_write_b32 v4, v44 offset:7392
	ds_write_b32 v4, v45 offset:7656
	ds_write_b32 v4, v46 offset:7920
	ds_write_b32 v4, v47 offset:8184
	s_waitcnt lgkmcnt(0)
	ds_read_b32 v48, v7
	ds_read_b32 v49, v7 offset:132
	ds_read_b32 v50, v7 offset:264
	ds_read_b32 v51, v7 offset:396
	ds_read_b32 v52, v7 offset:528
	ds_read_b32 v53, v7 offset:660
	ds_read_b32 v54, v7 offset:792
	ds_read_b32 v55, v7 offset:924
	ds_read_b32 v56, v7 offset:32
	ds_read_b32 v57, v7 offset:164
	ds_read_b32 v58, v7 offset:296
	ds_read_b32 v59, v7 offset:428
	ds_read_b32 v60, v7 offset:560
	ds_read_b32 v61, v7 offset:692
	ds_read_b32 v62, v7 offset:824
	ds_read_b32 v63, v7 offset:956
	ds_read_b32 v64, v7 offset:64
	ds_read_b32 v65, v7 offset:196
	ds_read_b32 v66, v7 offset:328
	ds_read_b32 v67, v7 offset:460
	ds_read_b32 v68, v7 offset:592
	ds_read_b32 v69, v7 offset:724
	ds_read_b32 v70, v7 offset:856
	ds_read_b32 v71, v7 offset:988
	ds_read_b32 v72, v7 offset:96
	ds_read_b32 v73, v7 offset:228
	ds_read_b32 v74, v7 offset:360
	ds_read_b32 v75, v7 offset:492
	ds_read_b32 v76, v7 offset:624
	ds_read_b32 v77, v7 offset:756
	ds_read_b32 v78, v7 offset:888
	ds_read_b32 v79, v7 offset:1020
	s_waitcnt lgkmcnt(0)
	v_cvt_pk_bf16_f32 v48, v48, v49
	v_cvt_pk_bf16_f32 v49, v50, v51
	v_cvt_pk_bf16_f32 v50, v52, v53
	v_cvt_pk_bf16_f32 v51, v54, v55
	global_store_dwordx4 v10, v[48:51], s[16:17]
	v_cvt_pk_bf16_f32 v56, v56, v57
	v_cvt_pk_bf16_f32 v57, v58, v59
	v_cvt_pk_bf16_f32 v58, v60, v61
	v_cvt_pk_bf16_f32 v59, v62, v63
	global_store_dwordx4 v10, v[56:59], s[16:17] offset:256
	v_cvt_pk_bf16_f32 v64, v64, v65
	v_cvt_pk_bf16_f32 v65, v66, v67
	v_cvt_pk_bf16_f32 v66, v68, v69
	v_cvt_pk_bf16_f32 v67, v70, v71
	global_store_dwordx4 v11, v[64:67], s[16:17] offset:512
	v_cvt_pk_bf16_f32 v72, v72, v73
	v_cvt_pk_bf16_f32 v73, v74, v75
	v_cvt_pk_bf16_f32 v74, v76, v77
	v_cvt_pk_bf16_f32 v75, v78, v79
	global_store_dwordx4 v11, v[72:75], s[16:17] offset:768
	s_add_u32 s9, s9, 0x400
	s_cmpk_ge_u32 s9, 0x400
	s_cbranch_scc1 .Ltc3a_lastB
; __device__ __forceinline__ void tr_load(const float* W, int N, int item, int lane, float (&wv)[32]) {
;     const int nblk = N / 32, kb = item / nblk, nb = item % nblk, k0 = 64 * kb, n0 = 32 * nb;
; #pragma unroll
;     for (int i = 0; i < 32; ++i) { const int kk = 2 * i + (lane >> 5); wv[i] = __builtin_nontemporal_load(W + (size_t)(k0 + kk) * N + n0 + (lane & 31)); }
; }
; template <int MAP, bool HASG, bool PERMW>
; __device__ __forceinline__ void tr_store(int K, int N, bf16_t* WT, LAS float* scr, int item, int lane, const float* gk) {
;     const int nblk = N / 32, kb = item / nblk, nb = item % nblk, k0 = 64 * kb, n0 = 32 * nb;
;     asm volatile("s_waitcnt lgkmcnt(0)" ::: "memory");
;     const int c = lane & 7;
;     f32x4 g0 = {1.f, 1.f, 1.f, 1.f}, g1 = {1.f, 1.f, 1.f, 1.f};
;     if (HASG) { g0 = *(const f32x4*)(gk + k0 + 8 * c); g1 = *(const f32x4*)(gk + k0 + 8 * c + 4); }
; #pragma unroll
;     for (int j = 0; j < 4; ++j) { const int n = (lane >> 3) + 8 * j; const LAS float* s = scr + (8 * c) * 33 + n;
;         u32x4 o; o.x = pk2(s[0 * 33] * g0[0], s[1 * 33] * g0[1]); o.y = pk2(s[2 * 33] * g0[2], s[3 * 33] * g0[3]); o.z = pk2(s[4 * 33] * g1[0], s[5 * 33] * g1[1]); o.w = pk2(s[6 * 33] * g1[2], s[7 * 33] * g1[3]);
;         const int wr_ = rowmap<MAP>(n0 + n), slot_ = PERMW ? ((wr_ & ~31) + invperm32(wr_ & 31)) : wr_;
;         *(u32x4*)((char*)WT + tiled_off(slot_, k0 + 8 * c, K / 64)) = o; }
;     asm volatile("s_waitcnt lgkmcnt(0)" ::: "memory");
; }
; template <int MAP, bool HASG = false, bool PERMW = false>
; __device__ __forceinline__ void transpose_mat(const float* W, int K, int N, bf16_t* WT, LAS float* scr, int gw, int ngw, int lane, const float* gk = nullptr) {
;     const int nitems = (K / 64) * (N / 32);
;     int it = gw;
;     if (it >= nitems) return;
;     float wv[32];
;     tr_load(W, N, it, lane, wv);
;     for (;;) {
;         __builtin_amdgcn_sched_barrier(0);
; #pragma unroll
;         for (int i = 0; i < 32; ++i) { const int kk = 2 * i + (lane >> 5); scr[kk * 33 + (lane & 31)] = wv[i]; }
;         __builtin_amdgcn_sched_barrier(0);
;         const int nx = it + ngw;
;         if (nx < nitems) tr_load(W, N, nx, lane, wv);
;         __builtin_amdgcn_sched_barrier(0);
;         tr_store<MAP, HASG, PERMW>(K, N, WT, scr, it, lane, gk);
;         if (nx >= nitems) break;
;         it = nx;
	s_lshr_b32 s11, s9, 6
	s_and_b32 s12, s9, 63
	s_lshl_b32 s13, s11, 19
	s_lshl_b32 s14, s12, 7
	s_add_u32 s13, s13, s14
	s_add_u32 s14, s4, s13
	s_addc_u32 s15, s5, 0
	global_load_dword v16, v3, s[14:15] nt
	s_add_u32 s14, s14, 0x4000
	s_addc_u32 s15, s15, 0
	global_load_dword v17, v3, s[14:15] nt
	s_add_u32 s14, s14, 0x4000
	s_addc_u32 s15, s15, 0
	global_load_dword v18, v3, s[14:15] nt
	s_add_u32 s14, s14, 0x4000
	s_addc_u32 s15, s15, 0
	global_load_dword v19, v3, s[14:15] nt
	s_add_u32 s14, s14, 0x4000
	s_addc_u32 s15, s15, 0
	global_load_dword v20, v3, s[14:15] nt
	s_add_u32 s14, s14, 0x4000
	s_addc_u32 s15, s15, 0
	global_load_dword v21, v3, s[14:15] nt
	s_add_u32 s14, s14, 0x4000
	s_addc_u32 s15, s15, 0
	global_load_dword v22, v3, s[14:15] nt
	s_add_u32 s14, s14, 0x4000
	s_addc_u32 s15, s15, 0
	global_load_dword v23, v3, s[14:15] nt
	s_add_u32 s14, s14, 0x4000
	s_addc_u32 s15, s15, 0
	global_load_dword v24, v3, s[14:15] nt
	s_add_u32 s14, s14, 0x4000
	s_addc_u32 s15, s15, 0
	global_load_dword v25, v3, s[14:15] nt
	s_add_u32 s14, s14, 0x4000
	s_addc_u32 s15, s15, 0
	global_load_dword v26, v3, s[14:15] nt
	s_add_u32 s14, s14, 0x4000
	s_addc_u32 s15, s15, 0
	global_load_dword v27, v3, s[14:15] nt
	s_add_u32 s14, s14, 0x4000
	s_addc_u32 s15, s15, 0
	global_load_dword v28, v3, s[14:15] nt
	s_add_u32 s14, s14, 0x4000
	s_addc_u32 s15, s15, 0
	global_load_dword v29, v3, s[14:15] nt
	s_add_u32 s14, s14, 0x4000
	s_addc_u32 s15, s15, 0
	global_load_dword v30, v3, s[14:15] nt
	s_add_u32 s14, s14, 0x4000
	s_addc_u32 s15, s15, 0
	global_load_dword v31, v3, s[14:15] nt
	s_add_u32 s14, s14, 0x4000
	s_addc_u32 s15, s15, 0
	global_load_dword v32, v3, s[14:15] nt
	s_add_u32 s14, s14, 0x4000
	s_addc_u32 s15, s15, 0
	global_load_dword v33, v3, s[14:15] nt
	s_add_u32 s14, s14, 0x4000
	s_addc_u32 s15, s15, 0
	global_load_dword v34, v3, s[14:15] nt
	s_add_u32 s14, s14, 0x4000
	s_addc_u32 s15, s15, 0
	global_load_dword v35, v3, s[14:15] nt
	s_add_u32 s14, s14, 0x4000
	s_addc_u32 s15, s15, 0
	global_load_dword v36, v3, s[14:15] nt
	s_add_u32 s14, s14, 0x4000
	s_addc_u32 s15, s15, 0
	global_load_dword v37, v3, s[14:15] nt
	s_add_u32 s14, s14, 0x4000
	s_addc_u32 s15, s15, 0
	global_load_dword v38, v3, s[14:15] nt
	s_add_u32 s14, s14, 0x4000
	s_addc_u32 s15, s15, 0
	global_load_dword v39, v3, s[14:15] nt
	s_add_u32 s14, s14, 0x4000
	s_addc_u32 s15, s15, 0
	global_load_dword v40, v3, s[14:15] nt
	s_add_u32 s14, s14, 0x4000
	s_addc_u32 s15, s15, 0
	global_load_dword v41, v3, s[14:15] nt
	s_add_u32 s14, s14, 0x4000
	s_addc_u32 s15, s15, 0
	global_load_dword v42, v3, s[14:15] nt
	s_add_u32 s14, s14, 0x4000
	s_addc_u32 s15, s15, 0
	global_load_dword v43, v3, s[14:15] nt
	s_add_u32 s14, s14, 0x4000
	s_addc_u32 s15, s15, 0
	global_load_dword v44, v3, s[14:15] nt
	s_add_u32 s14, s14, 0x4000
	s_addc_u32 s15, s15, 0
	global_load_dword v45, v3, s[14:15] nt
	s_add_u32 s14, s14, 0x4000
	s_addc_u32 s15, s15, 0
	global_load_dword v46, v3, s[14:15] nt
	s_add_u32 s14, s14, 0x4000
	s_addc_u32 s15, s15, 0
	global_load_dword v47, v3, s[14:15] nt
	s_lshr_b32 s16, s12, 2
	s_mul_i32 s16, s16, 0x10
	s_add_u32 s16, s16, s11
	s_lshl_b32 s16, s16, 14
	s_and_b32 s17, s12, 3
	s_lshl_b32 s17, s17, 12
	s_add_u32 s16, s16, s17
	s_add_u32 s16, s6, s16
	s_addc_u32 s17, s7, 0
	s_waitcnt vmcnt(32)
	ds_write_b32 v4, v88
	ds_write_b32 v4, v89 offset:264
	ds_write_b32 v4, v90 offset:528
	ds_write_b32 v4, v91 offset:792
	ds_write_b32 v4, v92 offset:1056
	ds_write_b32 v4, v93 offset:1320
	ds_write_b32 v4, v94 offset:1584
	ds_write_b32 v4, v95 offset:1848
	ds_write_b32 v4, v96 offset:2112
	ds_write_b32 v4, v97 offset:2376
	ds_write_b32 v4, v98 offset:2640
	ds_write_b32 v4, v99 offset:2904
	ds_write_b32 v4, v100 offset:3168
	ds_write_b32 v4, v101 offset:3432
	ds_write_b32 v4, v102 offset:3696
	ds_write_b32 v4, v103 offset:3960
	ds_write_b32 v4, v104 offset:4224
	ds_write_b32 v4, v105 offset:4488
	ds_write_b32 v4, v106 offset:4752
	ds_write_b32 v4, v107 offset:5016
	ds_write_b32 v4, v108 offset:5280
	ds_write_b32 v4, v109 offset:5544
	ds_write_b32 v4, v110 offset:5808
	ds_write_b32 v4, v111 offset:6072
	ds_write_b32 v4, v112 offset:6336
	ds_write_b32 v4, v113 offset:6600
	ds_write_b32 v4, v114 offset:6864
	ds_write_b32 v4, v115 offset:7128
	ds_write_b32 v4, v116 offset:7392
	ds_write_b32 v4, v117 offset:7656
	ds_write_b32 v4, v118 offset:7920
	ds_write_b32 v4, v119 offset:8184
	s_waitcnt lgkmcnt(0)
	ds_read_b32 v48, v7
	ds_read_b32 v49, v7 offset:132
	ds_read_b32 v50, v7 offset:264
	ds_read_b32 v51, v7 offset:396
	ds_read_b32 v52, v7 offset:528
	ds_read_b32 v53, v7 offset:660
	ds_read_b32 v54, v7 offset:792
	ds_read_b32 v55, v7 offset:924
	ds_read_b32 v56, v7 offset:32
	ds_read_b32 v57, v7 offset:164
	ds_read_b32 v58, v7 offset:296
	ds_read_b32 v59, v7 offset:428
	ds_read_b32 v60, v7 offset:560
	ds_read_b32 v61, v7 offset:692
	ds_read_b32 v62, v7 offset:824
	ds_read_b32 v63, v7 offset:956
	ds_read_b32 v64, v7 offset:64
	ds_read_b32 v65, v7 offset:196
	ds_read_b32 v66, v7 offset:328
	ds_read_b32 v67, v7 offset:460
	ds_read_b32 v68, v7 offset:592
	ds_read_b32 v69, v7 offset:724
	ds_read_b32 v70, v7 offset:856
	ds_read_b32 v71, v7 offset:988
	ds_read_b32 v72, v7 offset:96
	ds_read_b32 v73, v7 offset:228
	ds_read_b32 v74, v7 offset:360
	ds_read_b32 v75, v7 offset:492
	ds_read_b32 v76, v7 offset:624
	ds_read_b32 v77, v7 offset:756
	ds_read_b32 v78, v7 offset:888
	ds_read_b32 v79, v7 offset:1020
	s_waitcnt lgkmcnt(0)
	v_cvt_pk_bf16_f32 v48, v48, v49
	v_cvt_pk_bf16_f32 v49, v50, v51
	v_cvt_pk_bf16_f32 v50, v52, v53
	v_cvt_pk_bf16_f32 v51, v54, v55
	global_store_dwordx4 v10, v[48:51], s[24:25]
	v_cvt_pk_bf16_f32 v56, v56, v57
	v_cvt_pk_bf16_f32 v57, v58, v59
	v_cvt_pk_bf16_f32 v58, v60, v61
	v_cvt_pk_bf16_f32 v59, v62, v63
	global_store_dwordx4 v10, v[56:59], s[24:25] offset:256
	v_cvt_pk_bf16_f32 v64, v64, v65
	v_cvt_pk_bf16_f32 v65, v66, v67
	v_cvt_pk_bf16_f32 v66, v68, v69
	v_cvt_pk_bf16_f32 v67, v70, v71
	global_store_dwordx4 v11, v[64:67], s[24:25] offset:512
	v_cvt_pk_bf16_f32 v72, v72, v73
	v_cvt_pk_bf16_f32 v73, v74, v75
	v_cvt_pk_bf16_f32 v74, v76, v77
	v_cvt_pk_bf16_f32 v75, v78, v79
	global_store_dwordx4 v11, v[72:75], s[24:25] offset:768
	s_branch .Ltc3a_loop
; #define LAS __attribute__((address_space(3)))
; __device__ __forceinline__ unsigned pk2(float lo, float hi) { f32x2 f = {lo, hi}; bf16x2_t b = __builtin_convertvector(f, bf16x2_t); return __builtin_bit_cast(unsigned, b); }
; template <int MAP, bool HASG, bool PERMW>
; __device__ __forceinline__ void tr_store(int K, int N, bf16_t* WT, LAS float* scr, int item, int lane, const float* gk) {
;     const int nblk = N / 32, kb = item / nblk, nb = item % nblk, k0 = 64 * kb, n0 = 32 * nb;
;     asm volatile("s_waitcnt lgkmcnt(0)" ::: "memory");
;     const int c = lane & 7;
;     f32x4 g0 = {1.f, 1.f, 1.f, 1.f}, g1 = {1.f, 1.f, 1.f, 1.f};
;     if (HASG) { g0 = *(const f32x4*)(gk + k0 + 8 * c); g1 = *(const f32x4*)(gk + k0 + 8 * c + 4); }
; #pragma unroll
;     for (int j = 0; j < 4; ++j) { const int n = (lane >> 3) + 8 * j; const LAS float* s = scr + (8 * c) * 33 + n;
;         u32x4 o; o.x = pk2(s[0 * 33] * g0[0], s[1 * 33] * g0[1]); o.y = pk2(s[2 * 33] * g0[2], s[3 * 33] * g0[3]); o.z = pk2(s[4 * 33] * g1[0], s[5 * 33] * g1[1]); o.w = pk2(s[6 * 33] * g1[2], s[7 * 33] * g1[3]);
;         const int wr_ = rowmap<MAP>(n0 + n), slot_ = PERMW ? ((wr_ & ~31) + invperm32(wr_ & 31)) : wr_;
;         *(u32x4*)((char*)WT + tiled_off(slot_, k0 + 8 * c, K / 64)) = o; }
;     asm volatile("s_waitcnt lgkmcnt(0)" ::: "memory");
; }
.Ltc3a_lastA:
	s_waitcnt vmcnt(0)
	ds_write_b32 v4, v16
	ds_write_b32 v4, v17 offset:264
	ds_write_b32 v4, v18 offset:528
	ds_write_b32 v4, v19 offset:792
	ds_write_b32 v4, v20 offset:1056
	ds_write_b32 v4, v21 offset:1320
	ds_write_b32 v4, v22 offset:1584
	ds_write_b32 v4, v23 offset:1848
	ds_write_b32 v4, v24 offset:2112
	ds_write_b32 v4, v25 offset:2376
	ds_write_b32 v4, v26 offset:2640
	ds_write_b32 v4, v27 offset:2904
	ds_write_b32 v4, v28 offset:3168
	ds_write_b32 v4, v29 offset:3432
	ds_write_b32 v4, v30 offset:3696
	ds_write_b32 v4, v31 offset:3960
	ds_write_b32 v4, v32 offset:4224
	ds_write_b32 v4, v33 offset:4488
	ds_write_b32 v4, v34 offset:4752
	ds_write_b32 v4, v35 offset:5016
	ds_write_b32 v4, v36 offset:5280
	ds_write_b32 v4, v37 offset:5544
	ds_write_b32 v4, v38 offset:5808
	ds_write_b32 v4, v39 offset:6072
	ds_write_b32 v4, v40 offset:6336
	ds_write_b32 v4, v41 offset:6600
	ds_write_b32 v4, v42 offset:6864
	ds_write_b32 v4, v43 offset:7128
	ds_write_b32 v4, v44 offset:7392
	ds_write_b32 v4, v45 offset:7656
	ds_write_b32 v4, v46 offset:7920
	ds_write_b32 v4, v47 offset:8184
	s_waitcnt lgkmcnt(0)
	ds_read_b32 v48, v7
	ds_read_b32 v49, v7 offset:132
	ds_read_b32 v50, v7 offset:264
	ds_read_b32 v51, v7 offset:396
	ds_read_b32 v52, v7 offset:528
	ds_read_b32 v53, v7 offset:660
	ds_read_b32 v54, v7 offset:792
	ds_read_b32 v55, v7 offset:924
	ds_read_b32 v56, v7 offset:32
	ds_read_b32 v57, v7 offset:164
	ds_read_b32 v58, v7 offset:296
	ds_read_b32 v59, v7 offset:428
	ds_read_b32 v60, v7 offset:560
	ds_read_b32 v61, v7 offset:692
	ds_read_b32 v62, v7 offset:824
	ds_read_b32 v63, v7 offset:956
	ds_read_b32 v64, v7 offset:64
	ds_read_b32 v65, v7 offset:196
	ds_read_b32 v66, v7 offset:328
	ds_read_b32 v67, v7 offset:460
	ds_read_b32 v68, v7 offset:592
	ds_read_b32 v69, v7 offset:724
	ds_read_b32 v70, v7 offset:856
	ds_read_b32 v71, v7 offset:988
	ds_read_b32 v72, v7 offset:96
	ds_read_b32 v73, v7 offset:228
	ds_read_b32 v74, v7 offset:360
	ds_read_b32 v75, v7 offset:492
	ds_read_b32 v76, v7 offset:624
	ds_read_b32 v77, v7 offset:756
	ds_read_b32 v78, v7 offset:888
	ds_read_b32 v79, v7 offset:1020
	s_waitcnt lgkmcnt(0)
	v_cvt_pk_bf16_f32 v48, v48, v49
	v_cvt_pk_bf16_f32 v49, v50, v51
	v_cvt_pk_bf16_f32 v50, v52, v53
	v_cvt_pk_bf16_f32 v51, v54, v55
	global_store_dwordx4 v10, v[48:51], s[16:17]
	v_cvt_pk_bf16_f32 v56, v56, v57
	v_cvt_pk_bf16_f32 v57, v58, v59
	v_cvt_pk_bf16_f32 v58, v60, v61
	v_cvt_pk_bf16_f32 v59, v62, v63
	global_store_dwordx4 v10, v[56:59], s[16:17] offset:256
	v_cvt_pk_bf16_f32 v64, v64, v65
	v_cvt_pk_bf16_f32 v65, v66, v67
	v_cvt_pk_bf16_f32 v66, v68, v69
	v_cvt_pk_bf16_f32 v67, v70, v71
	global_store_dwordx4 v11, v[64:67], s[16:17] offset:512
	v_cvt_pk_bf16_f32 v72, v72, v73
	v_cvt_pk_bf16_f32 v73, v74, v75
	v_cvt_pk_bf16_f32 v74, v76, v77
	v_cvt_pk_bf16_f32 v75, v78, v79
	global_store_dwordx4 v11, v[72:75], s[16:17] offset:768
	s_branch .Ltc3a_exit
.Ltc3a_lastB:
	s_waitcnt vmcnt(0)
	ds_write_b32 v4, v88
	ds_write_b32 v4, v89 offset:264
	ds_write_b32 v4, v90 offset:528
	ds_write_b32 v4, v91 offset:792
	ds_write_b32 v4, v92 offset:1056
	ds_write_b32 v4, v93 offset:1320
	ds_write_b32 v4, v94 offset:1584
	ds_write_b32 v4, v95 offset:1848
	ds_write_b32 v4, v96 offset:2112
	ds_write_b32 v4, v97 offset:2376
	ds_write_b32 v4, v98 offset:2640
	ds_write_b32 v4, v99 offset:2904
	ds_write_b32 v4, v100 offset:3168
	ds_write_b32 v4, v101 offset:3432
	ds_write_b32 v4, v102 offset:3696
	ds_write_b32 v4, v103 offset:3960
	ds_write_b32 v4, v104 offset:4224
	ds_write_b32 v4, v105 offset:4488
	ds_write_b32 v4, v106 offset:4752
	ds_write_b32 v4, v107 offset:5016
	ds_write_b32 v4, v108 offset:5280
	ds_write_b32 v4, v109 offset:5544
	ds_write_b32 v4, v110 offset:5808
	ds_write_b32 v4, v111 offset:6072
	ds_write_b32 v4, v112 offset:6336
	ds_write_b32 v4, v113 offset:6600
	ds_write_b32 v4, v114 offset:6864
	ds_write_b32 v4, v115 offset:7128
	ds_write_b32 v4, v116 offset:7392
	ds_write_b32 v4, v117 offset:7656
	ds_write_b32 v4, v118 offset:7920
	ds_write_b32 v4, v119 offset:8184
	s_waitcnt lgkmcnt(0)
	ds_read_b32 v48, v7
	ds_read_b32 v49, v7 offset:132
	ds_read_b32 v50, v7 offset:264
	ds_read_b32 v51, v7 offset:396
	ds_read_b32 v52, v7 offset:528
	ds_read_b32 v53, v7 offset:660
	ds_read_b32 v54, v7 offset:792
	ds_read_b32 v55, v7 offset:924
	ds_read_b32 v56, v7 offset:32
	ds_read_b32 v57, v7 offset:164
	ds_read_b32 v58, v7 offset:296
	ds_read_b32 v59, v7 offset:428
	ds_read_b32 v60, v7 offset:560
	ds_read_b32 v61, v7 offset:692
	ds_read_b32 v62, v7 offset:824
	ds_read_b32 v63, v7 offset:956
	ds_read_b32 v64, v7 offset:64
	ds_read_b32 v65, v7 offset:196
	ds_read_b32 v66, v7 offset:328
	ds_read_b32 v67, v7 offset:460
	ds_read_b32 v68, v7 offset:592
	ds_read_b32 v69, v7 offset:724
	ds_read_b32 v70, v7 offset:856
	ds_read_b32 v71, v7 offset:988
	ds_read_b32 v72, v7 offset:96
	ds_read_b32 v73, v7 offset:228
	ds_read_b32 v74, v7 offset:360
	ds_read_b32 v75, v7 offset:492
	ds_read_b32 v76, v7 offset:624
	ds_read_b32 v77, v7 offset:756
	ds_read_b32 v78, v7 offset:888
	ds_read_b32 v79, v7 offset:1020
	s_waitcnt lgkmcnt(0)
	v_cvt_pk_bf16_f32 v48, v48, v49
	v_cvt_pk_bf16_f32 v49, v50, v51
	v_cvt_pk_bf16_f32 v50, v52, v53
	v_cvt_pk_bf16_f32 v51, v54, v55
	global_store_dwordx4 v10, v[48:51], s[24:25]
	v_cvt_pk_bf16_f32 v56, v56, v57
	v_cvt_pk_bf16_f32 v57, v58, v59
	v_cvt_pk_bf16_f32 v58, v60, v61
	v_cvt_pk_bf16_f32 v59, v62, v63
	global_store_dwordx4 v10, v[56:59], s[24:25] offset:256
	v_cvt_pk_bf16_f32 v64, v64, v65
	v_cvt_pk_bf16_f32 v65, v66, v67
	v_cvt_pk_bf16_f32 v66, v68, v69
	v_cvt_pk_bf16_f32 v67, v70, v71
	global_store_dwordx4 v11, v[64:67], s[24:25] offset:512
	v_cvt_pk_bf16_f32 v72, v72, v73
	v_cvt_pk_bf16_f32 v73, v74, v75
	v_cvt_pk_bf16_f32 v74, v76, v77
	v_cvt_pk_bf16_f32 v75, v78, v79
	global_store_dwordx4 v11, v[72:75], s[24:25] offset:768
; #define LAS __attribute__((address_space(3)))
; __device__ __forceinline__ unsigned pk2(float lo, float hi) { f32x2 f = {lo, hi}; bf16x2_t b = __builtin_convertvector(f, bf16x2_t); return __builtin_bit_cast(unsigned, b); }
; __device__ __forceinline__ void tr_load(const float* W, int N, int item, int lane, float (&wv)[32]) {
;     const int nblk = N / 32, kb = item / nblk, nb = item % nblk, k0 = 64 * kb, n0 = 32 * nb;
; #pragma unroll
;     for (int i = 0; i < 32; ++i) { const int kk = 2 * i + (lane >> 5); wv[i] = __builtin_nontemporal_load(W + (size_t)(k0 + kk) * N + n0 + (lane & 31)); }
; }
; template <int MAP, bool HASG, bool PERMW>
; __device__ __forceinline__ void tr_store(int K, int N, bf16_t* WT, LAS float* scr, int item, int lane, const float* gk) {
;     const int nblk = N / 32, kb = item / nblk, nb = item % nblk, k0 = 64 * kb, n0 = 32 * nb;
;     asm volatile("s_waitcnt lgkmcnt(0)" ::: "memory");
;     const int c = lane & 7;
;     f32x4 g0 = {1.f, 1.f, 1.f, 1.f}, g1 = {1.f, 1.f, 1.f, 1.f};
;     if (HASG) { g0 = *(const f32x4*)(gk + k0 + 8 * c); g1 = *(const f32x4*)(gk + k0 + 8 * c + 4); }
; #pragma unroll
;     for (int j = 0; j < 4; ++j) { const int n = (lane >> 3) + 8 * j; const LAS float* s = scr + (8 * c) * 33 + n;
;         u32x4 o; o.x = pk2(s[0 * 33] * g0[0], s[1 * 33] * g0[1]); o.y = pk2(s[2 * 33] * g0[2], s[3 * 33] * g0[3]); o.z = pk2(s[4 * 33] * g1[0], s[5 * 33] * g1[1]); o.w = pk2(s[6 * 33] * g1[2], s[7 * 33] * g1[3]);
;         const int wr_ = rowmap<MAP>(n0 + n), slot_ = PERMW ? ((wr_ & ~31) + invperm32(wr_ & 31)) : wr_;
;         *(u32x4*)((char*)WT + tiled_off(slot_, k0 + 8 * c, K / 64)) = o; }
; __global__ void __launch_bounds__(512, 2) mega_fwd(Params p) {
;     ...
;             transpose_mat<0, false, true>(p.in[8] + (size_t)l * 2048 * D, 2048, D, P_W(WS_WB), scr, gw, ngw, lane);
.Ltc3a_exit:
	v_readlane_b32 s4, v254, 0
	v_readlane_b32 s5, v254, 1
	s_nop 3
	s_and_b32 s6, s60, 0x1000000
	s_add_u32 s4, s4, s6
	s_addc_u32 s5, s5, 0
	s_add_u32 s6, s76, 0x7a00000
	s_addc_u32 s7, s77, 0
	s_mov_b32 s9, s18
	s_cmpk_ge_u32 s9, 0x800
	s_cbranch_scc1 .Ltc3b_exit
	s_lshr_b32 s11, s9, 6
	s_and_b32 s12, s9, 63
	s_lshl_b32 s13, s11, 19
	s_lshl_b32 s14, s12, 7
	s_add_u32 s13, s13, s14
	s_add_u32 s14, s4, s13
	s_addc_u32 s15, s5, 0
	global_load_dword v16, v3, s[14:15] nt
	s_add_u32 s14, s14, 0x4000
	s_addc_u32 s15, s15, 0
	global_load_dword v17, v3, s[14:15] nt
	s_add_u32 s14, s14, 0x4000
	s_addc_u32 s15, s15, 0
	global_load_dword v18, v3, s[14:15] nt
	s_add_u32 s14, s14, 0x4000
	s_addc_u32 s15, s15, 0
	global_load_dword v19, v3, s[14:15] nt
	s_add_u32 s14, s14, 0x4000
	s_addc_u32 s15, s15, 0
	global_load_dword v20, v3, s[14:15] nt
	s_add_u32 s14, s14, 0x4000
	s_addc_u32 s15, s15, 0
	global_load_dword v21, v3, s[14:15] nt
	s_add_u32 s14, s14, 0x4000
	s_addc_u32 s15, s15, 0
	global_load_dword v22, v3, s[14:15] nt
	s_add_u32 s14, s14, 0x4000
	s_addc_u32 s15, s15, 0
	global_load_dword v23, v3, s[14:15] nt
	s_add_u32 s14, s14, 0x4000
	s_addc_u32 s15, s15, 0
	global_load_dword v24, v3, s[14:15] nt
	s_add_u32 s14, s14, 0x4000
	s_addc_u32 s15, s15, 0
	global_load_dword v25, v3, s[14:15] nt
	s_add_u32 s14, s14, 0x4000
	s_addc_u32 s15, s15, 0
	global_load_dword v26, v3, s[14:15] nt
	s_add_u32 s14, s14, 0x4000
	s_addc_u32 s15, s15, 0
	global_load_dword v27, v3, s[14:15] nt
	s_add_u32 s14, s14, 0x4000
	s_addc_u32 s15, s15, 0
	global_load_dword v28, v3, s[14:15] nt
	s_add_u32 s14, s14, 0x4000
	s_addc_u32 s15, s15, 0
	global_load_dword v29, v3, s[14:15] nt
	s_add_u32 s14, s14, 0x4000
	s_addc_u32 s15, s15, 0
	global_load_dword v30, v3, s[14:15] nt
	s_add_u32 s14, s14, 0x4000
	s_addc_u32 s15, s15, 0
	global_load_dword v31, v3, s[14:15] nt
	s_add_u32 s14, s14, 0x4000
	s_addc_u32 s15, s15, 0
	global_load_dword v32, v3, s[14:15] nt
	s_add_u32 s14, s14, 0x4000
	s_addc_u32 s15, s15, 0
	global_load_dword v33, v3, s[14:15] nt
	s_add_u32 s14, s14, 0x4000
	s_addc_u32 s15, s15, 0
	global_load_dword v34, v3, s[14:15] nt
	s_add_u32 s14, s14, 0x4000
	s_addc_u32 s15, s15, 0
	global_load_dword v35, v3, s[14:15] nt
	s_add_u32 s14, s14, 0x4000
	s_addc_u32 s15, s15, 0
	global_load_dword v36, v3, s[14:15] nt
	s_add_u32 s14, s14, 0x4000
	s_addc_u32 s15, s15, 0
	global_load_dword v37, v3, s[14:15] nt
	s_add_u32 s14, s14, 0x4000
	s_addc_u32 s15, s15, 0
	global_load_dword v38, v3, s[14:15] nt
	s_add_u32 s14, s14, 0x4000
	s_addc_u32 s15, s15, 0
	global_load_dword v39, v3, s[14:15] nt
	s_add_u32 s14, s14, 0x4000
	s_addc_u32 s15, s15, 0
	global_load_dword v40, v3, s[14:15] nt
	s_add_u32 s14, s14, 0x4000
	s_addc_u32 s15, s15, 0
	global_load_dword v41, v3, s[14:15] nt
	s_add_u32 s14, s14, 0x4000
	s_addc_u32 s15, s15, 0
	global_load_dword v42, v3, s[14:15] nt
	s_add_u32 s14, s14, 0x4000
	s_addc_u32 s15, s15, 0
	global_load_dword v43, v3, s[14:15] nt
	s_add_u32 s14, s14, 0x4000
	s_addc_u32 s15, s15, 0
	global_load_dword v44, v3, s[14:15] nt
	s_add_u32 s14, s14, 0x4000
	s_addc_u32 s15, s15, 0
	global_load_dword v45, v3, s[14:15] nt
	s_add_u32 s14, s14, 0x4000
	s_addc_u32 s15, s15, 0
	global_load_dword v46, v3, s[14:15] nt
	s_add_u32 s14, s14, 0x4000
	s_addc_u32 s15, s15, 0
	global_load_dword v47, v3, s[14:15] nt
	s_lshr_b32 s16, s12, 2
	s_mul_i32 s16, s16, 0x20
	s_add_u32 s16, s16, s11
	s_lshl_b32 s16, s16, 14
	s_and_b32 s17, s12, 3
	s_lshl_b32 s17, s17, 12
	s_add_u32 s16, s16, s17
	s_add_u32 s16, s6, s16
	s_addc_u32 s17, s7, 0
.Ltc3b_loop:
	s_add_u32 s9, s9, 0x400
	s_cmpk_ge_u32 s9, 0x800
	s_cbranch_scc1 .Ltc3b_lastA
	s_lshr_b32 s11, s9, 6
	s_and_b32 s12, s9, 63
	s_lshl_b32 s13, s11, 19
	s_lshl_b32 s14, s12, 7
	s_add_u32 s13, s13, s14
	s_add_u32 s14, s4, s13
	s_addc_u32 s15, s5, 0
	global_load_dword v88, v3, s[14:15] nt
	s_add_u32 s14, s14, 0x4000
	s_addc_u32 s15, s15, 0
	global_load_dword v89, v3, s[14:15] nt
	s_add_u32 s14, s14, 0x4000
	s_addc_u32 s15, s15, 0
	global_load_dword v90, v3, s[14:15] nt
	s_add_u32 s14, s14, 0x4000
	s_addc_u32 s15, s15, 0
	global_load_dword v91, v3, s[14:15] nt
	s_add_u32 s14, s14, 0x4000
	s_addc_u32 s15, s15, 0
	global_load_dword v92, v3, s[14:15] nt
	s_add_u32 s14, s14, 0x4000
	s_addc_u32 s15, s15, 0
	global_load_dword v93, v3, s[14:15] nt
	s_add_u32 s14, s14, 0x4000
	s_addc_u32 s15, s15, 0
	global_load_dword v94, v3, s[14:15] nt
	s_add_u32 s14, s14, 0x4000
	s_addc_u32 s15, s15, 0
	global_load_dword v95, v3, s[14:15] nt
	s_add_u32 s14, s14, 0x4000
	s_addc_u32 s15, s15, 0
	global_load_dword v96, v3, s[14:15] nt
	s_add_u32 s14, s14, 0x4000
	s_addc_u32 s15, s15, 0
	global_load_dword v97, v3, s[14:15] nt
	s_add_u32 s14, s14, 0x4000
	s_addc_u32 s15, s15, 0
	global_load_dword v98, v3, s[14:15] nt
	s_add_u32 s14, s14, 0x4000
	s_addc_u32 s15, s15, 0
	global_load_dword v99, v3, s[14:15] nt
	s_add_u32 s14, s14, 0x4000
	s_addc_u32 s15, s15, 0
	global_load_dword v100, v3, s[14:15] nt
	s_add_u32 s14, s14, 0x4000
	s_addc_u32 s15, s15, 0
	global_load_dword v101, v3, s[14:15] nt
	s_add_u32 s14, s14, 0x4000
	s_addc_u32 s15, s15, 0
	global_load_dword v102, v3, s[14:15] nt
	s_add_u32 s14, s14, 0x4000
	s_addc_u32 s15, s15, 0
	global_load_dword v103, v3, s[14:15] nt
	s_add_u32 s14, s14, 0x4000
	s_addc_u32 s15, s15, 0
	global_load_dword v104, v3, s[14:15] nt
	s_add_u32 s14, s14, 0x4000
	s_addc_u32 s15, s15, 0
	global_load_dword v105, v3, s[14:15] nt
	s_add_u32 s14, s14, 0x4000
	s_addc_u32 s15, s15, 0
	global_load_dword v106, v3, s[14:15] nt
	s_add_u32 s14, s14, 0x4000
	s_addc_u32 s15, s15, 0
	global_load_dword v107, v3, s[14:15] nt
	s_add_u32 s14, s14, 0x4000
	s_addc_u32 s15, s15, 0
	global_load_dword v108, v3, s[14:15] nt
	s_add_u32 s14, s14, 0x4000
	s_addc_u32 s15, s15, 0
	global_load_dword v109, v3, s[14:15] nt
	s_add_u32 s14, s14, 0x4000
	s_addc_u32 s15, s15, 0
	global_load_dword v110, v3, s[14:15] nt
	s_add_u32 s14, s14, 0x4000
	s_addc_u32 s15, s15, 0
	global_load_dword v111, v3, s[14:15] nt
	s_add_u32 s14, s14, 0x4000
	s_addc_u32 s15, s15, 0
	global_load_dword v112, v3, s[14:15] nt
	s_add_u32 s14, s14, 0x4000
	s_addc_u32 s15, s15, 0
	global_load_dword v113, v3, s[14:15] nt
	s_add_u32 s14, s14, 0x4000
	s_addc_u32 s15, s15, 0
	global_load_dword v114, v3, s[14:15] nt
	s_add_u32 s14, s14, 0x4000
	s_addc_u32 s15, s15, 0
	global_load_dword v115, v3, s[14:15] nt
	s_add_u32 s14, s14, 0x4000
	s_addc_u32 s15, s15, 0
	global_load_dword v116, v3, s[14:15] nt
	s_add_u32 s14, s14, 0x4000
	s_addc_u32 s15, s15, 0
	global_load_dword v117, v3, s[14:15] nt
	s_add_u32 s14, s14, 0x4000
	s_addc_u32 s15, s15, 0
	global_load_dword v118, v3, s[14:15] nt
	s_add_u32 s14, s14, 0x4000
	s_addc_u32 s15, s15, 0
	global_load_dword v119, v3, s[14:15] nt
	s_lshr_b32 s24, s12, 2
	s_mul_i32 s24, s24, 0x20
	s_add_u32 s24, s24, s11
	s_lshl_b32 s24, s24, 14
	s_and_b32 s25, s12, 3
	s_lshl_b32 s25, s25, 12
	s_add_u32 s24, s24, s25
	s_add_u32 s24, s6, s24
	s_addc_u32 s25, s7, 0
	s_waitcnt vmcnt(32)
; #define LAS __attribute__((address_space(3)))
; __device__ __forceinline__ unsigned pk2(float lo, float hi) { f32x2 f = {lo, hi}; bf16x2_t b = __builtin_convertvector(f, bf16x2_t); return __builtin_bit_cast(unsigned, b); }
; template <int MAP, bool HASG, bool PERMW>
; __device__ __forceinline__ void tr_store(int K, int N, bf16_t* WT, LAS float* scr, int item, int lane, const float* gk) {
;     const int nblk = N / 32, kb = item / nblk, nb = item % nblk, k0 = 64 * kb, n0 = 32 * nb;
;     asm volatile("s_waitcnt lgkmcnt(0)" ::: "memory");
;     const int c = lane & 7;
;     f32x4 g0 = {1.f, 1.f, 1.f, 1.f}, g1 = {1.f, 1.f, 1.f, 1.f};
;     if (HASG) { g0 = *(const f32x4*)(gk + k0 + 8 * c); g1 = *(const f32x4*)(gk + k0 + 8 * c + 4); }
; #pragma unroll
;     for (int j = 0; j < 4; ++j) { const int n = (lane >> 3) + 8 * j; const LAS float* s = scr + (8 * c) * 33 + n;
;         u32x4 o; o.x = pk2(s[0 * 33] * g0[0], s[1 * 33] * g0[1]); o.y = pk2(s[2 * 33] * g0[2], s[3 * 33] * g0[3]); o.z = pk2(s[4 * 33] * g1[0], s[5 * 33] * g1[1]); o.w = pk2(s[6 * 33] * g1[2], s[7 * 33] * g1[3]);
;         const int wr_ = rowmap<MAP>(n0 + n), slot_ = PERMW ? ((wr_ & ~31) + invperm32(wr_ & 31)) : wr_;
;         *(u32x4*)((char*)WT + tiled_off(slot_, k0 + 8 * c, K / 64)) = o; }
;     asm volatile("s_waitcnt lgkmcnt(0)" ::: "memory");
; }
; template <int MAP, bool HASG = false, bool PERMW = false>
; __device__ __forceinline__ void transpose_mat(const float* W, int K, int N, bf16_t* WT, LAS float* scr, int gw, int ngw, int lane, const float* gk = nullptr) {
;     const int nitems = (K / 64) * (N / 32);
;     int it = gw;
;     if (it >= nitems) return;
;     float wv[32];
;     tr_load(W, N, it, lane, wv);
;     for (;;) {
;         __builtin_amdgcn_sched_barrier(0);
; #pragma unroll
;         for (int i = 0; i < 32; ++i) { const int kk = 2 * i + (lane >> 5); scr[kk * 33 + (lane & 31)] = wv[i]; }
;         __builtin_amdgcn_sched_barrier(0);
;         const int nx = it + ngw;
;         if (nx < nitems) tr_load(W, N, nx, lane, wv);
;         __builtin_amdgcn_sched_barrier(0);
;         tr_store<MAP, HASG, PERMW>(K, N, WT, scr, it, lane, gk);
;         if (nx >= nitems) break;
;         it = nx;
	ds_write_b32 v4, v16
	ds_write_b32 v4, v17 offset:264
	ds_write_b32 v4, v18 offset:528
	ds_write_b32 v4, v19 offset:792
	ds_write_b32 v4, v20 offset:1056
	ds_write_b32 v4, v21 offset:1320
	ds_write_b32 v4, v22 offset:1584
	ds_write_b32 v4, v23 offset:1848
	ds_write_b32 v4, v24 offset:2112
	ds_write_b32 v4, v25 offset:2376
	ds_write_b32 v4, v26 offset:2640
	ds_write_b32 v4, v27 offset:2904
	ds_write_b32 v4, v28 offset:3168
	ds_write_b32 v4, v29 offset:3432
	ds_write_b32 v4, v30 offset:3696
	ds_write_b32 v4, v31 offset:3960
	ds_write_b32 v4, v32 offset:4224
	ds_write_b32 v4, v33 offset:4488
	ds_write_b32 v4, v34 offset:4752
	ds_write_b32 v4, v35 offset:5016
	ds_write_b32 v4, v36 offset:5280
	ds_write_b32 v4, v37 offset:5544
	ds_write_b32 v4, v38 offset:5808
	ds_write_b32 v4, v39 offset:6072
	ds_write_b32 v4, v40 offset:6336
	ds_write_b32 v4, v41 offset:6600
	ds_write_b32 v4, v42 offset:6864
	ds_write_b32 v4, v43 offset:7128
	ds_write_b32 v4, v44 offset:7392
	ds_write_b32 v4, v45 offset:7656
	ds_write_b32 v4, v46 offset:7920
	ds_write_b32 v4, v47 offset:8184
	s_waitcnt lgkmcnt(0)
	ds_read_b32 v48, v7
	ds_read_b32 v49, v7 offset:132
	ds_read_b32 v50, v7 offset:264
	ds_read_b32 v51, v7 offset:396
	ds_read_b32 v52, v7 offset:528
	ds_read_b32 v53, v7 offset:660
	ds_read_b32 v54, v7 offset:792
	ds_read_b32 v55, v7 offset:924
	ds_read_b32 v56, v7 offset:32
	ds_read_b32 v57, v7 offset:164
	ds_read_b32 v58, v7 offset:296
	ds_read_b32 v59, v7 offset:428
	ds_read_b32 v60, v7 offset:560
	ds_read_b32 v61, v7 offset:692
	ds_read_b32 v62, v7 offset:824
	ds_read_b32 v63, v7 offset:956
	ds_read_b32 v64, v7 offset:64
	ds_read_b32 v65, v7 offset:196
	ds_read_b32 v66, v7 offset:328
	ds_read_b32 v67, v7 offset:460
	ds_read_b32 v68, v7 offset:592
	ds_read_b32 v69, v7 offset:724
	ds_read_b32 v70, v7 offset:856
	ds_read_b32 v71, v7 offset:988
	ds_read_b32 v72, v7 offset:96
	ds_read_b32 v73, v7 offset:228
	ds_read_b32 v74, v7 offset:360
	ds_read_b32 v75, v7 offset:492
	ds_read_b32 v76, v7 offset:624
	ds_read_b32 v77, v7 offset:756
	ds_read_b32 v78, v7 offset:888
	ds_read_b32 v79, v7 offset:1020
	s_waitcnt lgkmcnt(0)
	v_cvt_pk_bf16_f32 v48, v48, v49
	v_cvt_pk_bf16_f32 v49, v50, v51
	v_cvt_pk_bf16_f32 v50, v52, v53
	v_cvt_pk_bf16_f32 v51, v54, v55
	global_store_dwordx4 v10, v[48:51], s[16:17]
	v_cvt_pk_bf16_f32 v56, v56, v57
	v_cvt_pk_bf16_f32 v57, v58, v59
	v_cvt_pk_bf16_f32 v58, v60, v61
	v_cvt_pk_bf16_f32 v59, v62, v63
	global_store_dwordx4 v10, v[56:59], s[16:17] offset:256
	v_cvt_pk_bf16_f32 v64, v64, v65
	v_cvt_pk_bf16_f32 v65, v66, v67
	v_cvt_pk_bf16_f32 v66, v68, v69
	v_cvt_pk_bf16_f32 v67, v70, v71
	global_store_dwordx4 v11, v[64:67], s[16:17] offset:512
	v_cvt_pk_bf16_f32 v72, v72, v73
	v_cvt_pk_bf16_f32 v73, v74, v75
	v_cvt_pk_bf16_f32 v74, v76, v77
	v_cvt_pk_bf16_f32 v75, v78, v79
	global_store_dwordx4 v11, v[72:75], s[16:17] offset:768
	s_add_u32 s9, s9, 0x400
	s_cmpk_ge_u32 s9, 0x800
	s_cbranch_scc1 .Ltc3b_lastB
; __device__ __forceinline__ void tr_load(const float* W, int N, int item, int lane, float (&wv)[32]) {
;     const int nblk = N / 32, kb = item / nblk, nb = item % nblk, k0 = 64 * kb, n0 = 32 * nb;
; #pragma unroll
;     for (int i = 0; i < 32; ++i) { const int kk = 2 * i + (lane >> 5); wv[i] = __builtin_nontemporal_load(W + (size_t)(k0 + kk) * N + n0 + (lane & 31)); }
; }
; template <int MAP, bool HASG, bool PERMW>
; __device__ __forceinline__ void tr_store(int K, int N, bf16_t* WT, LAS float* scr, int item, int lane, const float* gk) {
;     const int nblk = N / 32, kb = item / nblk, nb = item % nblk, k0 = 64 * kb, n0 = 32 * nb;
;     asm volatile("s_waitcnt lgkmcnt(0)" ::: "memory");
;     const int c = lane & 7;
;     f32x4 g0 = {1.f, 1.f, 1.f, 1.f}, g1 = {1.f, 1.f, 1.f, 1.f};
;     if (HASG) { g0 = *(const f32x4*)(gk + k0 + 8 * c); g1 = *(const f32x4*)(gk + k0 + 8 * c + 4); }
; #pragma unroll
;     for (int j = 0; j < 4; ++j) { const int n = (lane >> 3) + 8 * j; const LAS float* s = scr + (8 * c) * 33 + n;
;         u32x4 o; o.x = pk2(s[0 * 33] * g0[0], s[1 * 33] * g0[1]); o.y = pk2(s[2 * 33] * g0[2], s[3 * 33] * g0[3]); o.z = pk2(s[4 * 33] * g1[0], s[5 * 33] * g1[1]); o.w = pk2(s[6 * 33] * g1[2], s[7 * 33] * g1[3]);
;         const int wr_ = rowmap<MAP>(n0 + n), slot_ = PERMW ? ((wr_ & ~31) + invperm32(wr_ & 31)) : wr_;
;         *(u32x4*)((char*)WT + tiled_off(slot_, k0 + 8 * c, K / 64)) = o; }
;     asm volatile("s_waitcnt lgkmcnt(0)" ::: "memory");
; }
; template <int MAP, bool HASG = false, bool PERMW = false>
; __device__ __forceinline__ void transpose_mat(const float* W, int K, int N, bf16_t* WT, LAS float* scr, int gw, int ngw, int lane, const float* gk = nullptr) {
;     const int nitems = (K / 64) * (N / 32);
;     int it = gw;
;     if (it >= nitems) return;
;     float wv[32];
;     tr_load(W, N, it, lane, wv);
;     for (;;) {
;         __builtin_amdgcn_sched_barrier(0);
; #pragma unroll
;         for (int i = 0; i < 32; ++i) { const int kk = 2 * i + (lane >> 5); scr[kk * 33 + (lane & 31)] = wv[i]; }
;         __builtin_amdgcn_sched_barrier(0);
;         const int nx = it + ngw;
;         if (nx < nitems) tr_load(W, N, nx, lane, wv);
;         __builtin_amdgcn_sched_barrier(0);
;         tr_store<MAP, HASG, PERMW>(K, N, WT, scr, it, lane, gk);
;         if (nx >= nitems) break;
;         it = nx;
;     }
; }
	s_lshr_b32 s11, s9, 6
	s_and_b32 s12, s9, 63
	s_lshl_b32 s13, s11, 19
	s_lshl_b32 s14, s12, 7
	s_add_u32 s13, s13, s14
	s_add_u32 s14, s4, s13
	s_addc_u32 s15, s5, 0
	global_load_dword v16, v3, s[14:15] nt
	s_add_u32 s14, s14, 0x4000
	s_addc_u32 s15, s15, 0
	global_load_dword v17, v3, s[14:15] nt
	s_add_u32 s14, s14, 0x4000
	s_addc_u32 s15, s15, 0
	global_load_dword v18, v3, s[14:15] nt
	s_add_u32 s14, s14, 0x4000
	s_addc_u32 s15, s15, 0
	global_load_dword v19, v3, s[14:15] nt
	s_add_u32 s14, s14, 0x4000
	s_addc_u32 s15, s15, 0
	global_load_dword v20, v3, s[14:15] nt
	s_add_u32 s14, s14, 0x4000
	s_addc_u32 s15, s15, 0
	global_load_dword v21, v3, s[14:15] nt
	s_add_u32 s14, s14, 0x4000
	s_addc_u32 s15, s15, 0
	global_load_dword v22, v3, s[14:15] nt
	s_add_u32 s14, s14, 0x4000
	s_addc_u32 s15, s15, 0
	global_load_dword v23, v3, s[14:15] nt
	s_add_u32 s14, s14, 0x4000
	s_addc_u32 s15, s15, 0
	global_load_dword v24, v3, s[14:15] nt
	s_add_u32 s14, s14, 0x4000
	s_addc_u32 s15, s15, 0
	global_load_dword v25, v3, s[14:15] nt
	s_add_u32 s14, s14, 0x4000
	s_addc_u32 s15, s15, 0
	global_load_dword v26, v3, s[14:15] nt
	s_add_u32 s14, s14, 0x4000
	s_addc_u32 s15, s15, 0
	global_load_dword v27, v3, s[14:15] nt
	s_add_u32 s14, s14, 0x4000
	s_addc_u32 s15, s15, 0
	global_load_dword v28, v3, s[14:15] nt
	s_add_u32 s14, s14, 0x4000
	s_addc_u32 s15, s15, 0
	global_load_dword v29, v3, s[14:15] nt
	s_add_u32 s14, s14, 0x4000
	s_addc_u32 s15, s15, 0
	global_load_dword v30, v3, s[14:15] nt
	s_add_u32 s14, s14, 0x4000
	s_addc_u32 s15, s15, 0
	global_load_dword v31, v3, s[14:15] nt
	s_add_u32 s14, s14, 0x4000
	s_addc_u32 s15, s15, 0
	global_load_dword v32, v3, s[14:15] nt
	s_add_u32 s14, s14, 0x4000
	s_addc_u32 s15, s15, 0
	global_load_dword v33, v3, s[14:15] nt
	s_add_u32 s14, s14, 0x4000
	s_addc_u32 s15, s15, 0
	global_load_dword v34, v3, s[14:15] nt
	s_add_u32 s14, s14, 0x4000
	s_addc_u32 s15, s15, 0
	global_load_dword v35, v3, s[14:15] nt
	s_add_u32 s14, s14, 0x4000
	s_addc_u32 s15, s15, 0
	global_load_dword v36, v3, s[14:15] nt
	s_add_u32 s14, s14, 0x4000
	s_addc_u32 s15, s15, 0
	global_load_dword v37, v3, s[14:15] nt
	s_add_u32 s14, s14, 0x4000
	s_addc_u32 s15, s15, 0
	global_load_dword v38, v3, s[14:15] nt
	s_add_u32 s14, s14, 0x4000
	s_addc_u32 s15, s15, 0
	global_load_dword v39, v3, s[14:15] nt
	s_add_u32 s14, s14, 0x4000
	s_addc_u32 s15, s15, 0
	global_load_dword v40, v3, s[14:15] nt
	s_add_u32 s14, s14, 0x4000
	s_addc_u32 s15, s15, 0
	global_load_dword v41, v3, s[14:15] nt
	s_add_u32 s14, s14, 0x4000
	s_addc_u32 s15, s15, 0
	global_load_dword v42, v3, s[14:15] nt
	s_add_u32 s14, s14, 0x4000
	s_addc_u32 s15, s15, 0
	global_load_dword v43, v3, s[14:15] nt
	s_add_u32 s14, s14, 0x4000
	s_addc_u32 s15, s15, 0
	global_load_dword v44, v3, s[14:15] nt
	s_add_u32 s14, s14, 0x4000
	s_addc_u32 s15, s15, 0
	global_load_dword v45, v3, s[14:15] nt
	s_add_u32 s14, s14, 0x4000
	s_addc_u32 s15, s15, 0
	global_load_dword v46, v3, s[14:15] nt
	s_add_u32 s14, s14, 0x4000
	s_addc_u32 s15, s15, 0
	global_load_dword v47, v3, s[14:15] nt
	s_lshr_b32 s16, s12, 2
	s_mul_i32 s16, s16, 0x20
	s_add_u32 s16, s16, s11
	s_lshl_b32 s16, s16, 14
	s_and_b32 s17, s12, 3
	s_lshl_b32 s17, s17, 12
	s_add_u32 s16, s16, s17
	s_add_u32 s16, s6, s16
	s_addc_u32 s17, s7, 0
	s_waitcnt vmcnt(32)
	ds_write_b32 v4, v88
	ds_write_b32 v4, v89 offset:264
	ds_write_b32 v4, v90 offset:528
	ds_write_b32 v4, v91 offset:792
	ds_write_b32 v4, v92 offset:1056
	ds_write_b32 v4, v93 offset:1320
	ds_write_b32 v4, v94 offset:1584
	ds_write_b32 v4, v95 offset:1848
	ds_write_b32 v4, v96 offset:2112
	ds_write_b32 v4, v97 offset:2376
	ds_write_b32 v4, v98 offset:2640
	ds_write_b32 v4, v99 offset:2904
	ds_write_b32 v4, v100 offset:3168
	ds_write_b32 v4, v101 offset:3432
	ds_write_b32 v4, v102 offset:3696
	ds_write_b32 v4, v103 offset:3960
	ds_write_b32 v4, v104 offset:4224
	ds_write_b32 v4, v105 offset:4488
	ds_write_b32 v4, v106 offset:4752
	ds_write_b32 v4, v107 offset:5016
	ds_write_b32 v4, v108 offset:5280
	ds_write_b32 v4, v109 offset:5544
	ds_write_b32 v4, v110 offset:5808
	ds_write_b32 v4, v111 offset:6072
	ds_write_b32 v4, v112 offset:6336
	ds_write_b32 v4, v113 offset:6600
	ds_write_b32 v4, v114 offset:6864
	ds_write_b32 v4, v115 offset:7128
	ds_write_b32 v4, v116 offset:7392
	ds_write_b32 v4, v117 offset:7656
	ds_write_b32 v4, v118 offset:7920
	ds_write_b32 v4, v119 offset:8184
	s_waitcnt lgkmcnt(0)
	ds_read_b32 v48, v7
	ds_read_b32 v49, v7 offset:132
	ds_read_b32 v50, v7 offset:264
	ds_read_b32 v51, v7 offset:396
	ds_read_b32 v52, v7 offset:528
	ds_read_b32 v53, v7 offset:660
	ds_read_b32 v54, v7 offset:792
	ds_read_b32 v55, v7 offset:924
	ds_read_b32 v56, v7 offset:32
	ds_read_b32 v57, v7 offset:164
	ds_read_b32 v58, v7 offset:296
	ds_read_b32 v59, v7 offset:428
	ds_read_b32 v60, v7 offset:560
	ds_read_b32 v61, v7 offset:692
	ds_read_b32 v62, v7 offset:824
	ds_read_b32 v63, v7 offset:956
	ds_read_b32 v64, v7 offset:64
	ds_read_b32 v65, v7 offset:196
	ds_read_b32 v66, v7 offset:328
	ds_read_b32 v67, v7 offset:460
	ds_read_b32 v68, v7 offset:592
	ds_read_b32 v69, v7 offset:724
	ds_read_b32 v70, v7 offset:856
	ds_read_b32 v71, v7 offset:988
	ds_read_b32 v72, v7 offset:96
	ds_read_b32 v73, v7 offset:228
	ds_read_b32 v74, v7 offset:360
	ds_read_b32 v75, v7 offset:492
	ds_read_b32 v76, v7 offset:624
	ds_read_b32 v77, v7 offset:756
	ds_read_b32 v78, v7 offset:888
	ds_read_b32 v79, v7 offset:1020
	s_waitcnt lgkmcnt(0)
	v_cvt_pk_bf16_f32 v48, v48, v49
	v_cvt_pk_bf16_f32 v49, v50, v51
	v_cvt_pk_bf16_f32 v50, v52, v53
	v_cvt_pk_bf16_f32 v51, v54, v55
	global_store_dwordx4 v10, v[48:51], s[24:25]
	v_cvt_pk_bf16_f32 v56, v56, v57
	v_cvt_pk_bf16_f32 v57, v58, v59
	v_cvt_pk_bf16_f32 v58, v60, v61
	v_cvt_pk_bf16_f32 v59, v62, v63
	global_store_dwordx4 v10, v[56:59], s[24:25] offset:256
	v_cvt_pk_bf16_f32 v64, v64, v65
	v_cvt_pk_bf16_f32 v65, v66, v67
	v_cvt_pk_bf16_f32 v66, v68, v69
	v_cvt_pk_bf16_f32 v67, v70, v71
	global_store_dwordx4 v11, v[64:67], s[24:25] offset:512
	v_cvt_pk_bf16_f32 v72, v72, v73
	v_cvt_pk_bf16_f32 v73, v74, v75
	v_cvt_pk_bf16_f32 v74, v76, v77
	v_cvt_pk_bf16_f32 v75, v78, v79
	global_store_dwordx4 v11, v[72:75], s[24:25] offset:768
	s_branch .Ltc3b_loop

; __device__ __forceinline__ void tr_load(const float* W, int N, int item, int lane, float (&wv)[32]) {
;     const int nblk = N / 32, kb = item / nblk, nb = item % nblk, k0 = 64 * kb, n0 = 32 * nb;
; #pragma unroll
;     for (int i = 0; i < 32; ++i) { const int kk = 2 * i + (lane >> 5); wv[i] = __builtin_nontemporal_load(W + (size_t)(k0 + kk) * N + n0 + (lane & 31)); }
; }
; template <int MAP, bool HASG, bool PERMW>
; __device__ __forceinline__ void tr_store(int K, int N, bf16_t* WT, LAS float* scr, int item, int lane, const float* gk) {
;     const int nblk = N / 32, kb = item / nblk, nb = item % nblk, k0 = 64 * kb, n0 = 32 * nb;
;     asm volatile("s_waitcnt lgkmcnt(0)" ::: "memory");
;     const int c = lane & 7;
;     f32x4 g0 = {1.f, 1.f, 1.f, 1.f}, g1 = {1.f, 1.f, 1.f, 1.f};
;     if (HASG) { g0 = *(const f32x4*)(gk + k0 + 8 * c); g1 = *(const f32x4*)(gk + k0 + 8 * c + 4); }
; #pragma unroll
;     for (int j = 0; j < 4; ++j) { const int n = (lane >> 3) + 8 * j; const LAS float* s = scr + (8 * c) * 33 + n;
;         u32x4 o; o.x = pk2(s[0 * 33] * g0[0], s[1 * 33] * g0[1]); o.y = pk2(s[2 * 33] * g0[2], s[3 * 33] * g0[3]); o.z = pk2(s[4 * 33] * g1[0], s[5 * 33] * g1[1]); o.w = pk2(s[6 * 33] * g1[2], s[7 * 33] * g1[3]);
;         const int wr_ = rowmap<MAP>(n0 + n), slot_ = PERMW ? ((wr_ & ~31) + invperm32(wr_ & 31)) : wr_;
;         *(u32x4*)((char*)WT + tiled_off(slot_, k0 + 8 * c, K / 64)) = o; }
;     asm volatile("s_waitcnt lgkmcnt(0)" ::: "memory");
; }
; template <int MAP, bool HASG = false, bool PERMW = false>
; __device__ __forceinline__ void transpose_mat(const float* W, int K, int N, bf16_t* WT, LAS float* scr, int gw, int ngw, int lane, const float* gk = nullptr) {
;     const int nitems = (K / 64) * (N / 32);
;     int it = gw;
;     if (it >= nitems) return;
;     float wv[32];
;     tr_load(W, N, it, lane, wv);
;     for (;;) {
;         __builtin_amdgcn_sched_barrier(0);
; #pragma unroll
;         for (int i = 0; i < 32; ++i) { const int kk = 2 * i + (lane >> 5); scr[kk * 33 + (lane & 31)] = wv[i]; }
;         __builtin_amdgcn_sched_barrier(0);
;         const int nx = it + ngw;
;         if (nx < nitems) tr_load(W, N, nx, lane, wv);
;         __builtin_amdgcn_sched_barrier(0);
;         tr_store<MAP, HASG, PERMW>(K, N, WT, scr, it, lane, gk);
;         if (nx >= nitems) break;
;         it = nx;
;     }
; }
.Ltc3b_exit:
	v_readlane_b32 s4, v254, 2
	v_readlane_b32 s5, v254, 3
	s_nop 3
	s_and_b32 s6, s60, 0x1000000
	s_add_u32 s4, s4, s6
	s_addc_u32 s5, s5, 0
	s_add_u32 s6, s76, 0x8200000
	s_addc_u32 s7, s77, 0
	s_mov_b32 s9, s18
	s_cmpk_ge_u32 s9, 0x800
	s_cbranch_scc1 .Ltc3c_exit
	s_lshr_b32 s11, s9, 6
	s_and_b32 s12, s9, 63
	s_lshl_b32 s13, s11, 19
	s_lshl_b32 s14, s12, 7
	s_add_u32 s13, s13, s14
	s_add_u32 s14, s4, s13
	s_addc_u32 s15, s5, 0
	global_load_dword v16, v3, s[14:15] nt
	s_add_u32 s14, s14, 0x4000
	s_addc_u32 s15, s15, 0
	global_load_dword v17, v3, s[14:15] nt
	s_add_u32 s14, s14, 0x4000
	s_addc_u32 s15, s15, 0
	global_load_dword v18, v3, s[14:15] nt
	s_add_u32 s14, s14, 0x4000
	s_addc_u32 s15, s15, 0
	global_load_dword v19, v3, s[14:15] nt
	s_add_u32 s14, s14, 0x4000
	s_addc_u32 s15, s15, 0
	global_load_dword v20, v3, s[14:15] nt
	s_add_u32 s14, s14, 0x4000
	s_addc_u32 s15, s15, 0
	global_load_dword v21, v3, s[14:15] nt
	s_add_u32 s14, s14, 0x4000
	s_addc_u32 s15, s15, 0
	global_load_dword v22, v3, s[14:15] nt
	s_add_u32 s14, s14, 0x4000
	s_addc_u32 s15, s15, 0
	global_load_dword v23, v3, s[14:15] nt
	s_add_u32 s14, s14, 0x4000
	s_addc_u32 s15, s15, 0
	global_load_dword v24, v3, s[14:15] nt
	s_add_u32 s14, s14, 0x4000
	s_addc_u32 s15, s15, 0
	global_load_dword v25, v3, s[14:15] nt
	s_add_u32 s14, s14, 0x4000
	s_addc_u32 s15, s15, 0
	global_load_dword v26, v3, s[14:15] nt
	s_add_u32 s14, s14, 0x4000
	s_addc_u32 s15, s15, 0
	global_load_dword v27, v3, s[14:15] nt
	s_add_u32 s14, s14, 0x4000
	s_addc_u32 s15, s15, 0
	global_load_dword v28, v3, s[14:15] nt
	s_add_u32 s14, s14, 0x4000
	s_addc_u32 s15, s15, 0
	global_load_dword v29, v3, s[14:15] nt
	s_add_u32 s14, s14, 0x4000
	s_addc_u32 s15, s15, 0
	global_load_dword v30, v3, s[14:15] nt
	s_add_u32 s14, s14, 0x4000
	s_addc_u32 s15, s15, 0
	global_load_dword v31, v3, s[14:15] nt
	s_add_u32 s14, s14, 0x4000
	s_addc_u32 s15, s15, 0
	global_load_dword v32, v3, s[14:15] nt
	s_add_u32 s14, s14, 0x4000
	s_addc_u32 s15, s15, 0
	global_load_dword v33, v3, s[14:15] nt
	s_add_u32 s14, s14, 0x4000
	s_addc_u32 s15, s15, 0
	global_load_dword v34, v3, s[14:15] nt
	s_add_u32 s14, s14, 0x4000
	s_addc_u32 s15, s15, 0
	global_load_dword v35, v3, s[14:15] nt
	s_add_u32 s14, s14, 0x4000
	s_addc_u32 s15, s15, 0
	global_load_dword v36, v3, s[14:15] nt
	s_add_u32 s14, s14, 0x4000
	s_addc_u32 s15, s15, 0
	global_load_dword v37, v3, s[14:15] nt
	s_add_u32 s14, s14, 0x4000
	s_addc_u32 s15, s15, 0
	global_load_dword v38, v3, s[14:15] nt
	s_add_u32 s14, s14, 0x4000
	s_addc_u32 s15, s15, 0
	global_load_dword v39, v3, s[14:15] nt
	s_add_u32 s14, s14, 0x4000
	s_addc_u32 s15, s15, 0
	global_load_dword v40, v3, s[14:15] nt
	s_add_u32 s14, s14, 0x4000
	s_addc_u32 s15, s15, 0
	global_load_dword v41, v3, s[14:15] nt
	s_add_u32 s14, s14, 0x4000
	s_addc_u32 s15, s15, 0
	global_load_dword v42, v3, s[14:15] nt
	s_add_u32 s14, s14, 0x4000
	s_addc_u32 s15, s15, 0
	global_load_dword v43, v3, s[14:15] nt
	s_add_u32 s14, s14, 0x4000
	s_addc_u32 s15, s15, 0
	global_load_dword v44, v3, s[14:15] nt
	s_add_u32 s14, s14, 0x4000
	s_addc_u32 s15, s15, 0
	global_load_dword v45, v3, s[14:15] nt
	s_add_u32 s14, s14, 0x4000
	s_addc_u32 s15, s15, 0
	global_load_dword v46, v3, s[14:15] nt
	s_add_u32 s14, s14, 0x4000
	s_addc_u32 s15, s15, 0
	global_load_dword v47, v3, s[14:15] nt
	s_lshr_b32 s16, s12, 2
	s_mul_i32 s16, s16, 0x20
	s_add_u32 s16, s16, s11
	s_lshl_b32 s16, s16, 14
	s_and_b32 s17, s12, 3
	s_lshl_b32 s17, s17, 12
	s_add_u32 s16, s16, s17
	s_add_u32 s16, s6, s16
	s_addc_u32 s17, s7, 0
.Ltc3c_loop:
	s_add_u32 s9, s9, 0x400
	s_cmpk_ge_u32 s9, 0x800
	s_cbranch_scc1 .Ltc3c_lastA
	s_lshr_b32 s11, s9, 6
	s_and_b32 s12, s9, 63
	s_lshl_b32 s13, s11, 19
	s_lshl_b32 s14, s12, 7
	s_add_u32 s13, s13, s14
	s_add_u32 s14, s4, s13
	s_addc_u32 s15, s5, 0
	global_load_dword v88, v3, s[14:15] nt
	s_add_u32 s14, s14, 0x4000
	s_addc_u32 s15, s15, 0
	global_load_dword v89, v3, s[14:15] nt
	s_add_u32 s14, s14, 0x4000
	s_addc_u32 s15, s15, 0
	global_load_dword v90, v3, s[14:15] nt
	s_add_u32 s14, s14, 0x4000
	s_addc_u32 s15, s15, 0
	global_load_dword v91, v3, s[14:15] nt
	s_add_u32 s14, s14, 0x4000
	s_addc_u32 s15, s15, 0
	global_load_dword v92, v3, s[14:15] nt
	s_add_u32 s14, s14, 0x4000
	s_addc_u32 s15, s15, 0
	global_load_dword v93, v3, s[14:15] nt
	s_add_u32 s14, s14, 0x4000
	s_addc_u32 s15, s15, 0
	global_load_dword v94, v3, s[14:15] nt
	s_add_u32 s14, s14, 0x4000
	s_addc_u32 s15, s15, 0
	global_load_dword v95, v3, s[14:15] nt
	s_add_u32 s14, s14, 0x4000
	s_addc_u32 s15, s15, 0
	global_load_dword v96, v3, s[14:15] nt
	s_add_u32 s14, s14, 0x4000
	s_addc_u32 s15, s15, 0
	global_load_dword v97, v3, s[14:15] nt
	s_add_u32 s14, s14, 0x4000
	s_addc_u32 s15, s15, 0
	global_load_dword v98, v3, s[14:15] nt
	s_add_u32 s14, s14, 0x4000
	s_addc_u32 s15, s15, 0
	global_load_dword v99, v3, s[14:15] nt
	s_add_u32 s14, s14, 0x4000
	s_addc_u32 s15, s15, 0
	global_load_dword v100, v3, s[14:15] nt
	s_add_u32 s14, s14, 0x4000
	s_addc_u32 s15, s15, 0
	global_load_dword v101, v3, s[14:15] nt
	s_add_u32 s14, s14, 0x4000
	s_addc_u32 s15, s15, 0
	global_load_dword v102, v3, s[14:15] nt
	s_add_u32 s14, s14, 0x4000
	s_addc_u32 s15, s15, 0
	global_load_dword v103, v3, s[14:15] nt
	s_add_u32 s14, s14, 0x4000
	s_addc_u32 s15, s15, 0
	global_load_dword v104, v3, s[14:15] nt
	s_add_u32 s14, s14, 0x4000
	s_addc_u32 s15, s15, 0
	global_load_dword v105, v3, s[14:15] nt
	s_add_u32 s14, s14, 0x4000
	s_addc_u32 s15, s15, 0
	global_load_dword v106, v3, s[14:15] nt
	s_add_u32 s14, s14, 0x4000
	s_addc_u32 s15, s15, 0
	global_load_dword v107, v3, s[14:15] nt
	s_add_u32 s14, s14, 0x4000
	s_addc_u32 s15, s15, 0
	global_load_dword v108, v3, s[14:15] nt
	s_add_u32 s14, s14, 0x4000
	s_addc_u32 s15, s15, 0
	global_load_dword v109, v3, s[14:15] nt
	s_add_u32 s14, s14, 0x4000
	s_addc_u32 s15, s15, 0
	global_load_dword v110, v3, s[14:15] nt
	s_add_u32 s14, s14, 0x4000
	s_addc_u32 s15, s15, 0
	global_load_dword v111, v3, s[14:15] nt
	s_add_u32 s14, s14, 0x4000
	s_addc_u32 s15, s15, 0
	global_load_dword v112, v3, s[14:15] nt
	s_add_u32 s14, s14, 0x4000
	s_addc_u32 s15, s15, 0
	global_load_dword v113, v3, s[14:15] nt
	s_add_u32 s14, s14, 0x4000
	s_addc_u32 s15, s15, 0
	global_load_dword v114, v3, s[14:15] nt
	s_add_u32 s14, s14, 0x4000
	s_addc_u32 s15, s15, 0
	global_load_dword v115, v3, s[14:15] nt
	s_add_u32 s14, s14, 0x4000
	s_addc_u32 s15, s15, 0
	global_load_dword v116, v3, s[14:15] nt
	s_add_u32 s14, s14, 0x4000
	s_addc_u32 s15, s15, 0
	global_load_dword v117, v3, s[14:15] nt
	s_add_u32 s14, s14, 0x4000
	s_addc_u32 s15, s15, 0
	global_load_dword v118, v3, s[14:15] nt
	s_add_u32 s14, s14, 0x4000
	s_addc_u32 s15, s15, 0
	global_load_dword v119, v3, s[14:15] nt
	s_lshr_b32 s24, s12, 2
	s_mul_i32 s24, s24, 0x20
	s_add_u32 s24, s24, s11
	s_lshl_b32 s24, s24, 14
	s_and_b32 s25, s12, 3
	s_lshl_b32 s25, s25, 12
	s_add_u32 s24, s24, s25
	s_add_u32 s24, s6, s24
	s_addc_u32 s25, s7, 0
	s_waitcnt vmcnt(32)
; #define LAS __attribute__((address_space(3)))
; template <int MAP, bool HASG = false, bool PERMW = false>
; __device__ __forceinline__ void transpose_mat(const float* W, int K, int N, bf16_t* WT, LAS float* scr, int gw, int ngw, int lane, const float* gk = nullptr) {
;     const int nitems = (K / 64) * (N / 32);
;     int it = gw;
;     if (it >= nitems) return;
;     float wv[32];
;     tr_load(W, N, it, lane, wv);
;     for (;;) {
;         __builtin_amdgcn_sched_barrier(0);
; #pragma unroll
;         for (int i = 0; i < 32; ++i) { const int kk = 2 * i + (lane >> 5); scr[kk * 33 + (lane & 31)] = wv[i]; }
;         __builtin_amdgcn_sched_barrier(0);
;         const int nx = it + ngw;
;         if (nx < nitems) tr_load(W, N, nx, lane, wv);
;         __builtin_amdgcn_sched_barrier(0);
;         tr_store<MAP, HASG, PERMW>(K, N, WT, scr, it, lane, gk);
;         if (nx >= nitems) break;
;         it = nx;
;     }
; }
	ds_write_b32 v4, v16
	ds_write_b32 v4, v17 offset:264
	ds_write_b32 v4, v18 offset:528
	ds_write_b32 v4, v19 offset:792
	ds_write_b32 v4, v20 offset:1056
	ds_write_b32 v4, v21 offset:1320
	ds_write_b32 v4, v22 offset:1584
	ds_write_b32 v4, v23 offset:1848
	ds_write_b32 v4, v24 offset:2112
	ds_write_b32 v4, v25 offset:2376
	ds_write_b32 v4, v26 offset:2640
	ds_write_b32 v4, v27 offset:2904
	ds_write_b32 v4, v28 offset:3168
	ds_write_b32 v4, v29 offset:3432
	ds_write_b32 v4, v30 offset:3696
	ds_write_b32 v4, v31 offset:3960
	ds_write_b32 v4, v32 offset:4224
	ds_write_b32 v4, v33 offset:4488
	ds_write_b32 v4, v34 offset:4752
	ds_write_b32 v4, v35 offset:5016
	ds_write_b32 v4, v36 offset:5280
	ds_write_b32 v4, v37 offset:5544
	ds_write_b32 v4, v38 offset:5808
	ds_write_b32 v4, v39 offset:6072
	ds_write_b32 v4, v40 offset:6336
	ds_write_b32 v4, v41 offset:6600
	ds_write_b32 v4, v42 offset:6864
	ds_write_b32 v4, v43 offset:7128
	ds_write_b32 v4, v44 offset:7392
	ds_write_b32 v4, v45 offset:7656
	ds_write_b32 v4, v46 offset:7920
	ds_write_b32 v4, v47 offset:8184
	s_waitcnt lgkmcnt(0)
	ds_read_b32 v48, v7
	ds_read_b32 v49, v7 offset:132
	ds_read_b32 v50, v7 offset:264
	ds_read_b32 v51, v7 offset:396
	ds_read_b32 v52, v7 offset:528
	ds_read_b32 v53, v7 offset:660
	ds_read_b32 v54, v7 offset:792
	ds_read_b32 v55, v7 offset:924
	ds_read_b32 v56, v7 offset:32
	ds_read_b32 v57, v7 offset:164
	ds_read_b32 v58, v7 offset:296
	ds_read_b32 v59, v7 offset:428
	ds_read_b32 v60, v7 offset:560
	ds_read_b32 v61, v7 offset:692
	ds_read_b32 v62, v7 offset:824
	ds_read_b32 v63, v7 offset:956
	ds_read_b32 v64, v7 offset:64
	ds_read_b32 v65, v7 offset:196
	ds_read_b32 v66, v7 offset:328
	ds_read_b32 v67, v7 offset:460
	ds_read_b32 v68, v7 offset:592
	ds_read_b32 v69, v7 offset:724
	ds_read_b32 v70, v7 offset:856
	ds_read_b32 v71, v7 offset:988
	ds_read_b32 v72, v7 offset:96
	ds_read_b32 v73, v7 offset:228
	ds_read_b32 v74, v7 offset:360
	ds_read_b32 v75, v7 offset:492
	ds_read_b32 v76, v7 offset:624
	ds_read_b32 v77, v7 offset:756
	ds_read_b32 v78, v7 offset:888
	ds_read_b32 v79, v7 offset:1020
	s_waitcnt lgkmcnt(0)
	v_cvt_pk_bf16_f32 v48, v48, v49
	v_cvt_pk_bf16_f32 v49, v50, v51
	v_cvt_pk_bf16_f32 v50, v52, v53
	v_cvt_pk_bf16_f32 v51, v54, v55
	global_store_dwordx4 v8, v[48:51], s[16:17]
	v_cvt_pk_bf16_f32 v56, v56, v57
	v_cvt_pk_bf16_f32 v57, v58, v59
	v_cvt_pk_bf16_f32 v58, v60, v61
	v_cvt_pk_bf16_f32 v59, v62, v63
	global_store_dwordx4 v9, v[56:59], s[16:17]
	v_cvt_pk_bf16_f32 v64, v64, v65
	v_cvt_pk_bf16_f32 v65, v66, v67
	v_cvt_pk_bf16_f32 v66, v68, v69
	v_cvt_pk_bf16_f32 v67, v70, v71
	global_store_dwordx4 v8, v[64:67], s[16:17] offset:2048
	v_cvt_pk_bf16_f32 v72, v72, v73
	v_cvt_pk_bf16_f32 v73, v74, v75
	v_cvt_pk_bf16_f32 v74, v76, v77
	v_cvt_pk_bf16_f32 v75, v78, v79
	global_store_dwordx4 v9, v[72:75], s[16:17] offset:2048
	s_add_u32 s9, s9, 0x400
	s_cmpk_ge_u32 s9, 0x800
	s_cbranch_scc1 .Ltc3c_lastB
; __device__ __forceinline__ void tr_load(const float* W, int N, int item, int lane, float (&wv)[32]) {
;     const int nblk = N / 32, kb = item / nblk, nb = item % nblk, k0 = 64 * kb, n0 = 32 * nb;
; #pragma unroll
;     for (int i = 0; i < 32; ++i) { const int kk = 2 * i + (lane >> 5); wv[i] = __builtin_nontemporal_load(W + (size_t)(k0 + kk) * N + n0 + (lane & 31)); }
; }
; template <int MAP, bool HASG, bool PERMW>
; __device__ __forceinline__ void tr_store(int K, int N, bf16_t* WT, LAS float* scr, int item, int lane, const float* gk) {
;     const int nblk = N / 32, kb = item / nblk, nb = item % nblk, k0 = 64 * kb, n0 = 32 * nb;
;     asm volatile("s_waitcnt lgkmcnt(0)" ::: "memory");
;     const int c = lane & 7;
;     f32x4 g0 = {1.f, 1.f, 1.f, 1.f}, g1 = {1.f, 1.f, 1.f, 1.f};
;     if (HASG) { g0 = *(const f32x4*)(gk + k0 + 8 * c); g1 = *(const f32x4*)(gk + k0 + 8 * c + 4); }
; #pragma unroll
;     for (int j = 0; j < 4; ++j) { const int n = (lane >> 3) + 8 * j; const LAS float* s = scr + (8 * c) * 33 + n;
;         u32x4 o; o.x = pk2(s[0 * 33] * g0[0], s[1 * 33] * g0[1]); o.y = pk2(s[2 * 33] * g0[2], s[3 * 33] * g0[3]); o.z = pk2(s[4 * 33] * g1[0], s[5 * 33] * g1[1]); o.w = pk2(s[6 * 33] * g1[2], s[7 * 33] * g1[3]);
;         const int wr_ = rowmap<MAP>(n0 + n), slot_ = PERMW ? ((wr_ & ~31) + invperm32(wr_ & 31)) : wr_;
;         *(u32x4*)((char*)WT + tiled_off(slot_, k0 + 8 * c, K / 64)) = o; }
;     asm volatile("s_waitcnt lgkmcnt(0)" ::: "memory");
; }
; template <int MAP, bool HASG = false, bool PERMW = false>
; __device__ __forceinline__ void transpose_mat(const float* W, int K, int N, bf16_t* WT, LAS float* scr, int gw, int ngw, int lane, const float* gk = nullptr) {
;     const int nitems = (K / 64) * (N / 32);
;     int it = gw;
;     if (it >= nitems) return;
;     float wv[32];
;     tr_load(W, N, it, lane, wv);
;     for (;;) {
;         __builtin_amdgcn_sched_barrier(0);
; #pragma unroll
;         for (int i = 0; i < 32; ++i) { const int kk = 2 * i + (lane >> 5); scr[kk * 33 + (lane & 31)] = wv[i]; }
;         __builtin_amdgcn_sched_barrier(0);
;         const int nx = it + ngw;
;         if (nx < nitems) tr_load(W, N, nx, lane, wv);
;         __builtin_amdgcn_sched_barrier(0);
;         tr_store<MAP, HASG, PERMW>(K, N, WT, scr, it, lane, gk);
;         if (nx >= nitems) break;
;         it = nx;
;     }
; }
	s_lshr_b32 s11, s9, 6
	s_and_b32 s12, s9, 63
	s_lshl_b32 s13, s11, 19
	s_lshl_b32 s14, s12, 7
	s_add_u32 s13, s13, s14
	s_add_u32 s14, s4, s13
	s_addc_u32 s15, s5, 0
	global_load_dword v16, v3, s[14:15] nt
	s_add_u32 s14, s14, 0x4000
	s_addc_u32 s15, s15, 0
	global_load_dword v17, v3, s[14:15] nt
	s_add_u32 s14, s14, 0x4000
	s_addc_u32 s15, s15, 0
	global_load_dword v18, v3, s[14:15] nt
	s_add_u32 s14, s14, 0x4000
	s_addc_u32 s15, s15, 0
	global_load_dword v19, v3, s[14:15] nt
	s_add_u32 s14, s14, 0x4000
	s_addc_u32 s15, s15, 0
	global_load_dword v20, v3, s[14:15] nt
	s_add_u32 s14, s14, 0x4000
	s_addc_u32 s15, s15, 0
	global_load_dword v21, v3, s[14:15] nt
	s_add_u32 s14, s14, 0x4000
	s_addc_u32 s15, s15, 0
	global_load_dword v22, v3, s[14:15] nt
	s_add_u32 s14, s14, 0x4000
	s_addc_u32 s15, s15, 0
	global_load_dword v23, v3, s[14:15] nt
	s_add_u32 s14, s14, 0x4000
	s_addc_u32 s15, s15, 0
	global_load_dword v24, v3, s[14:15] nt
	s_add_u32 s14, s14, 0x4000
	s_addc_u32 s15, s15, 0
	global_load_dword v25, v3, s[14:15] nt
	s_add_u32 s14, s14, 0x4000
	s_addc_u32 s15, s15, 0
	global_load_dword v26, v3, s[14:15] nt
	s_add_u32 s14, s14, 0x4000
	s_addc_u32 s15, s15, 0
	global_load_dword v27, v3, s[14:15] nt
	s_add_u32 s14, s14, 0x4000
	s_addc_u32 s15, s15, 0
	global_load_dword v28, v3, s[14:15] nt
	s_add_u32 s14, s14, 0x4000
	s_addc_u32 s15, s15, 0
	global_load_dword v29, v3, s[14:15] nt
	s_add_u32 s14, s14, 0x4000
	s_addc_u32 s15, s15, 0
	global_load_dword v30, v3, s[14:15] nt
	s_add_u32 s14, s14, 0x4000
	s_addc_u32 s15, s15, 0
	global_load_dword v31, v3, s[14:15] nt
	s_add_u32 s14, s14, 0x4000
	s_addc_u32 s15, s15, 0
	global_load_dword v32, v3, s[14:15] nt
	s_add_u32 s14, s14, 0x4000
	s_addc_u32 s15, s15, 0
	global_load_dword v33, v3, s[14:15] nt
	s_add_u32 s14, s14, 0x4000
	s_addc_u32 s15, s15, 0
	global_load_dword v34, v3, s[14:15] nt
	s_add_u32 s14, s14, 0x4000
	s_addc_u32 s15, s15, 0
	global_load_dword v35, v3, s[14:15] nt
	s_add_u32 s14, s14, 0x4000
	s_addc_u32 s15, s15, 0
	global_load_dword v36, v3, s[14:15] nt
	s_add_u32 s14, s14, 0x4000
	s_addc_u32 s15, s15, 0
	global_load_dword v37, v3, s[14:15] nt
	s_add_u32 s14, s14, 0x4000
	s_addc_u32 s15, s15, 0
	global_load_dword v38, v3, s[14:15] nt
	s_add_u32 s14, s14, 0x4000
	s_addc_u32 s15, s15, 0
	global_load_dword v39, v3, s[14:15] nt
	s_add_u32 s14, s14, 0x4000
	s_addc_u32 s15, s15, 0
	global_load_dword v40, v3, s[14:15] nt
	s_add_u32 s14, s14, 0x4000
	s_addc_u32 s15, s15, 0
	global_load_dword v41, v3, s[14:15] nt
	s_add_u32 s14, s14, 0x4000
	s_addc_u32 s15, s15, 0
	global_load_dword v42, v3, s[14:15] nt
	s_add_u32 s14, s14, 0x4000
	s_addc_u32 s15, s15, 0
	global_load_dword v43, v3, s[14:15] nt
	s_add_u32 s14, s14, 0x4000
	s_addc_u32 s15, s15, 0
	global_load_dword v44, v3, s[14:15] nt
	s_add_u32 s14, s14, 0x4000
	s_addc_u32 s15, s15, 0
	global_load_dword v45, v3, s[14:15] nt
	s_add_u32 s14, s14, 0x4000
	s_addc_u32 s15, s15, 0
	global_load_dword v46, v3, s[14:15] nt
	s_add_u32 s14, s14, 0x4000
	s_addc_u32 s15, s15, 0
	global_load_dword v47, v3, s[14:15] nt
	s_lshr_b32 s16, s12, 2
	s_mul_i32 s16, s16, 0x20
	s_add_u32 s16, s16, s11
	s_lshl_b32 s16, s16, 14
	s_and_b32 s17, s12, 3
	s_lshl_b32 s17, s17, 12
	s_add_u32 s16, s16, s17
	s_add_u32 s16, s6, s16
	s_addc_u32 s17, s7, 0
	s_waitcnt vmcnt(32)
	ds_write_b32 v4, v88
	ds_write_b32 v4, v89 offset:264
	ds_write_b32 v4, v90 offset:528
	ds_write_b32 v4, v91 offset:792
	ds_write_b32 v4, v92 offset:1056
	ds_write_b32 v4, v93 offset:1320
	ds_write_b32 v4, v94 offset:1584
	ds_write_b32 v4, v95 offset:1848
	ds_write_b32 v4, v96 offset:2112
	ds_write_b32 v4, v97 offset:2376
	ds_write_b32 v4, v98 offset:2640
	ds_write_b32 v4, v99 offset:2904
	ds_write_b32 v4, v100 offset:3168
	ds_write_b32 v4, v101 offset:3432
	ds_write_b32 v4, v102 offset:3696
	ds_write_b32 v4, v103 offset:3960
	ds_write_b32 v4, v104 offset:4224
	ds_write_b32 v4, v105 offset:4488
	ds_write_b32 v4, v106 offset:4752
	ds_write_b32 v4, v107 offset:5016
	ds_write_b32 v4, v108 offset:5280
	ds_write_b32 v4, v109 offset:5544
	ds_write_b32 v4, v110 offset:5808
	ds_write_b32 v4, v111 offset:6072
	ds_write_b32 v4, v112 offset:6336
	ds_write_b32 v4, v113 offset:6600
	ds_write_b32 v4, v114 offset:6864
	ds_write_b32 v4, v115 offset:7128
	ds_write_b32 v4, v116 offset:7392
	ds_write_b32 v4, v117 offset:7656
	ds_write_b32 v4, v118 offset:7920
	ds_write_b32 v4, v119 offset:8184
	s_waitcnt lgkmcnt(0)
	ds_read_b32 v48, v7
	ds_read_b32 v49, v7 offset:132
	ds_read_b32 v50, v7 offset:264
	ds_read_b32 v51, v7 offset:396
	ds_read_b32 v52, v7 offset:528
	ds_read_b32 v53, v7 offset:660
	ds_read_b32 v54, v7 offset:792
	ds_read_b32 v55, v7 offset:924
	ds_read_b32 v56, v7 offset:32
	ds_read_b32 v57, v7 offset:164
	ds_read_b32 v58, v7 offset:296
	ds_read_b32 v59, v7 offset:428
	ds_read_b32 v60, v7 offset:560
	ds_read_b32 v61, v7 offset:692
	ds_read_b32 v62, v7 offset:824
	ds_read_b32 v63, v7 offset:956
	ds_read_b32 v64, v7 offset:64
	ds_read_b32 v65, v7 offset:196
	ds_read_b32 v66, v7 offset:328
	ds_read_b32 v67, v7 offset:460
	ds_read_b32 v68, v7 offset:592
	ds_read_b32 v69, v7 offset:724
	ds_read_b32 v70, v7 offset:856
	ds_read_b32 v71, v7 offset:988
	ds_read_b32 v72, v7 offset:96
	ds_read_b32 v73, v7 offset:228
	ds_read_b32 v74, v7 offset:360
	ds_read_b32 v75, v7 offset:492
	ds_read_b32 v76, v7 offset:624
	ds_read_b32 v77, v7 offset:756
	ds_read_b32 v78, v7 offset:888
	ds_read_b32 v79, v7 offset:1020
	s_waitcnt lgkmcnt(0)
	v_cvt_pk_bf16_f32 v48, v48, v49
	v_cvt_pk_bf16_f32 v49, v50, v51
	v_cvt_pk_bf16_f32 v50, v52, v53
	v_cvt_pk_bf16_f32 v51, v54, v55
	global_store_dwordx4 v8, v[48:51], s[24:25]
	v_cvt_pk_bf16_f32 v56, v56, v57
	v_cvt_pk_bf16_f32 v57, v58, v59
	v_cvt_pk_bf16_f32 v58, v60, v61
	v_cvt_pk_bf16_f32 v59, v62, v63
	global_store_dwordx4 v9, v[56:59], s[24:25]
	v_cvt_pk_bf16_f32 v64, v64, v65
	v_cvt_pk_bf16_f32 v65, v66, v67
	v_cvt_pk_bf16_f32 v66, v68, v69
	v_cvt_pk_bf16_f32 v67, v70, v71
	global_store_dwordx4 v8, v[64:67], s[24:25] offset:2048
	v_cvt_pk_bf16_f32 v72, v72, v73
	v_cvt_pk_bf16_f32 v73, v74, v75
	v_cvt_pk_bf16_f32 v74, v76, v77
	v_cvt_pk_bf16_f32 v75, v78, v79
	global_store_dwordx4 v9, v[72:75], s[24:25] offset:2048
	s_branch .Ltc3c_loop

; __device__ __forceinline__ void tr_load(const float* W, int N, int item, int lane, float (&wv)[32]) {
;     const int nblk = N / 32, kb = item / nblk, nb = item % nblk, k0 = 64 * kb, n0 = 32 * nb;
; #pragma unroll
;     for (int i = 0; i < 32; ++i) { const int kk = 2 * i + (lane >> 5); wv[i] = __builtin_nontemporal_load(W + (size_t)(k0 + kk) * N + n0 + (lane & 31)); }
; }
; template <int MAP, bool HASG, bool PERMW>
; __device__ __forceinline__ void tr_store(int K, int N, bf16_t* WT, LAS float* scr, int item, int lane, const float* gk) {
;     const int nblk = N / 32, kb = item / nblk, nb = item % nblk, k0 = 64 * kb, n0 = 32 * nb;
;     asm volatile("s_waitcnt lgkmcnt(0)" ::: "memory");
;     const int c = lane & 7;
;     f32x4 g0 = {1.f, 1.f, 1.f, 1.f}, g1 = {1.f, 1.f, 1.f, 1.f};
;     if (HASG) { g0 = *(const f32x4*)(gk + k0 + 8 * c); g1 = *(const f32x4*)(gk + k0 + 8 * c + 4); }
; #pragma unroll
;     for (int j = 0; j < 4; ++j) { const int n = (lane >> 3) + 8 * j; const LAS float* s = scr + (8 * c) * 33 + n;
;         u32x4 o; o.x = pk2(s[0 * 33] * g0[0], s[1 * 33] * g0[1]); o.y = pk2(s[2 * 33] * g0[2], s[3 * 33] * g0[3]); o.z = pk2(s[4 * 33] * g1[0], s[5 * 33] * g1[1]); o.w = pk2(s[6 * 33] * g1[2], s[7 * 33] * g1[3]);
;         const int wr_ = rowmap<MAP>(n0 + n), slot_ = PERMW ? ((wr_ & ~31) + invperm32(wr_ & 31)) : wr_;
;         *(u32x4*)((char*)WT + tiled_off(slot_, k0 + 8 * c, K / 64)) = o; }
;     asm volatile("s_waitcnt lgkmcnt(0)" ::: "memory");
; }
; template <int MAP, bool HASG = false, bool PERMW = false>
; __device__ __forceinline__ void transpose_mat(const float* W, int K, int N, bf16_t* WT, LAS float* scr, int gw, int ngw, int lane, const float* gk = nullptr) {
;     const int nitems = (K / 64) * (N / 32);
;     int it = gw;
;     if (it >= nitems) return;
;     float wv[32];
;     tr_load(W, N, it, lane, wv);
;     for (;;) {
;         __builtin_amdgcn_sched_barrier(0);
; #pragma unroll
;         for (int i = 0; i < 32; ++i) { const int kk = 2 * i + (lane >> 5); scr[kk * 33 + (lane & 31)] = wv[i]; }
;         __builtin_amdgcn_sched_barrier(0);
;         const int nx = it + ngw;
;         if (nx < nitems) tr_load(W, N, nx, lane, wv);
;         __builtin_amdgcn_sched_barrier(0);
;         tr_store<MAP, HASG, PERMW>(K, N, WT, scr, it, lane, gk);
;         if (nx >= nitems) break;
;         it = nx;
;     }
; }
.Ltc3c_exit:
	v_readlane_b32 s4, v254, 8
	v_readlane_b32 s5, v254, 9
	v_readlane_b32 s20, v254, 4
	v_readlane_b32 s21, v254, 5
	s_nop 3
	s_and_b32 s6, s60, 0x2c00000
	s_add_u32 s4, s4, s6
	s_addc_u32 s5, s5, 0
	s_and_b32 s6, s60, 0x2000
	s_add_u32 s20, s20, s6
	s_addc_u32 s21, s21, 0
	s_add_u32 s6, s76, 0x8a00000
	s_addc_u32 s7, s77, 0
	s_mov_b32 s9, s18
	s_cmpk_ge_u32 s9, 0x1600
	s_cbranch_scc1 .Ltc3d_exit
	s_mul_hi_u32 s11, s9, 0x2e8ba2e9
	s_lshr_b32 s11, s11, 5
	s_mul_i32 s12, s11, 0xb0
	s_sub_u32 s12, s9, s12
	s_mul_i32 s13, s11, 0x160000
	s_lshl_b32 s14, s12, 7
	s_add_u32 s13, s13, s14
	s_add_u32 s14, s4, s13
	s_addc_u32 s15, s5, 0
	global_load_dword v16, v15, s[14:15] nt
	s_add_u32 s14, s14, 0xb000
	s_addc_u32 s15, s15, 0
	global_load_dword v17, v15, s[14:15] nt
	s_add_u32 s14, s14, 0xb000
	s_addc_u32 s15, s15, 0
	global_load_dword v18, v15, s[14:15] nt
	s_add_u32 s14, s14, 0xb000
	s_addc_u32 s15, s15, 0
	global_load_dword v19, v15, s[14:15] nt
	s_add_u32 s14, s14, 0xb000
	s_addc_u32 s15, s15, 0
	global_load_dword v20, v15, s[14:15] nt
	s_add_u32 s14, s14, 0xb000
	s_addc_u32 s15, s15, 0
	global_load_dword v21, v15, s[14:15] nt
	s_add_u32 s14, s14, 0xb000
	s_addc_u32 s15, s15, 0
	global_load_dword v22, v15, s[14:15] nt
	s_add_u32 s14, s14, 0xb000
	s_addc_u32 s15, s15, 0
	global_load_dword v23, v15, s[14:15] nt
	s_add_u32 s14, s14, 0xb000
	s_addc_u32 s15, s15, 0
	global_load_dword v24, v15, s[14:15] nt
	s_add_u32 s14, s14, 0xb000
	s_addc_u32 s15, s15, 0
	global_load_dword v25, v15, s[14:15] nt
	s_add_u32 s14, s14, 0xb000
	s_addc_u32 s15, s15, 0
	global_load_dword v26, v15, s[14:15] nt
	s_add_u32 s14, s14, 0xb000
	s_addc_u32 s15, s15, 0
	global_load_dword v27, v15, s[14:15] nt
	s_add_u32 s14, s14, 0xb000
	s_addc_u32 s15, s15, 0
	global_load_dword v28, v15, s[14:15] nt
	s_add_u32 s14, s14, 0xb000
	s_addc_u32 s15, s15, 0
	global_load_dword v29, v15, s[14:15] nt
	s_add_u32 s14, s14, 0xb000
	s_addc_u32 s15, s15, 0
	global_load_dword v30, v15, s[14:15] nt
	s_add_u32 s14, s14, 0xb000
	s_addc_u32 s15, s15, 0
	global_load_dword v31, v15, s[14:15] nt
	s_add_u32 s14, s14, 0xb000
	s_addc_u32 s15, s15, 0
	global_load_dword v32, v15, s[14:15] nt
	s_add_u32 s14, s14, 0xb000
	s_addc_u32 s15, s15, 0
	global_load_dword v33, v15, s[14:15] nt
	s_add_u32 s14, s14, 0xb000
	s_addc_u32 s15, s15, 0
	global_load_dword v34, v15, s[14:15] nt
	s_add_u32 s14, s14, 0xb000
	s_addc_u32 s15, s15, 0
	global_load_dword v35, v15, s[14:15] nt
	s_add_u32 s14, s14, 0xb000
	s_addc_u32 s15, s15, 0
	global_load_dword v36, v15, s[14:15] nt
	s_add_u32 s14, s14, 0xb000
	s_addc_u32 s15, s15, 0
	global_load_dword v37, v15, s[14:15] nt
	s_add_u32 s14, s14, 0xb000
	s_addc_u32 s15, s15, 0
	global_load_dword v38, v15, s[14:15] nt
	s_add_u32 s14, s14, 0xb000
	s_addc_u32 s15, s15, 0
	global_load_dword v39, v15, s[14:15] nt
	s_add_u32 s14, s14, 0xb000
	s_addc_u32 s15, s15, 0
	global_load_dword v40, v15, s[14:15] nt
	s_add_u32 s14, s14, 0xb000
	s_addc_u32 s15, s15, 0
	global_load_dword v41, v15, s[14:15] nt
	s_add_u32 s14, s14, 0xb000
	s_addc_u32 s15, s15, 0
	global_load_dword v42, v15, s[14:15] nt
	s_add_u32 s14, s14, 0xb000
	s_addc_u32 s15, s15, 0
	global_load_dword v43, v15, s[14:15] nt
	s_add_u32 s14, s14, 0xb000
	s_addc_u32 s15, s15, 0
	global_load_dword v44, v15, s[14:15] nt
	s_add_u32 s14, s14, 0xb000
	s_addc_u32 s15, s15, 0
	global_load_dword v45, v15, s[14:15] nt
	s_add_u32 s14, s14, 0xb000
	s_addc_u32 s15, s15, 0
	global_load_dword v46, v15, s[14:15] nt
	s_add_u32 s14, s14, 0xb000
	s_addc_u32 s15, s15, 0
	global_load_dword v47, v15, s[14:15] nt
	s_lshl_b32 s14, s11, 8
	s_add_u32 s14, s20, s14
	s_addc_u32 s15, s21, 0
	global_load_dwordx4 v[80:83], v14, s[14:15]
	global_load_dwordx4 v[84:87], v14, s[14:15] offset:16
	s_lshr_b32 s16, s12, 2
	s_lshl_b32 s16, s16, 1
	s_add_u32 s16, s16, 1
	s_lshl_b32 s16, s16, 5
	s_add_u32 s16, s16, s11
	s_lshl_b32 s16, s16, 14
	s_and_b32 s17, s12, 3
	s_lshl_b32 s17, s17, 12
	s_add_u32 s16, s16, s17
	s_add_u32 s16, s6, s16
	s_addc_u32 s17, s7, 0
.Ltc3d_loop:
	s_add_u32 s9, s9, 0x400
	s_cmpk_ge_u32 s9, 0x1600
	s_cbranch_scc1 .Ltc3d_lastA
	s_mul_hi_u32 s11, s9, 0x2e8ba2e9
	s_lshr_b32 s11, s11, 5
	s_mul_i32 s12, s11, 0xb0
	s_sub_u32 s12, s9, s12
	s_mul_i32 s13, s11, 0x160000
	s_lshl_b32 s14, s12, 7
	s_add_u32 s13, s13, s14
	s_add_u32 s14, s4, s13
	s_addc_u32 s15, s5, 0
	global_load_dword v88, v15, s[14:15] nt
	s_add_u32 s14, s14, 0xb000
	s_addc_u32 s15, s15, 0
	global_load_dword v89, v15, s[14:15] nt
	s_add_u32 s14, s14, 0xb000
	s_addc_u32 s15, s15, 0
	global_load_dword v90, v15, s[14:15] nt
	s_add_u32 s14, s14, 0xb000
	s_addc_u32 s15, s15, 0
	global_load_dword v91, v15, s[14:15] nt
	s_add_u32 s14, s14, 0xb000
	s_addc_u32 s15, s15, 0
	global_load_dword v92, v15, s[14:15] nt
	s_add_u32 s14, s14, 0xb000
	s_addc_u32 s15, s15, 0
	global_load_dword v93, v15, s[14:15] nt
	s_add_u32 s14, s14, 0xb000
	s_addc_u32 s15, s15, 0
	global_load_dword v94, v15, s[14:15] nt
	s_add_u32 s14, s14, 0xb000
	s_addc_u32 s15, s15, 0
	global_load_dword v95, v15, s[14:15] nt
	s_add_u32 s14, s14, 0xb000
	s_addc_u32 s15, s15, 0
	global_load_dword v96, v15, s[14:15] nt
	s_add_u32 s14, s14, 0xb000
	s_addc_u32 s15, s15, 0
	global_load_dword v97, v15, s[14:15] nt
	s_add_u32 s14, s14, 0xb000
	s_addc_u32 s15, s15, 0
	global_load_dword v98, v15, s[14:15] nt
	s_add_u32 s14, s14, 0xb000
	s_addc_u32 s15, s15, 0
	global_load_dword v99, v15, s[14:15] nt
	s_add_u32 s14, s14, 0xb000
	s_addc_u32 s15, s15, 0
	global_load_dword v100, v15, s[14:15] nt
	s_add_u32 s14, s14, 0xb000
	s_addc_u32 s15, s15, 0
	global_load_dword v101, v15, s[14:15] nt
	s_add_u32 s14, s14, 0xb000
	s_addc_u32 s15, s15, 0
; __device__ __forceinline__ void tr_load(const float* W, int N, int item, int lane, float (&wv)[32]) {
;     const int nblk = N / 32, kb = item / nblk, nb = item % nblk, k0 = 64 * kb, n0 = 32 * nb;
; #pragma unroll
;     for (int i = 0; i < 32; ++i) { const int kk = 2 * i + (lane >> 5); wv[i] = __builtin_nontemporal_load(W + (size_t)(k0 + kk) * N + n0 + (lane & 31)); }
; }
; template <int MAP, bool HASG, bool PERMW>
; __device__ __forceinline__ void tr_store(int K, int N, bf16_t* WT, LAS float* scr, int item, int lane, const float* gk) {
;     const int nblk = N / 32, kb = item / nblk, nb = item % nblk, k0 = 64 * kb, n0 = 32 * nb;
;     asm volatile("s_waitcnt lgkmcnt(0)" ::: "memory");
;     const int c = lane & 7;
;     f32x4 g0 = {1.f, 1.f, 1.f, 1.f}, g1 = {1.f, 1.f, 1.f, 1.f};
;     if (HASG) { g0 = *(const f32x4*)(gk + k0 + 8 * c); g1 = *(const f32x4*)(gk + k0 + 8 * c + 4); }
; #pragma unroll
;     for (int j = 0; j < 4; ++j) { const int n = (lane >> 3) + 8 * j; const LAS float* s = scr + (8 * c) * 33 + n;
;         u32x4 o; o.x = pk2(s[0 * 33] * g0[0], s[1 * 33] * g0[1]); o.y = pk2(s[2 * 33] * g0[2], s[3 * 33] * g0[3]); o.z = pk2(s[4 * 33] * g1[0], s[5 * 33] * g1[1]); o.w = pk2(s[6 * 33] * g1[2], s[7 * 33] * g1[3]);
;         const int wr_ = rowmap<MAP>(n0 + n), slot_ = PERMW ? ((wr_ & ~31) + invperm32(wr_ & 31)) : wr_;
;         *(u32x4*)((char*)WT + tiled_off(slot_, k0 + 8 * c, K / 64)) = o; }
;     asm volatile("s_waitcnt lgkmcnt(0)" ::: "memory");
; }
; template <int MAP, bool HASG = false, bool PERMW = false>
; __device__ __forceinline__ void transpose_mat(const float* W, int K, int N, bf16_t* WT, LAS float* scr, int gw, int ngw, int lane, const float* gk = nullptr) {
;     const int nitems = (K / 64) * (N / 32);
;     int it = gw;
;     if (it >= nitems) return;
;     float wv[32];
;     tr_load(W, N, it, lane, wv);
;     for (;;) {
;         __builtin_amdgcn_sched_barrier(0);
; #pragma unroll
;         for (int i = 0; i < 32; ++i) { const int kk = 2 * i + (lane >> 5); scr[kk * 33 + (lane & 31)] = wv[i]; }
;         __builtin_amdgcn_sched_barrier(0);
;         const int nx = it + ngw;
;         if (nx < nitems) tr_load(W, N, nx, lane, wv);
;         __builtin_amdgcn_sched_barrier(0);
;         tr_store<MAP, HASG, PERMW>(K, N, WT, scr, it, lane, gk);
;         if (nx >= nitems) break;
;         it = nx;
;     }
; }
	global_load_dword v102, v15, s[14:15] nt
	s_add_u32 s14, s14, 0xb000
	s_addc_u32 s15, s15, 0
	global_load_dword v103, v15, s[14:15] nt
	s_add_u32 s14, s14, 0xb000
	s_addc_u32 s15, s15, 0
	global_load_dword v104, v15, s[14:15] nt
	s_add_u32 s14, s14, 0xb000
	s_addc_u32 s15, s15, 0
	global_load_dword v105, v15, s[14:15] nt
	s_add_u32 s14, s14, 0xb000
	s_addc_u32 s15, s15, 0
	global_load_dword v106, v15, s[14:15] nt
	s_add_u32 s14, s14, 0xb000
	s_addc_u32 s15, s15, 0
	global_load_dword v107, v15, s[14:15] nt
	s_add_u32 s14, s14, 0xb000
	s_addc_u32 s15, s15, 0
	global_load_dword v108, v15, s[14:15] nt
	s_add_u32 s14, s14, 0xb000
	s_addc_u32 s15, s15, 0
	global_load_dword v109, v15, s[14:15] nt
	s_add_u32 s14, s14, 0xb000
	s_addc_u32 s15, s15, 0
	global_load_dword v110, v15, s[14:15] nt
	s_add_u32 s14, s14, 0xb000
	s_addc_u32 s15, s15, 0
	global_load_dword v111, v15, s[14:15] nt
	s_add_u32 s14, s14, 0xb000
	s_addc_u32 s15, s15, 0
	global_load_dword v112, v15, s[14:15] nt
	s_add_u32 s14, s14, 0xb000
	s_addc_u32 s15, s15, 0
	global_load_dword v113, v15, s[14:15] nt
	s_add_u32 s14, s14, 0xb000
	s_addc_u32 s15, s15, 0
	global_load_dword v114, v15, s[14:15] nt
	s_add_u32 s14, s14, 0xb000
	s_addc_u32 s15, s15, 0
	global_load_dword v115, v15, s[14:15] nt
	s_add_u32 s14, s14, 0xb000
	s_addc_u32 s15, s15, 0
	global_load_dword v116, v15, s[14:15] nt
	s_add_u32 s14, s14, 0xb000
	s_addc_u32 s15, s15, 0
	global_load_dword v117, v15, s[14:15] nt
	s_add_u32 s14, s14, 0xb000
	s_addc_u32 s15, s15, 0
	global_load_dword v118, v15, s[14:15] nt
	s_add_u32 s14, s14, 0xb000
	s_addc_u32 s15, s15, 0
	global_load_dword v119, v15, s[14:15] nt
	s_lshl_b32 s14, s11, 8
	s_add_u32 s14, s20, s14
	s_addc_u32 s15, s21, 0
	global_load_dwordx4 v[120:123], v14, s[14:15]
	global_load_dwordx4 v[124:127], v14, s[14:15] offset:16
	s_lshr_b32 s24, s12, 2
	s_lshl_b32 s24, s24, 1
	s_add_u32 s24, s24, 1
	s_lshl_b32 s24, s24, 5
	s_add_u32 s24, s24, s11
	s_lshl_b32 s24, s24, 14
	s_and_b32 s25, s12, 3
	s_lshl_b32 s25, s25, 12
	s_add_u32 s24, s24, s25
	s_add_u32 s24, s6, s24
	s_addc_u32 s25, s7, 0
	s_waitcnt vmcnt(34)
	ds_write_b32 v4, v16
	ds_write_b32 v4, v17 offset:264
	ds_write_b32 v4, v18 offset:528
	ds_write_b32 v4, v19 offset:792
	ds_write_b32 v4, v20 offset:1056
	ds_write_b32 v4, v21 offset:1320
	ds_write_b32 v4, v22 offset:1584
	ds_write_b32 v4, v23 offset:1848
	ds_write_b32 v4, v24 offset:2112
	ds_write_b32 v4, v25 offset:2376
	ds_write_b32 v4, v26 offset:2640
	ds_write_b32 v4, v27 offset:2904
	ds_write_b32 v4, v28 offset:3168
	ds_write_b32 v4, v29 offset:3432
	ds_write_b32 v4, v30 offset:3696
	ds_write_b32 v4, v31 offset:3960
	ds_write_b32 v4, v32 offset:4224
	ds_write_b32 v4, v33 offset:4488
	ds_write_b32 v4, v34 offset:4752
	ds_write_b32 v4, v35 offset:5016
	ds_write_b32 v4, v36 offset:5280
	ds_write_b32 v4, v37 offset:5544
	ds_write_b32 v4, v38 offset:5808
	ds_write_b32 v4, v39 offset:6072
	ds_write_b32 v4, v40 offset:6336
	ds_write_b32 v4, v41 offset:6600
	ds_write_b32 v4, v42 offset:6864
	ds_write_b32 v4, v43 offset:7128
	ds_write_b32 v4, v44 offset:7392
	ds_write_b32 v4, v45 offset:7656
	ds_write_b32 v4, v46 offset:7920
	ds_write_b32 v4, v47 offset:8184
	s_waitcnt lgkmcnt(0)
	ds_read_b32 v48, v7
	ds_read_b32 v49, v7 offset:132
	ds_read_b32 v50, v7 offset:264
	ds_read_b32 v51, v7 offset:396
	ds_read_b32 v52, v7 offset:528
	ds_read_b32 v53, v7 offset:660
	ds_read_b32 v54, v7 offset:792
	ds_read_b32 v55, v7 offset:924
	ds_read_b32 v56, v7 offset:32
	ds_read_b32 v57, v7 offset:164
	ds_read_b32 v58, v7 offset:296
	ds_read_b32 v59, v7 offset:428
	ds_read_b32 v60, v7 offset:560
	ds_read_b32 v61, v7 offset:692
	ds_read_b32 v62, v7 offset:824
	ds_read_b32 v63, v7 offset:956
	ds_read_b32 v64, v7 offset:64
	ds_read_b32 v65, v7 offset:196
	ds_read_b32 v66, v7 offset:328
	ds_read_b32 v67, v7 offset:460
	ds_read_b32 v68, v7 offset:592
	ds_read_b32 v69, v7 offset:724
	ds_read_b32 v70, v7 offset:856
	ds_read_b32 v71, v7 offset:988
	ds_read_b32 v72, v7 offset:96
	ds_read_b32 v73, v7 offset:228
	ds_read_b32 v74, v7 offset:360
	ds_read_b32 v75, v7 offset:492
	ds_read_b32 v76, v7 offset:624
	ds_read_b32 v77, v7 offset:756
	ds_read_b32 v78, v7 offset:888
	ds_read_b32 v79, v7 offset:1020
	s_waitcnt lgkmcnt(0)
	v_mul_f32_e32 v48, v48, v80
	v_mul_f32_e32 v49, v49, v81
	v_mul_f32_e32 v50, v50, v82
	v_mul_f32_e32 v51, v51, v83
	v_mul_f32_e32 v52, v52, v84
	v_mul_f32_e32 v53, v53, v85
	v_mul_f32_e32 v54, v54, v86
	v_mul_f32_e32 v55, v55, v87
	v_cvt_pk_bf16_f32 v48, v48, v49
	v_cvt_pk_bf16_f32 v49, v50, v51
	v_cvt_pk_bf16_f32 v50, v52, v53
	v_cvt_pk_bf16_f32 v51, v54, v55
	global_store_dwordx4 v10, v[48:51], s[16:17]
	v_mul_f32_e32 v56, v56, v80
	v_mul_f32_e32 v57, v57, v81
	v_mul_f32_e32 v58, v58, v82
	v_mul_f32_e32 v59, v59, v83
	v_mul_f32_e32 v60, v60, v84
	v_mul_f32_e32 v61, v61, v85
	v_mul_f32_e32 v62, v62, v86
	v_mul_f32_e32 v63, v63, v87
	v_cvt_pk_bf16_f32 v56, v56, v57
	v_cvt_pk_bf16_f32 v57, v58, v59
	v_cvt_pk_bf16_f32 v58, v60, v61
	v_cvt_pk_bf16_f32 v59, v62, v63
	global_store_dwordx4 v10, v[56:59], s[16:17] offset:256
	v_mul_f32_e32 v64, v64, v80
	v_mul_f32_e32 v65, v65, v81
	v_mul_f32_e32 v66, v66, v82
	v_mul_f32_e32 v67, v67, v83
	v_mul_f32_e32 v68, v68, v84
	v_mul_f32_e32 v69, v69, v85
	v_mul_f32_e32 v70, v70, v86
	v_mul_f32_e32 v71, v71, v87
	v_cvt_pk_bf16_f32 v64, v64, v65
	v_cvt_pk_bf16_f32 v65, v66, v67
	v_cvt_pk_bf16_f32 v66, v68, v69
	v_cvt_pk_bf16_f32 v67, v70, v71
	global_store_dwordx4 v11, v[64:67], s[16:17] offset:512
	v_mul_f32_e32 v72, v72, v80
	v_mul_f32_e32 v73, v73, v81
	v_mul_f32_e32 v74, v74, v82
	v_mul_f32_e32 v75, v75, v83
	v_mul_f32_e32 v76, v76, v84
	v_mul_f32_e32 v77, v77, v85
	v_mul_f32_e32 v78, v78, v86
	v_mul_f32_e32 v79, v79, v87
	v_cvt_pk_bf16_f32 v72, v72, v73
	v_cvt_pk_bf16_f32 v73, v74, v75
	v_cvt_pk_bf16_f32 v74, v76, v77
	v_cvt_pk_bf16_f32 v75, v78, v79
	global_store_dwordx4 v11, v[72:75], s[16:17] offset:768
	s_add_u32 s9, s9, 0x400
	s_cmpk_ge_u32 s9, 0x1600
	s_cbranch_scc1 .Ltc3d_lastB
; __device__ __forceinline__ void tr_load(const float* W, int N, int item, int lane, float (&wv)[32]) {
;     const int nblk = N / 32, kb = item / nblk, nb = item % nblk, k0 = 64 * kb, n0 = 32 * nb;
; #pragma unroll
;     for (int i = 0; i < 32; ++i) { const int kk = 2 * i + (lane >> 5); wv[i] = __builtin_nontemporal_load(W + (size_t)(k0 + kk) * N + n0 + (lane & 31)); }
; }
; template <int MAP, bool HASG, bool PERMW>
; __device__ __forceinline__ void tr_store(int K, int N, bf16_t* WT, LAS float* scr, int item, int lane, const float* gk) {
;     ...
;     if (HASG) { g0 = *(const f32x4*)(gk + k0 + 8 * c); g1 = *(const f32x4*)(gk + k0 + 8 * c + 4); }
	s_mul_hi_u32 s11, s9, 0x2e8ba2e9
	s_lshr_b32 s11, s11, 5
	s_mul_i32 s12, s11, 0xb0
	s_sub_u32 s12, s9, s12
	s_mul_i32 s13, s11, 0x160000
	s_lshl_b32 s14, s12, 7
	s_add_u32 s13, s13, s14
	s_add_u32 s14, s4, s13
	s_addc_u32 s15, s5, 0
	global_load_dword v16, v15, s[14:15] nt
	s_add_u32 s14, s14, 0xb000
	s_addc_u32 s15, s15, 0
	global_load_dword v17, v15, s[14:15] nt
	s_add_u32 s14, s14, 0xb000
	s_addc_u32 s15, s15, 0
	global_load_dword v18, v15, s[14:15] nt
	s_add_u32 s14, s14, 0xb000
	s_addc_u32 s15, s15, 0
	global_load_dword v19, v15, s[14:15] nt
	s_add_u32 s14, s14, 0xb000
	s_addc_u32 s15, s15, 0
	global_load_dword v20, v15, s[14:15] nt
	s_add_u32 s14, s14, 0xb000
	s_addc_u32 s15, s15, 0
	global_load_dword v21, v15, s[14:15] nt
	s_add_u32 s14, s14, 0xb000
	s_addc_u32 s15, s15, 0
	global_load_dword v22, v15, s[14:15] nt
	s_add_u32 s14, s14, 0xb000
	s_addc_u32 s15, s15, 0
	global_load_dword v23, v15, s[14:15] nt
	s_add_u32 s14, s14, 0xb000
	s_addc_u32 s15, s15, 0
	global_load_dword v24, v15, s[14:15] nt
	s_add_u32 s14, s14, 0xb000
	s_addc_u32 s15, s15, 0
	global_load_dword v25, v15, s[14:15] nt
	s_add_u32 s14, s14, 0xb000
	s_addc_u32 s15, s15, 0
	global_load_dword v26, v15, s[14:15] nt
	s_add_u32 s14, s14, 0xb000
	s_addc_u32 s15, s15, 0
	global_load_dword v27, v15, s[14:15] nt
	s_add_u32 s14, s14, 0xb000
	s_addc_u32 s15, s15, 0
	global_load_dword v28, v15, s[14:15] nt
	s_add_u32 s14, s14, 0xb000
	s_addc_u32 s15, s15, 0
	global_load_dword v29, v15, s[14:15] nt
	s_add_u32 s14, s14, 0xb000
	s_addc_u32 s15, s15, 0
	global_load_dword v30, v15, s[14:15] nt
	s_add_u32 s14, s14, 0xb000
	s_addc_u32 s15, s15, 0
	global_load_dword v31, v15, s[14:15] nt
	s_add_u32 s14, s14, 0xb000
	s_addc_u32 s15, s15, 0
	global_load_dword v32, v15, s[14:15] nt
	s_add_u32 s14, s14, 0xb000
	s_addc_u32 s15, s15, 0
	global_load_dword v33, v15, s[14:15] nt
	s_add_u32 s14, s14, 0xb000
	s_addc_u32 s15, s15, 0
	global_load_dword v34, v15, s[14:15] nt
	s_add_u32 s14, s14, 0xb000
	s_addc_u32 s15, s15, 0
	global_load_dword v35, v15, s[14:15] nt
	s_add_u32 s14, s14, 0xb000
	s_addc_u32 s15, s15, 0
	global_load_dword v36, v15, s[14:15] nt
	s_add_u32 s14, s14, 0xb000
	s_addc_u32 s15, s15, 0
	global_load_dword v37, v15, s[14:15] nt
	s_add_u32 s14, s14, 0xb000
	s_addc_u32 s15, s15, 0
	global_load_dword v38, v15, s[14:15] nt
	s_add_u32 s14, s14, 0xb000
	s_addc_u32 s15, s15, 0
	global_load_dword v39, v15, s[14:15] nt
	s_add_u32 s14, s14, 0xb000
	s_addc_u32 s15, s15, 0
	global_load_dword v40, v15, s[14:15] nt
	s_add_u32 s14, s14, 0xb000
	s_addc_u32 s15, s15, 0
	global_load_dword v41, v15, s[14:15] nt
	s_add_u32 s14, s14, 0xb000
	s_addc_u32 s15, s15, 0
	global_load_dword v42, v15, s[14:15] nt
	s_add_u32 s14, s14, 0xb000
	s_addc_u32 s15, s15, 0
	global_load_dword v43, v15, s[14:15] nt
	s_add_u32 s14, s14, 0xb000
	s_addc_u32 s15, s15, 0
	global_load_dword v44, v15, s[14:15] nt
	s_add_u32 s14, s14, 0xb000
	s_addc_u32 s15, s15, 0
	global_load_dword v45, v15, s[14:15] nt
	s_add_u32 s14, s14, 0xb000
	s_addc_u32 s15, s15, 0
	global_load_dword v46, v15, s[14:15] nt
	s_add_u32 s14, s14, 0xb000
	s_addc_u32 s15, s15, 0
	global_load_dword v47, v15, s[14:15] nt
	s_lshl_b32 s14, s11, 8
	s_add_u32 s14, s20, s14
	s_addc_u32 s15, s21, 0
	global_load_dwordx4 v[80:83], v14, s[14:15]
	global_load_dwordx4 v[84:87], v14, s[14:15] offset:16
	s_lshr_b32 s16, s12, 2
	s_lshl_b32 s16, s16, 1
	s_add_u32 s16, s16, 1
	s_lshl_b32 s16, s16, 5
	s_add_u32 s16, s16, s11
	s_lshl_b32 s16, s16, 14
	s_and_b32 s17, s12, 3
	s_lshl_b32 s17, s17, 12
	s_add_u32 s16, s16, s17
	s_add_u32 s16, s6, s16
	s_addc_u32 s17, s7, 0
	s_waitcnt vmcnt(34)
; #define LAS __attribute__((address_space(3)))
; __device__ __forceinline__ unsigned pk2(float lo, float hi) { f32x2 f = {lo, hi}; bf16x2_t b = __builtin_convertvector(f, bf16x2_t); return __builtin_bit_cast(unsigned, b); }
; template <int MAP, bool HASG, bool PERMW>
; __device__ __forceinline__ void tr_store(int K, int N, bf16_t* WT, LAS float* scr, int item, int lane, const float* gk) {
;     const int nblk = N / 32, kb = item / nblk, nb = item % nblk, k0 = 64 * kb, n0 = 32 * nb;
;     asm volatile("s_waitcnt lgkmcnt(0)" ::: "memory");
;     const int c = lane & 7;
;     f32x4 g0 = {1.f, 1.f, 1.f, 1.f}, g1 = {1.f, 1.f, 1.f, 1.f};
;     if (HASG) { g0 = *(const f32x4*)(gk + k0 + 8 * c); g1 = *(const f32x4*)(gk + k0 + 8 * c + 4); }
; #pragma unroll
;     for (int j = 0; j < 4; ++j) { const int n = (lane >> 3) + 8 * j; const LAS float* s = scr + (8 * c) * 33 + n;
;         u32x4 o; o.x = pk2(s[0 * 33] * g0[0], s[1 * 33] * g0[1]); o.y = pk2(s[2 * 33] * g0[2], s[3 * 33] * g0[3]); o.z = pk2(s[4 * 33] * g1[0], s[5 * 33] * g1[1]); o.w = pk2(s[6 * 33] * g1[2], s[7 * 33] * g1[3]);
;         const int wr_ = rowmap<MAP>(n0 + n), slot_ = PERMW ? ((wr_ & ~31) + invperm32(wr_ & 31)) : wr_;
;         *(u32x4*)((char*)WT + tiled_off(slot_, k0 + 8 * c, K / 64)) = o; }
;     asm volatile("s_waitcnt lgkmcnt(0)" ::: "memory");
; }
	ds_write_b32 v4, v88
	ds_write_b32 v4, v89 offset:264
	ds_write_b32 v4, v90 offset:528
	ds_write_b32 v4, v91 offset:792
	ds_write_b32 v4, v92 offset:1056
	ds_write_b32 v4, v93 offset:1320
	ds_write_b32 v4, v94 offset:1584
	ds_write_b32 v4, v95 offset:1848
	ds_write_b32 v4, v96 offset:2112
	ds_write_b32 v4, v97 offset:2376
	ds_write_b32 v4, v98 offset:2640
	ds_write_b32 v4, v99 offset:2904
	ds_write_b32 v4, v100 offset:3168
	ds_write_b32 v4, v101 offset:3432
	ds_write_b32 v4, v102 offset:3696
	ds_write_b32 v4, v103 offset:3960
	ds_write_b32 v4, v104 offset:4224
	ds_write_b32 v4, v105 offset:4488
	ds_write_b32 v4, v106 offset:4752
	ds_write_b32 v4, v107 offset:5016
	ds_write_b32 v4, v108 offset:5280
	ds_write_b32 v4, v109 offset:5544
	ds_write_b32 v4, v110 offset:5808
	ds_write_b32 v4, v111 offset:6072
	ds_write_b32 v4, v112 offset:6336
	ds_write_b32 v4, v113 offset:6600
	ds_write_b32 v4, v114 offset:6864
	ds_write_b32 v4, v115 offset:7128
	ds_write_b32 v4, v116 offset:7392
	ds_write_b32 v4, v117 offset:7656
	ds_write_b32 v4, v118 offset:7920
	ds_write_b32 v4, v119 offset:8184
	s_waitcnt lgkmcnt(0)
	ds_read_b32 v48, v7
	ds_read_b32 v49, v7 offset:132
	ds_read_b32 v50, v7 offset:264
	ds_read_b32 v51, v7 offset:396
	ds_read_b32 v52, v7 offset:528
	ds_read_b32 v53, v7 offset:660
	ds_read_b32 v54, v7 offset:792
	ds_read_b32 v55, v7 offset:924
	ds_read_b32 v56, v7 offset:32
	ds_read_b32 v57, v7 offset:164
	ds_read_b32 v58, v7 offset:296
	ds_read_b32 v59, v7 offset:428
	ds_read_b32 v60, v7 offset:560
	ds_read_b32 v61, v7 offset:692
	ds_read_b32 v62, v7 offset:824
	ds_read_b32 v63, v7 offset:956
	ds_read_b32 v64, v7 offset:64
	ds_read_b32 v65, v7 offset:196
	ds_read_b32 v66, v7 offset:328
	ds_read_b32 v67, v7 offset:460
	ds_read_b32 v68, v7 offset:592
	ds_read_b32 v69, v7 offset:724
	ds_read_b32 v70, v7 offset:856
	ds_read_b32 v71, v7 offset:988
	ds_read_b32 v72, v7 offset:96
	ds_read_b32 v73, v7 offset:228
	ds_read_b32 v74, v7 offset:360
	ds_read_b32 v75, v7 offset:492
	ds_read_b32 v76, v7 offset:624
	ds_read_b32 v77, v7 offset:756
	ds_read_b32 v78, v7 offset:888
	ds_read_b32 v79, v7 offset:1020
	s_waitcnt lgkmcnt(0)
	v_mul_f32_e32 v48, v48, v120
	v_mul_f32_e32 v49, v49, v121
	v_mul_f32_e32 v50, v50, v122
	v_mul_f32_e32 v51, v51, v123
	v_mul_f32_e32 v52, v52, v124
	v_mul_f32_e32 v53, v53, v125
	v_mul_f32_e32 v54, v54, v126
	v_mul_f32_e32 v55, v55, v127
	v_cvt_pk_bf16_f32 v48, v48, v49
	v_cvt_pk_bf16_f32 v49, v50, v51
	v_cvt_pk_bf16_f32 v50, v52, v53
	v_cvt_pk_bf16_f32 v51, v54, v55
	global_store_dwordx4 v10, v[48:51], s[24:25]
	v_mul_f32_e32 v56, v56, v120
	v_mul_f32_e32 v57, v57, v121
	v_mul_f32_e32 v58, v58, v122
	v_mul_f32_e32 v59, v59, v123
	v_mul_f32_e32 v60, v60, v124
	v_mul_f32_e32 v61, v61, v125
	v_mul_f32_e32 v62, v62, v126
	v_mul_f32_e32 v63, v63, v127
	v_cvt_pk_bf16_f32 v56, v56, v57
	v_cvt_pk_bf16_f32 v57, v58, v59
	v_cvt_pk_bf16_f32 v58, v60, v61
	v_cvt_pk_bf16_f32 v59, v62, v63
	global_store_dwordx4 v10, v[56:59], s[24:25] offset:256
	v_mul_f32_e32 v64, v64, v120
	v_mul_f32_e32 v65, v65, v121
	v_mul_f32_e32 v66, v66, v122
	v_mul_f32_e32 v67, v67, v123
	v_mul_f32_e32 v68, v68, v124
	v_mul_f32_e32 v69, v69, v125
	v_mul_f32_e32 v70, v70, v126
	v_mul_f32_e32 v71, v71, v127
	v_cvt_pk_bf16_f32 v64, v64, v65
	v_cvt_pk_bf16_f32 v65, v66, v67
	v_cvt_pk_bf16_f32 v66, v68, v69
	v_cvt_pk_bf16_f32 v67, v70, v71
	global_store_dwordx4 v11, v[64:67], s[24:25] offset:512
	v_mul_f32_e32 v72, v72, v120
	v_mul_f32_e32 v73, v73, v121
	v_mul_f32_e32 v74, v74, v122
	v_mul_f32_e32 v75, v75, v123
	v_mul_f32_e32 v76, v76, v124
	v_mul_f32_e32 v77, v77, v125
	v_mul_f32_e32 v78, v78, v126
	v_mul_f32_e32 v79, v79, v127
	v_cvt_pk_bf16_f32 v72, v72, v73
	v_cvt_pk_bf16_f32 v73, v74, v75
	v_cvt_pk_bf16_f32 v74, v76, v77
	v_cvt_pk_bf16_f32 v75, v78, v79
	global_store_dwordx4 v11, v[72:75], s[24:25] offset:768
	s_branch .Ltc3d_loop

; __global__ void __launch_bounds__(512, 2) mega_fwd(Params p) {
;     ...
;             transpose_mat<1, true, true>(p.in[2] + (size_t)l * D * DFF, D, DFF, P_W(WS_WGU1), scr, gw, ngw, lane, p.in[1] + l * D);
;             transpose_mat<2, true, true>(p.in[3] + (size_t)l * D * DFF, D, DFF, P_W(WS_WGU1), scr, gw, ngw, lane, p.in[1] + l * D);
;             transpose_mat<0>(p.in[4] + (size_t)l * DFF * D, DFF, D, P_W(WS_WD1), scr, gw, ngw, lane);
;             transpose_mat<3, true, true>(p.in[6] + (size_t)l * D * INW, D, INW, P_W(WS_WIN), scr, gw, ngw, lane, p.in[5] + l * D);
;             transpose_mat<0, false, true>(p.in[7] + (size_t)l * 1024 * D, 1024, D, P_W(WS_WA), scr, gw, ngw, lane);
;             transpose_mat<0, false, true>(p.in[8] + (size_t)l * 2048 * D, 2048, D, P_W(WS_WB), scr, gw, ngw, lane);
;             transpose_mat<0>(p.in[9] + (size_t)l * D * D, D, D, P_W(WS_WO), scr, gw, ngw, lane);
;             transpose_mat<1, true, true>(p.in[11] + (size_t)l * D * DFF, D, DFF, P_W(WS_WGU2), scr, gw, ngw, lane, p.in[10] + l * D);
;             transpose_mat<2, true, true>(p.in[12] + (size_t)l * D * DFF, D, DFF, P_W(WS_WGU2), scr, gw, ngw, lane, p.in[10] + l * D);
;             transpose_mat<0>(p.in[13] + (size_t)l * DFF * D, DFF, D, P_W(WS_WD2), scr, gw, ngw, lane);
.Ltc3d_exit:
	v_readlane_b32 s4, v255, 24
	v_readlane_b32 s5, v255, 25
	v_readlane_b32 s6, v255, 26
	v_readlane_b32 s7, v255, 27
	v_readlane_b32 s8, v255, 28
	v_readlane_b32 s9, v255, 29
	v_readlane_b32 s10, v255, 30
	v_readlane_b32 s11, v255, 31
	v_readlane_b32 s12, v255, 32
	v_readlane_b32 s13, v255, 33
	v_readlane_b32 s14, v255, 34
	v_readlane_b32 s15, v255, 35
	v_readlane_b32 s16, v255, 36
	v_readlane_b32 s17, v255, 37
	v_readlane_b32 s18, v255, 38
	v_readlane_b32 s19, v255, 39
	v_readlane_b32 s20, v255, 40
	v_readlane_b32 s21, v255, 41
	v_readlane_b32 s22, v255, 42
	v_readlane_b32 s23, v255, 43
	v_readlane_b32 s24, v255, 44
	v_readlane_b32 s25, v255, 45
	v_readlane_b32 s26, v255, 46
	v_readlane_b32 s27, v255, 47
	v_readlane_b32 s28, v255, 48
	v_readlane_b32 s29, v255, 49
	s_nop 3

; __device__ __forceinline__ void tr_load(const float* W, int N, int item, int lane, float (&wv)[32]) {
;     const int nblk = N / 32, kb = item / nblk, nb = item % nblk, k0 = 64 * kb, n0 = 32 * nb;
; #pragma unroll
;     for (int i = 0; i < 32; ++i) { const int kk = 2 * i + (lane >> 5); wv[i] = __builtin_nontemporal_load(W + (size_t)(k0 + kk) * N + n0 + (lane & 31)); }
; }
; template <int MAP, bool HASG, bool PERMW>
; __device__ __forceinline__ void tr_store(int K, int N, bf16_t* WT, LAS float* scr, int item, int lane, const float* gk) {
;     const int nblk = N / 32, kb = item / nblk, nb = item % nblk, k0 = 64 * kb, n0 = 32 * nb;
;     asm volatile("s_waitcnt lgkmcnt(0)" ::: "memory");
;     const int c = lane & 7;
;     f32x4 g0 = {1.f, 1.f, 1.f, 1.f}, g1 = {1.f, 1.f, 1.f, 1.f};
;     if (HASG) { g0 = *(const f32x4*)(gk + k0 + 8 * c); g1 = *(const f32x4*)(gk + k0 + 8 * c + 4); }
; #pragma unroll
;     for (int j = 0; j < 4; ++j) { const int n = (lane >> 3) + 8 * j; const LAS float* s = scr + (8 * c) * 33 + n;
;         u32x4 o; o.x = pk2(s[0 * 33] * g0[0], s[1 * 33] * g0[1]); o.y = pk2(s[2 * 33] * g0[2], s[3 * 33] * g0[3]); o.z = pk2(s[4 * 33] * g1[0], s[5 * 33] * g1[1]); o.w = pk2(s[6 * 33] * g1[2], s[7 * 33] * g1[3]);
;         const int wr_ = rowmap<MAP>(n0 + n), slot_ = PERMW ? ((wr_ & ~31) + invperm32(wr_ & 31)) : wr_;
;         *(u32x4*)((char*)WT + tiled_off(slot_, k0 + 8 * c, K / 64)) = o; }
;     asm volatile("s_waitcnt lgkmcnt(0)" ::: "memory");
; }
; template <int MAP, bool HASG = false, bool PERMW = false>
; __device__ __forceinline__ void transpose_mat(const float* W, int K, int N, bf16_t* WT, LAS float* scr, int gw, int ngw, int lane, const float* gk = nullptr) {
;     const int nitems = (K / 64) * (N / 32);
;     int it = gw;
;     if (it >= nitems) return;
;     float wv[32];
;     tr_load(W, N, it, lane, wv);
;     for (;;) {
;         __builtin_amdgcn_sched_barrier(0);
; #pragma unroll
;         for (int i = 0; i < 32; ++i) { const int kk = 2 * i + (lane >> 5); scr[kk * 33 + (lane & 31)] = wv[i]; }
;         __builtin_amdgcn_sched_barrier(0);
;         const int nx = it + ngw;
;         if (nx < nitems) tr_load(W, N, nx, lane, wv);
;         __builtin_amdgcn_sched_barrier(0);
;         tr_store<MAP, HASG, PERMW>(K, N, WT, scr, it, lane, gk);
;         if (nx >= nitems) break;
;         it = nx;
;     }
; }
.LBB0_826:
	s_cmpk_lt_u32 s2, 0x80
	s_cbranch_scc1 .Ltc2_done
	v_writelane_b32 v255, s4, 24
	v_writelane_b32 v255, s5, 25
	v_writelane_b32 v255, s6, 26
	v_writelane_b32 v255, s7, 27
	v_writelane_b32 v255, s8, 28
	v_writelane_b32 v255, s9, 29
	v_writelane_b32 v255, s10, 30
	v_writelane_b32 v255, s11, 31
	v_writelane_b32 v255, s12, 32
	v_writelane_b32 v255, s13, 33
	v_writelane_b32 v255, s14, 34
	v_writelane_b32 v255, s15, 35
	v_writelane_b32 v255, s16, 36
	v_writelane_b32 v255, s17, 37
	v_writelane_b32 v255, s18, 38
	v_writelane_b32 v255, s19, 39
	v_writelane_b32 v255, s20, 40
	v_writelane_b32 v255, s21, 41
	v_writelane_b32 v255, s22, 42
	v_writelane_b32 v255, s23, 43
	v_writelane_b32 v255, s24, 44
	v_writelane_b32 v255, s25, 45
	v_writelane_b32 v255, s26, 46
	v_writelane_b32 v255, s27, 47
	v_writelane_b32 v255, s28, 48
	v_writelane_b32 v255, s29, 49
	v_readfirstlane_b32 s8, v234
	s_nop 3
	s_lshr_b32 s8, s8, 6
	s_sub_u32 s18, s2, 0x80
	s_lshl_b32 s18, s18, 3
	s_add_u32 s18, s18, s8
	s_mul_i32 s10, s8, 0x2100
	v_and_b32_e32 v0, 63, v234
	v_and_b32_e32 v1, 31, v0
	v_lshrrev_b32_e32 v2, 5, v0
	v_lshlrev_b32_e32 v3, 13, v2
	v_lshl_add_u32 v3, v1, 2, v3
	v_mul_u32_u24_e32 v4, 33, v2
	v_add_u32_e32 v4, v4, v1
	v_lshl_add_u32 v4, v4, 2, s10
	v_and_b32_e32 v5, 7, v0
	v_lshrrev_b32_e32 v6, 3, v0
	v_mul_u32_u24_e32 v7, 0x108, v5
	v_add_u32_e32 v7, v7, v6
	v_lshl_add_u32 v7, v7, 2, s10
	v_lshrrev_b32_e32 v12, 2, v5
	v_lshlrev_b32_e32 v12, 10, v12
	v_and_b32_e32 v13, 3, v5
	v_lshl_add_u32 v12, v13, 4, v12
	v_lshl_add_u32 v8, v6, 6, v12
	v_xor_b32_e32 v9, 32, v8
	v_add_u32_e32 v9, 0x200, v9
	v_and_b32_e32 v13, 3, v6
	v_lshl_add_u32 v10, v13, 6, v12
	v_bfe_u32 v13, v6, 2, 1
	v_lshl_add_u32 v10, v13, 11, v10
	v_xor_b32_e32 v11, 32, v10
	v_lshlrev_b32_e32 v14, 5, v5
	v_mul_u32_u24_e32 v15, 0x5800, v2
	v_lshl_add_u32 v15, v1, 2, v15
	v_mul_u32_u24_e32 v12, 0xd000, v2
	v_lshl_add_u32 v12, v1, 2, v12
	v_readlane_b32 s4, v254, 10
	v_readlane_b32 s5, v254, 11
	s_nop 3
	s_and_b32 s6, s60, 0x2c00000
	s_add_u32 s4, s4, s6
	s_addc_u32 s5, s5, 0
	s_add_u32 s6, s76, 0xb600000
	s_addc_u32 s7, s77, 0
	s_mov_b32 s9, s18
	s_cmpk_ge_u32 s9, 0x1600
	s_cbranch_scc1 .Ltc2a_exit
	s_lshr_b32 s11, s9, 6
	s_and_b32 s12, s9, 63
	s_lshl_b32 s13, s11, 19
	s_lshl_b32 s14, s12, 7
	s_add_u32 s13, s13, s14
	s_add_u32 s14, s4, s13
	s_addc_u32 s15, s5, 0
	global_load_dword v16, v3, s[14:15] nt
	s_add_u32 s14, s14, 0x4000
	s_addc_u32 s15, s15, 0
	global_load_dword v17, v3, s[14:15] nt
	s_add_u32 s14, s14, 0x4000
	s_addc_u32 s15, s15, 0
	global_load_dword v18, v3, s[14:15] nt
	s_add_u32 s14, s14, 0x4000
	s_addc_u32 s15, s15, 0
	global_load_dword v19, v3, s[14:15] nt
	s_add_u32 s14, s14, 0x4000
	s_addc_u32 s15, s15, 0
	global_load_dword v20, v3, s[14:15] nt
	s_add_u32 s14, s14, 0x4000
	s_addc_u32 s15, s15, 0
	global_load_dword v21, v3, s[14:15] nt
	s_add_u32 s14, s14, 0x4000
	s_addc_u32 s15, s15, 0
	global_load_dword v22, v3, s[14:15] nt
	s_add_u32 s14, s14, 0x4000
	s_addc_u32 s15, s15, 0
	global_load_dword v23, v3, s[14:15] nt
	s_add_u32 s14, s14, 0x4000
	s_addc_u32 s15, s15, 0
	global_load_dword v24, v3, s[14:15] nt
	s_add_u32 s14, s14, 0x4000
	s_addc_u32 s15, s15, 0
	global_load_dword v25, v3, s[14:15] nt
	s_add_u32 s14, s14, 0x4000
	s_addc_u32 s15, s15, 0
	global_load_dword v26, v3, s[14:15] nt
	s_add_u32 s14, s14, 0x4000
	s_addc_u32 s15, s15, 0
	global_load_dword v27, v3, s[14:15] nt
	s_add_u32 s14, s14, 0x4000
	s_addc_u32 s15, s15, 0
	global_load_dword v28, v3, s[14:15] nt
	s_add_u32 s14, s14, 0x4000
	s_addc_u32 s15, s15, 0
	global_load_dword v29, v3, s[14:15] nt
	s_add_u32 s14, s14, 0x4000
	s_addc_u32 s15, s15, 0
	global_load_dword v30, v3, s[14:15] nt
	s_add_u32 s14, s14, 0x4000
	s_addc_u32 s15, s15, 0
	global_load_dword v31, v3, s[14:15] nt
	s_add_u32 s14, s14, 0x4000
	s_addc_u32 s15, s15, 0
	global_load_dword v32, v3, s[14:15] nt
	s_add_u32 s14, s14, 0x4000
	s_addc_u32 s15, s15, 0
	global_load_dword v33, v3, s[14:15] nt
	s_add_u32 s14, s14, 0x4000
	s_addc_u32 s15, s15, 0
	global_load_dword v34, v3, s[14:15] nt
	s_add_u32 s14, s14, 0x4000
	s_addc_u32 s15, s15, 0
	global_load_dword v35, v3, s[14:15] nt
	s_add_u32 s14, s14, 0x4000
	s_addc_u32 s15, s15, 0
	global_load_dword v36, v3, s[14:15] nt
	s_add_u32 s14, s14, 0x4000
	s_addc_u32 s15, s15, 0
	global_load_dword v37, v3, s[14:15] nt
	s_add_u32 s14, s14, 0x4000
	s_addc_u32 s15, s15, 0
	global_load_dword v38, v3, s[14:15] nt
	s_add_u32 s14, s14, 0x4000
	s_addc_u32 s15, s15, 0
	global_load_dword v39, v3, s[14:15] nt
	s_add_u32 s14, s14, 0x4000
	s_addc_u32 s15, s15, 0
	global_load_dword v40, v3, s[14:15] nt
	s_add_u32 s14, s14, 0x4000
	s_addc_u32 s15, s15, 0
	global_load_dword v41, v3, s[14:15] nt
	s_add_u32 s14, s14, 0x4000
	s_addc_u32 s15, s15, 0
	global_load_dword v42, v3, s[14:15] nt
	s_add_u32 s14, s14, 0x4000
	s_addc_u32 s15, s15, 0
	global_load_dword v43, v3, s[14:15] nt
	s_add_u32 s14, s14, 0x4000
	s_addc_u32 s15, s15, 0
	global_load_dword v44, v3, s[14:15] nt
	s_add_u32 s14, s14, 0x4000
	s_addc_u32 s15, s15, 0
	global_load_dword v45, v3, s[14:15] nt
	s_add_u32 s14, s14, 0x4000
	s_addc_u32 s15, s15, 0
	global_load_dword v46, v3, s[14:15] nt
	s_add_u32 s14, s14, 0x4000
	s_addc_u32 s15, s15, 0
	global_load_dword v47, v3, s[14:15] nt
	s_lshr_b32 s16, s12, 2
	s_mul_i32 s16, s16, 0x58
	s_add_u32 s16, s16, s11
	s_lshl_b32 s16, s16, 14
	s_and_b32 s17, s12, 3
	s_lshl_b32 s17, s17, 12
	s_add_u32 s16, s16, s17
	s_add_u32 s16, s6, s16
	s_addc_u32 s17, s7, 0
